# GEMM K-loops: per-segment s_setprio 1/0 toggling removed (priority 0 through the K-loop, 2 over the unit transition as before)
# speedup vs baseline: 1.0052x; 1.0016x over previous
; #define PG8_STAGE(bufoff, gbase, voff) do { _Pragma("unroll") for (int _i = 0; _i < 2; ++_i) \
;         __builtin_amdgcn_global_load_lds((const unsigned*)((const char*)(gbase) + (voff)[_i]), (LAS unsigned*)(lds + (bufoff) + ldsw + _i * 8192), 16, 0, 0); } while (0)
; #define PG8_LDA(dst, b, h) do { _Pragma("unroll") for (int m = 0; m < 4; ++m) _Pragma("unroll") for (int k = 0; k < 2; ++k) dst[m][k] = *(const LAS bf16x8*)(lds + PG8_SA(b, h) + aoff + m * 2048 + k * 1024); } while (0)
; #define PG8_LDB(dst, b, h) do { _Pragma("unroll") for (int n = 0; n < 2; ++n) _Pragma("unroll") for (int k = 0; k < 2; ++k) dst[n][k] = *(const LAS bf16x8*)(lds + PG8_SB(b, h) + boff + n * 2048 + k * 1024); } while (0)
; #define PG8_MMA(ai, bj, At, Bt) do { __builtin_amdgcn_s_setprio(1); _Pragma("unroll") for (int m = 0; m < 4; ++m) _Pragma("unroll") for (int n = 0; n < 2; ++n) _Pragma("unroll") for (int k = 0; k < 2; ++k) \
;         acc[ai][bj][m][n] = __builtin_amdgcn_mfma_f32_16x16x32_bf16(Bt[n][k], At[m][k], acc[ai][bj][m][n], 0, 0, 0); __builtin_amdgcn_s_setprio(0); } while (0)
; #define PG8_WAIT_V(n) asm volatile("s_waitcnt vmcnt(" #n ")" ::: "memory")
; #define PG8_BAR __builtin_amdgcn_s_barrier()
; template <class Epi, class Sched, bool ALIGN_EPI>
; __device__ __forceinline__ void gemm_phase(LAS unsigned char* lds, const int wid, const int lda_, const int ldb_, const int K_, const Sched& S, const Epi& E) {
;     ...
;         const bool has_next = S.next(ui + 1, nxt);
;         const int nt = S.nt(cur);
;         const char* nA = has_next ? S.a(nxt) : cA; const char* nB = has_next ? S.b(nxt) : cB;
; #pragma unroll 1
;         for (int t = 0; t < nt; t += 2) {
;             const bool last = (t == nt - 2);
;             const char* a1 = cA + (size_t)(t + 1) * kstep;
;             const char* a2 = last ? nA : cA + (size_t)(t + 2) * kstep; const char* b2 = last ? nB : cB + (size_t)(t + 2) * kstep;
;             const char* a3 = a2 + kstep; const char* b3 = b2 + kstep;
;             PG8_LDB(B0, 0, 0); PG8_LDB(B1, 0, 1); PG8_SCHED; PG8_LDA(At, 0, 0); PG8_STAGE(PG8_SA(1, 1), a1 + hstepA, voffA);
;             PG8_WAIT_V(8); PG8_WAIT_L(0); PG8_BAR; PG8_MMA(0, 0, At, B0); PG8_MMA(0, 1, At, B1); PG8_BAR; PG8_SCHED;
;             PG8_LDA(At, 0, 1); PG8_STAGE(PG8_SB(0, 0), b2, voffB); PG8_STAGE(PG8_SB(0, 1), b2 + hstepB, voffB); PG8_STAGE(PG8_SA(0, 0), a2, voffA);
.LBB0_298:
	s_ashr_i32 s37, s36, 31
	s_xor_b64 s[40:41], s[4:5], -1
	s_lshl_b64 s[38:39], s[36:37], 20
	v_readlane_b32 s42, v253, 52
	v_readlane_b32 s43, v253, 53
	s_add_u32 s38, s42, s38
	s_addc_u32 s39, s43, s39
	s_and_b64 s[42:43], s[4:5], exec
	s_cselect_b32 s31, s39, s47
	s_cselect_b32 s37, s38, s46
	s_ashr_i32 s35, s34, 31
	s_lshl_b64 s[42:43], s[34:35], 20
	s_add_u32 s42, s7, s42
	s_addc_u32 s43, s14, s43
	s_and_b64 s[4:5], s[4:5], exec
	s_cselect_b32 s4, s43, s49
	s_cselect_b32 s5, s42, s48
	s_add_u32 s50, s46, 0x80
	s_addc_u32 s51, s47, 0
	s_add_u32 s35, s48, 0x100
	v_lshl_add_u64 v[156:157], s[50:51], 0, v[152:153]
	v_lshl_add_u64 v[158:159], s[50:51], 0, v[154:155]
	s_addc_u32 s45, s49, 0
	s_mov_b32 s76, -2
	s_mov_b64 s[48:49], 0
	s_add_u32 s17, s46, s48
	s_addc_u32 s27, s47, s49
	s_add_u32 s17, s17, 0x100
	s_addc_u32 s27, s27, 0
	s_add_u32 s77, s35, s48
	s_addc_u32 s78, s45, s49
	s_add_i32 s80, 0, 0x10000
	s_cmpk_eq_i32 s48, 0xf00
	s_cselect_b32 s51, s31, s27
	s_cselect_b32 s50, s37, s17
	v_add_u32_e32 v141, s80, v135
	s_cselect_b32 s79, s4, s78
	s_cselect_b32 s78, s5, s77
	s_add_i32 s17, 0, 0x14000
	ds_read_b128 v[160:163], v141
	ds_read_b128 v[164:167], v141 offset:1024
	ds_read_b128 v[168:171], v141 offset:2048
	ds_read_b128 v[172:175], v141 offset:3072
	v_add_u32_e32 v141, s17, v135
	ds_read_b128 v[180:183], v141
	ds_read_b128 v[184:187], v141 offset:1024
	ds_read_b128 v[188:191], v141 offset:2048
	ds_read_b128 v[192:195], v141 offset:3072
	v_lshl_add_u64 v[228:229], v[158:159], 0, s[48:49]
	s_add_i32 m0, s16, 0xc000
	ds_read_b128 v[196:199], v139
	ds_read_b128 v[200:203], v139 offset:1024
	ds_read_b128 v[204:207], v139 offset:2048
	ds_read_b128 v[208:211], v139 offset:3072
	ds_read_b128 v[212:215], v139 offset:4096
	ds_read_b128 v[216:219], v139 offset:5120
	ds_read_b128 v[220:223], v139 offset:6144
	ds_read_b128 v[224:227], v139 offset:7168
	global_load_lds_dwordx4 v[228:229], off
	v_lshl_add_u64 v[228:229], v[156:157], 0, s[48:49]
	s_add_i32 m0, s16, 0xe000
	s_nop 0
	global_load_lds_dwordx4 v[228:229], off
	s_waitcnt vmcnt(8)
	s_waitcnt lgkmcnt(0)
	s_barrier
	s_setprio 0
	s_waitcnt lgkmcnt(0)
	v_mfma_f32_16x16x32_bf16 v[124:127], v[160:163], v[196:199], 0
	v_mfma_f32_16x16x32_bf16 v[120:123], v[168:171], v[196:199], 0
	v_mfma_f32_16x16x32_bf16 v[116:119], v[160:163], v[204:207], 0
	v_mfma_f32_16x16x32_bf16 v[112:115], v[168:171], v[204:207], 0
	v_mfma_f32_16x16x32_bf16 v[100:103], v[160:163], v[212:215], 0
	v_mfma_f32_16x16x32_bf16 v[96:99], v[168:171], v[212:215], 0
	v_mfma_f32_16x16x32_bf16 v[84:87], v[160:163], v[220:223], 0
	v_mfma_f32_16x16x32_bf16 v[80:83], v[168:171], v[220:223], 0
	v_mfma_f32_16x16x32_bf16 v[124:127], v[164:167], v[200:203], v[124:127]
	v_mfma_f32_16x16x32_bf16 v[120:123], v[172:175], v[200:203], v[120:123]
	v_mfma_f32_16x16x32_bf16 v[116:119], v[164:167], v[208:211], v[116:119]
	v_mfma_f32_16x16x32_bf16 v[112:115], v[172:175], v[208:211], v[112:115]
	v_mfma_f32_16x16x32_bf16 v[100:103], v[164:167], v[216:219], v[100:103]
	v_mfma_f32_16x16x32_bf16 v[96:99], v[172:175], v[216:219], v[96:99]
	v_mfma_f32_16x16x32_bf16 v[84:87], v[164:167], v[224:227], v[84:87]
	v_mfma_f32_16x16x32_bf16 v[80:83], v[172:175], v[224:227], v[80:83]
	v_mfma_f32_16x16x32_bf16 v[108:111], v[180:183], v[196:199], 0
	v_mfma_f32_16x16x32_bf16 v[104:107], v[188:191], v[196:199], 0
	v_mfma_f32_16x16x32_bf16 v[92:95], v[180:183], v[204:207], 0
	v_mfma_f32_16x16x32_bf16 v[88:91], v[188:191], v[204:207], 0
	v_mfma_f32_16x16x32_bf16 v[76:79], v[180:183], v[212:215], 0
	v_mfma_f32_16x16x32_bf16 v[72:75], v[188:191], v[212:215], 0
	v_mfma_f32_16x16x32_bf16 v[68:71], v[180:183], v[220:223], 0
	v_mfma_f32_16x16x32_bf16 v[64:67], v[188:191], v[220:223], 0
	v_mfma_f32_16x16x32_bf16 v[108:111], v[184:187], v[200:203], v[108:111]
	v_mfma_f32_16x16x32_bf16 v[104:107], v[192:195], v[200:203], v[104:107]
	v_mfma_f32_16x16x32_bf16 v[92:95], v[184:187], v[208:211], v[92:95]
	v_mfma_f32_16x16x32_bf16 v[88:91], v[192:195], v[208:211], v[88:91]
	v_mfma_f32_16x16x32_bf16 v[76:79], v[184:187], v[216:219], v[76:79]
	v_mfma_f32_16x16x32_bf16 v[72:75], v[192:195], v[216:219], v[72:75]
	v_mfma_f32_16x16x32_bf16 v[68:71], v[184:187], v[224:227], v[68:71]
	v_mfma_f32_16x16x32_bf16 v[64:67], v[192:195], v[224:227], v[64:67]
	s_barrier
	s_add_i32 s27, s80, s3
	v_lshl_add_u64 v[228:229], s[78:79], 0, v[176:177]
	s_mov_b32 m0, s27
	ds_read_b128 v[196:199], v139 offset:16384
	ds_read_b128 v[200:203], v139 offset:17408
	ds_read_b128 v[204:207], v139 offset:18432
	ds_read_b128 v[208:211], v139 offset:19456
	ds_read_b128 v[212:215], v139 offset:20480
	ds_read_b128 v[216:219], v139 offset:21504
	ds_read_b128 v[220:223], v139 offset:22528
	ds_read_b128 v[224:227], v139 offset:23552
	global_load_lds_dwordx4 v[228:229], off
	s_add_i32 m0, s27, 0x2000
	v_lshl_add_u64 v[230:231], s[78:79], 0, v[128:129]
	s_add_u32 s78, s78, s10
	s_addc_u32 s79, s79, s11
	s_add_i32 s17, s17, s3
	global_load_lds_dwordx4 v[230:231], off
	v_lshl_add_u64 v[232:233], s[78:79], 0, v[176:177]
	s_mov_b32 m0, s17
	v_lshl_add_u64 v[234:235], s[78:79], 0, v[128:129]
	global_load_lds_dwordx4 v[232:233], off
	s_add_i32 m0, s17, 0x2000
	v_lshl_add_u64 v[236:237], s[50:51], 0, v[132:133]
	global_load_lds_dwordx4 v[234:235], off
	s_mov_b32 m0, s16
	v_lshl_add_u64 v[246:247], s[50:51], 0, v[130:131]
	global_load_lds_dwordx4 v[236:237], off
	s_mov_b32 m0, s15
	s_nop 0
	global_load_lds_dwordx4 v[246:247], off
	s_waitcnt vmcnt(8)
	s_waitcnt lgkmcnt(0)
	s_barrier
; #define PG8_STAGE(bufoff, gbase, voff) do { _Pragma("unroll") for (int _i = 0; _i < 2; ++_i) \
;         __builtin_amdgcn_global_load_lds((const unsigned*)((const char*)(gbase) + (voff)[_i]), (LAS unsigned*)(lds + (bufoff) + ldsw + _i * 8192), 16, 0, 0); } while (0)
; #define PG8_LDA(dst, b, h) do { _Pragma("unroll") for (int m = 0; m < 4; ++m) _Pragma("unroll") for (int k = 0; k < 2; ++k) dst[m][k] = *(const LAS bf16x8*)(lds + PG8_SA(b, h) + aoff + m * 2048 + k * 1024); } while (0)
; #define PG8_LDB(dst, b, h) do { _Pragma("unroll") for (int n = 0; n < 2; ++n) _Pragma("unroll") for (int k = 0; k < 2; ++k) dst[n][k] = *(const LAS bf16x8*)(lds + PG8_SB(b, h) + boff + n * 2048 + k * 1024); } while (0)
; #define PG8_MMA(ai, bj, At, Bt) do { __builtin_amdgcn_s_setprio(1); _Pragma("unroll") for (int m = 0; m < 4; ++m) _Pragma("unroll") for (int n = 0; n < 2; ++n) _Pragma("unroll") for (int k = 0; k < 2; ++k) \
;         acc[ai][bj][m][n] = __builtin_amdgcn_mfma_f32_16x16x32_bf16(Bt[n][k], At[m][k], acc[ai][bj][m][n], 0, 0, 0); __builtin_amdgcn_s_setprio(0); } while (0)
; #define PG8_WAIT_V(n) asm volatile("s_waitcnt vmcnt(" #n ")" ::: "memory")
; #define PG8_WAIT_L(n) asm volatile("s_waitcnt lgkmcnt(" #n ")" ::: "memory")
; #define PG8_BAR __builtin_amdgcn_s_barrier()
; #define PG8_SCHED __builtin_amdgcn_sched_barrier(0)
; template <class Epi, class Sched, bool ALIGN_EPI>
; __device__ __forceinline__ void gemm_phase(LAS unsigned char* lds, const int wid, const int lda_, const int ldb_, const int K_, const Sched& S, const Epi& E) {
;     ...
;             PG8_LDB(B0, 0, 0); PG8_LDB(B1, 0, 1); PG8_SCHED; PG8_LDA(At, 0, 0); PG8_STAGE(PG8_SA(1, 1), a1 + hstepA, voffA);
;             PG8_WAIT_V(8); PG8_WAIT_L(0); PG8_BAR; PG8_MMA(0, 0, At, B0); PG8_MMA(0, 1, At, B1); PG8_BAR; PG8_SCHED;
;             PG8_LDA(At, 0, 1); PG8_STAGE(PG8_SB(0, 0), b2, voffB); PG8_STAGE(PG8_SB(0, 1), b2 + hstepB, voffB); PG8_STAGE(PG8_SA(0, 0), a2, voffA);
;             PG8_WAIT_V(8); PG8_WAIT_L(0); PG8_BAR; PG8_MMA(1, 0, At, B0); PG8_MMA(1, 1, At, B1); PG8_BAR; PG8_SCHED;
	s_waitcnt lgkmcnt(0)
	v_mfma_f32_16x16x32_bf16 v[60:63], v[160:163], v[196:199], 0
	v_mfma_f32_16x16x32_bf16 v[56:59], v[168:171], v[196:199], 0
	v_mfma_f32_16x16x32_bf16 v[52:55], v[160:163], v[204:207], 0
	v_mfma_f32_16x16x32_bf16 v[48:51], v[168:171], v[204:207], 0
	v_mfma_f32_16x16x32_bf16 v[36:39], v[160:163], v[212:215], 0
	v_mfma_f32_16x16x32_bf16 v[32:35], v[168:171], v[212:215], 0
	v_mfma_f32_16x16x32_bf16 v[20:23], v[160:163], v[220:223], 0
	v_mfma_f32_16x16x32_bf16 v[16:19], v[168:171], v[220:223], 0
	v_mfma_f32_16x16x32_bf16 v[60:63], v[164:167], v[200:203], v[60:63]
	v_mfma_f32_16x16x32_bf16 v[56:59], v[172:175], v[200:203], v[56:59]
	v_mfma_f32_16x16x32_bf16 v[52:55], v[164:167], v[208:211], v[52:55]
	v_mfma_f32_16x16x32_bf16 v[48:51], v[172:175], v[208:211], v[48:51]
	v_mfma_f32_16x16x32_bf16 v[36:39], v[164:167], v[216:219], v[36:39]
	v_mfma_f32_16x16x32_bf16 v[32:35], v[172:175], v[216:219], v[32:35]
	v_mfma_f32_16x16x32_bf16 v[20:23], v[164:167], v[224:227], v[20:23]
	v_mfma_f32_16x16x32_bf16 v[16:19], v[172:175], v[224:227], v[16:19]
	v_mfma_f32_16x16x32_bf16 v[44:47], v[180:183], v[196:199], 0
	v_mfma_f32_16x16x32_bf16 v[40:43], v[188:191], v[196:199], 0
	v_mfma_f32_16x16x32_bf16 v[28:31], v[180:183], v[204:207], 0
	v_mfma_f32_16x16x32_bf16 v[24:27], v[188:191], v[204:207], 0
	v_mfma_f32_16x16x32_bf16 v[12:15], v[180:183], v[212:215], 0
	v_mfma_f32_16x16x32_bf16 v[8:11], v[188:191], v[212:215], 0
	v_mfma_f32_16x16x32_bf16 v[4:7], v[180:183], v[220:223], 0
	v_mfma_f32_16x16x32_bf16 v[0:3], v[188:191], v[220:223], 0
	v_mfma_f32_16x16x32_bf16 v[44:47], v[184:187], v[200:203], v[44:47]
	v_mfma_f32_16x16x32_bf16 v[40:43], v[192:195], v[200:203], v[40:43]
	v_mfma_f32_16x16x32_bf16 v[28:31], v[184:187], v[208:211], v[28:31]
	v_mfma_f32_16x16x32_bf16 v[24:27], v[192:195], v[208:211], v[24:27]
	v_mfma_f32_16x16x32_bf16 v[12:15], v[184:187], v[216:219], v[12:15]
	v_mfma_f32_16x16x32_bf16 v[8:11], v[192:195], v[216:219], v[8:11]
	v_mfma_f32_16x16x32_bf16 v[4:7], v[184:187], v[224:227], v[4:7]
	v_mfma_f32_16x16x32_bf16 v[0:3], v[192:195], v[224:227], v[0:3]
	s_barrier
	s_branch .Lgemm_join_299
.LBB0_299:
	s_add_u32 s17, s46, s48
	s_addc_u32 s27, s47, s49
	s_add_u32 s17, s17, 0x100
	s_addc_u32 s27, s27, 0
	s_add_u32 s77, s35, s48
	s_addc_u32 s78, s45, s49
	s_add_i32 s80, 0, 0x10000
	s_cmpk_eq_i32 s48, 0xf00
	s_cselect_b32 s51, s31, s27
	s_cselect_b32 s50, s37, s17
	v_add_u32_e32 v141, s80, v135
	s_cselect_b32 s79, s4, s78
	s_cselect_b32 s78, s5, s77
	s_add_i32 s17, 0, 0x14000
	ds_read_b128 v[160:163], v141
	ds_read_b128 v[164:167], v141 offset:1024
	ds_read_b128 v[168:171], v141 offset:2048
	ds_read_b128 v[172:175], v141 offset:3072
	v_add_u32_e32 v141, s17, v135
	ds_read_b128 v[180:183], v141
	ds_read_b128 v[184:187], v141 offset:1024
	ds_read_b128 v[188:191], v141 offset:2048
	ds_read_b128 v[192:195], v141 offset:3072
	v_lshl_add_u64 v[228:229], v[158:159], 0, s[48:49]
	s_add_i32 m0, s16, 0xc000
	ds_read_b128 v[196:199], v139
	ds_read_b128 v[200:203], v139 offset:1024
	ds_read_b128 v[204:207], v139 offset:2048
	ds_read_b128 v[208:211], v139 offset:3072
	ds_read_b128 v[212:215], v139 offset:4096
	ds_read_b128 v[216:219], v139 offset:5120
	ds_read_b128 v[220:223], v139 offset:6144
	ds_read_b128 v[224:227], v139 offset:7168
	global_load_lds_dwordx4 v[228:229], off
	v_lshl_add_u64 v[228:229], v[156:157], 0, s[48:49]
	s_add_i32 m0, s16, 0xe000
	s_nop 0
	global_load_lds_dwordx4 v[228:229], off
	s_waitcnt vmcnt(8)
	s_waitcnt lgkmcnt(0)
	s_barrier
	s_waitcnt lgkmcnt(0)
	v_mfma_f32_16x16x32_bf16 v[124:127], v[160:163], v[196:199], v[124:127]
	v_mfma_f32_16x16x32_bf16 v[120:123], v[168:171], v[196:199], v[120:123]
	v_mfma_f32_16x16x32_bf16 v[116:119], v[160:163], v[204:207], v[116:119]
	v_mfma_f32_16x16x32_bf16 v[112:115], v[168:171], v[204:207], v[112:115]
	v_mfma_f32_16x16x32_bf16 v[100:103], v[160:163], v[212:215], v[100:103]
	v_mfma_f32_16x16x32_bf16 v[96:99], v[168:171], v[212:215], v[96:99]
	v_mfma_f32_16x16x32_bf16 v[84:87], v[160:163], v[220:223], v[84:87]
	v_mfma_f32_16x16x32_bf16 v[80:83], v[168:171], v[220:223], v[80:83]
	v_mfma_f32_16x16x32_bf16 v[124:127], v[164:167], v[200:203], v[124:127]
	v_mfma_f32_16x16x32_bf16 v[120:123], v[172:175], v[200:203], v[120:123]
	v_mfma_f32_16x16x32_bf16 v[116:119], v[164:167], v[208:211], v[116:119]
	v_mfma_f32_16x16x32_bf16 v[112:115], v[172:175], v[208:211], v[112:115]
	v_mfma_f32_16x16x32_bf16 v[100:103], v[164:167], v[216:219], v[100:103]
	v_mfma_f32_16x16x32_bf16 v[96:99], v[172:175], v[216:219], v[96:99]
	v_mfma_f32_16x16x32_bf16 v[84:87], v[164:167], v[224:227], v[84:87]
	v_mfma_f32_16x16x32_bf16 v[80:83], v[172:175], v[224:227], v[80:83]
	v_mfma_f32_16x16x32_bf16 v[108:111], v[180:183], v[196:199], v[108:111]
	v_mfma_f32_16x16x32_bf16 v[104:107], v[188:191], v[196:199], v[104:107]
	v_mfma_f32_16x16x32_bf16 v[92:95], v[180:183], v[204:207], v[92:95]
	v_mfma_f32_16x16x32_bf16 v[88:91], v[188:191], v[204:207], v[88:91]
	v_mfma_f32_16x16x32_bf16 v[76:79], v[180:183], v[212:215], v[76:79]
	v_mfma_f32_16x16x32_bf16 v[72:75], v[188:191], v[212:215], v[72:75]
	v_mfma_f32_16x16x32_bf16 v[68:71], v[180:183], v[220:223], v[68:71]
	v_mfma_f32_16x16x32_bf16 v[64:67], v[188:191], v[220:223], v[64:67]
	v_mfma_f32_16x16x32_bf16 v[108:111], v[184:187], v[200:203], v[108:111]
	v_mfma_f32_16x16x32_bf16 v[104:107], v[192:195], v[200:203], v[104:107]
	v_mfma_f32_16x16x32_bf16 v[92:95], v[184:187], v[208:211], v[92:95]
	v_mfma_f32_16x16x32_bf16 v[88:91], v[192:195], v[208:211], v[88:91]
	v_mfma_f32_16x16x32_bf16 v[76:79], v[184:187], v[216:219], v[76:79]
	v_mfma_f32_16x16x32_bf16 v[72:75], v[192:195], v[216:219], v[72:75]
	v_mfma_f32_16x16x32_bf16 v[68:71], v[184:187], v[224:227], v[68:71]
	v_mfma_f32_16x16x32_bf16 v[64:67], v[192:195], v[224:227], v[64:67]
	s_barrier
; #define PG8_STAGE(bufoff, gbase, voff) do { _Pragma("unroll") for (int _i = 0; _i < 2; ++_i) \
;         __builtin_amdgcn_global_load_lds((const unsigned*)((const char*)(gbase) + (voff)[_i]), (LAS unsigned*)(lds + (bufoff) + ldsw + _i * 8192), 16, 0, 0); } while (0)
; #define PG8_LDA(dst, b, h) do { _Pragma("unroll") for (int m = 0; m < 4; ++m) _Pragma("unroll") for (int k = 0; k < 2; ++k) dst[m][k] = *(const LAS bf16x8*)(lds + PG8_SA(b, h) + aoff + m * 2048 + k * 1024); } while (0)
; #define PG8_LDB(dst, b, h) do { _Pragma("unroll") for (int n = 0; n < 2; ++n) _Pragma("unroll") for (int k = 0; k < 2; ++k) dst[n][k] = *(const LAS bf16x8*)(lds + PG8_SB(b, h) + boff + n * 2048 + k * 1024); } while (0)
; #define PG8_MMA(ai, bj, At, Bt) do { __builtin_amdgcn_s_setprio(1); _Pragma("unroll") for (int m = 0; m < 4; ++m) _Pragma("unroll") for (int n = 0; n < 2; ++n) _Pragma("unroll") for (int k = 0; k < 2; ++k) \
;         acc[ai][bj][m][n] = __builtin_amdgcn_mfma_f32_16x16x32_bf16(Bt[n][k], At[m][k], acc[ai][bj][m][n], 0, 0, 0); __builtin_amdgcn_s_setprio(0); } while (0)
; #define PG8_WAIT_V(n) asm volatile("s_waitcnt vmcnt(" #n ")" ::: "memory")
; #define PG8_WAIT_L(n) asm volatile("s_waitcnt lgkmcnt(" #n ")" ::: "memory")
; #define PG8_BAR __builtin_amdgcn_s_barrier()
; #define PG8_SCHED __builtin_amdgcn_sched_barrier(0)
; template <class Epi, class Sched, bool ALIGN_EPI>
; __device__ __forceinline__ void gemm_phase(LAS unsigned char* lds, const int wid, const int lda_, const int ldb_, const int K_, const Sched& S, const Epi& E) {
;     ...
;             PG8_LDA(At, 0, 1); PG8_STAGE(PG8_SB(0, 0), b2, voffB); PG8_STAGE(PG8_SB(0, 1), b2 + hstepB, voffB); PG8_STAGE(PG8_SA(0, 0), a2, voffA);
;             PG8_WAIT_V(8); PG8_WAIT_L(0); PG8_BAR; PG8_MMA(1, 0, At, B0); PG8_MMA(1, 1, At, B1); PG8_BAR; PG8_SCHED;
;             PG8_LDB(B0, 1, 0); PG8_LDB(B1, 1, 1); PG8_SCHED; PG8_LDA(At, 1, 0); PG8_STAGE(PG8_SA(0, 1), a2 + hstepA, voffA);
	s_add_i32 s27, s80, s3
	v_lshl_add_u64 v[228:229], s[78:79], 0, v[176:177]
	s_mov_b32 m0, s27
	ds_read_b128 v[196:199], v139 offset:16384
	ds_read_b128 v[200:203], v139 offset:17408
	ds_read_b128 v[204:207], v139 offset:18432
	ds_read_b128 v[208:211], v139 offset:19456
	ds_read_b128 v[212:215], v139 offset:20480
	ds_read_b128 v[216:219], v139 offset:21504
	ds_read_b128 v[220:223], v139 offset:22528
	ds_read_b128 v[224:227], v139 offset:23552
	global_load_lds_dwordx4 v[228:229], off
	s_add_i32 m0, s27, 0x2000
	v_lshl_add_u64 v[230:231], s[78:79], 0, v[128:129]
	s_add_u32 s78, s78, s10
	s_addc_u32 s79, s79, s11
	s_add_i32 s17, s17, s3
	global_load_lds_dwordx4 v[230:231], off
	v_lshl_add_u64 v[232:233], s[78:79], 0, v[176:177]
	s_mov_b32 m0, s17
	v_lshl_add_u64 v[234:235], s[78:79], 0, v[128:129]
	global_load_lds_dwordx4 v[232:233], off
	s_add_i32 m0, s17, 0x2000
	v_lshl_add_u64 v[236:237], s[50:51], 0, v[132:133]
	global_load_lds_dwordx4 v[234:235], off
	s_mov_b32 m0, s16
	v_lshl_add_u64 v[246:247], s[50:51], 0, v[130:131]
	global_load_lds_dwordx4 v[236:237], off
	s_mov_b32 m0, s15
	s_nop 0
	global_load_lds_dwordx4 v[246:247], off
	s_waitcnt vmcnt(8)
	s_waitcnt lgkmcnt(0)
	s_barrier
	s_waitcnt lgkmcnt(0)
	v_mfma_f32_16x16x32_bf16 v[60:63], v[160:163], v[196:199], v[60:63]
	v_mfma_f32_16x16x32_bf16 v[56:59], v[168:171], v[196:199], v[56:59]
	v_mfma_f32_16x16x32_bf16 v[52:55], v[160:163], v[204:207], v[52:55]
	v_mfma_f32_16x16x32_bf16 v[48:51], v[168:171], v[204:207], v[48:51]
	v_mfma_f32_16x16x32_bf16 v[36:39], v[160:163], v[212:215], v[36:39]
	v_mfma_f32_16x16x32_bf16 v[32:35], v[168:171], v[212:215], v[32:35]
	v_mfma_f32_16x16x32_bf16 v[20:23], v[160:163], v[220:223], v[20:23]
	v_mfma_f32_16x16x32_bf16 v[16:19], v[168:171], v[220:223], v[16:19]
	v_mfma_f32_16x16x32_bf16 v[60:63], v[164:167], v[200:203], v[60:63]
	v_mfma_f32_16x16x32_bf16 v[56:59], v[172:175], v[200:203], v[56:59]
	v_mfma_f32_16x16x32_bf16 v[52:55], v[164:167], v[208:211], v[52:55]
	v_mfma_f32_16x16x32_bf16 v[48:51], v[172:175], v[208:211], v[48:51]
	v_mfma_f32_16x16x32_bf16 v[36:39], v[164:167], v[216:219], v[36:39]
	v_mfma_f32_16x16x32_bf16 v[32:35], v[172:175], v[216:219], v[32:35]
	v_mfma_f32_16x16x32_bf16 v[20:23], v[164:167], v[224:227], v[20:23]
	v_mfma_f32_16x16x32_bf16 v[16:19], v[172:175], v[224:227], v[16:19]
	v_mfma_f32_16x16x32_bf16 v[44:47], v[180:183], v[196:199], v[44:47]
	v_mfma_f32_16x16x32_bf16 v[40:43], v[188:191], v[196:199], v[40:43]
	v_mfma_f32_16x16x32_bf16 v[28:31], v[180:183], v[204:207], v[28:31]
	v_mfma_f32_16x16x32_bf16 v[24:27], v[188:191], v[204:207], v[24:27]
	v_mfma_f32_16x16x32_bf16 v[12:15], v[180:183], v[212:215], v[12:15]
	v_mfma_f32_16x16x32_bf16 v[8:11], v[188:191], v[212:215], v[8:11]
	v_mfma_f32_16x16x32_bf16 v[4:7], v[180:183], v[220:223], v[4:7]
	v_mfma_f32_16x16x32_bf16 v[0:3], v[188:191], v[220:223], v[0:3]
	v_mfma_f32_16x16x32_bf16 v[44:47], v[184:187], v[200:203], v[44:47]
	v_mfma_f32_16x16x32_bf16 v[40:43], v[192:195], v[200:203], v[40:43]
	v_mfma_f32_16x16x32_bf16 v[28:31], v[184:187], v[208:211], v[28:31]
	v_mfma_f32_16x16x32_bf16 v[24:27], v[192:195], v[208:211], v[24:27]
	v_mfma_f32_16x16x32_bf16 v[12:15], v[184:187], v[216:219], v[12:15]
	v_mfma_f32_16x16x32_bf16 v[8:11], v[192:195], v[216:219], v[8:11]
	v_mfma_f32_16x16x32_bf16 v[4:7], v[184:187], v[224:227], v[4:7]
	v_mfma_f32_16x16x32_bf16 v[0:3], v[192:195], v[224:227], v[0:3]
	s_barrier
.Lgemm_join_299:
	s_add_i32 s17, 0, 0x18000
	v_add_u32_e32 v141, s17, v135
	s_add_i32 s27, 0, 0x1c000
	ds_read_b128 v[160:163], v141
	ds_read_b128 v[164:167], v141 offset:1024
	ds_read_b128 v[168:171], v141 offset:2048
	ds_read_b128 v[172:175], v141 offset:3072
	v_add_u32_e32 v141, s27, v135
	ds_read_b128 v[180:183], v141
	ds_read_b128 v[184:187], v141 offset:1024
	ds_read_b128 v[188:191], v141 offset:2048
	ds_read_b128 v[192:195], v141 offset:3072
	s_add_u32 s50, s50, s0
	s_addc_u32 s51, s51, s1
	s_mov_b32 m0, s26
	v_lshl_add_u64 v[248:249], s[50:51], 0, v[132:133]
	ds_read_b128 v[196:199], v139 offset:32768
	ds_read_b128 v[200:203], v139 offset:33792
	ds_read_b128 v[204:207], v139 offset:34816
	ds_read_b128 v[208:211], v139 offset:35840
	ds_read_b128 v[212:215], v139 offset:36864
	ds_read_b128 v[216:219], v139 offset:37888
	ds_read_b128 v[220:223], v139 offset:38912
	ds_read_b128 v[224:227], v139 offset:39936
	global_load_lds_dwordx4 v[248:249], off
	v_lshl_add_u64 v[248:249], s[50:51], 0, v[130:131]
	s_mov_b32 m0, s72
	s_nop 0
	global_load_lds_dwordx4 v[248:249], off
	s_waitcnt vmcnt(8)
	s_waitcnt lgkmcnt(0)
	s_barrier
; #define PG8_STAGE(bufoff, gbase, voff) do { _Pragma("unroll") for (int _i = 0; _i < 2; ++_i) \
;         __builtin_amdgcn_global_load_lds((const unsigned*)((const char*)(gbase) + (voff)[_i]), (LAS unsigned*)(lds + (bufoff) + ldsw + _i * 8192), 16, 0, 0); } while (0)
; #define PG8_LDA(dst, b, h) do { _Pragma("unroll") for (int m = 0; m < 4; ++m) _Pragma("unroll") for (int k = 0; k < 2; ++k) dst[m][k] = *(const LAS bf16x8*)(lds + PG8_SA(b, h) + aoff + m * 2048 + k * 1024); } while (0)
; #define PG8_MMA(ai, bj, At, Bt) do { __builtin_amdgcn_s_setprio(1); _Pragma("unroll") for (int m = 0; m < 4; ++m) _Pragma("unroll") for (int n = 0; n < 2; ++n) _Pragma("unroll") for (int k = 0; k < 2; ++k) \
;         acc[ai][bj][m][n] = __builtin_amdgcn_mfma_f32_16x16x32_bf16(Bt[n][k], At[m][k], acc[ai][bj][m][n], 0, 0, 0); __builtin_amdgcn_s_setprio(0); } while (0)
; #define PG8_WAIT_V(n) asm volatile("s_waitcnt vmcnt(" #n ")" ::: "memory")
; #define PG8_WAIT_L(n) asm volatile("s_waitcnt lgkmcnt(" #n ")" ::: "memory")
; #define PG8_BAR __builtin_amdgcn_s_barrier()
; #define PG8_SCHED __builtin_amdgcn_sched_barrier(0)
; template <class Epi, class Sched, bool ALIGN_EPI>
; __device__ __forceinline__ void gemm_phase(LAS unsigned char* lds, const int wid, const int lda_, const int ldb_, const int K_, const Sched& S, const Epi& E) {
;     ...
;             PG8_WAIT_V(8); PG8_WAIT_L(0); PG8_BAR; PG8_MMA(0, 0, At, B0); PG8_MMA(0, 1, At, B1); PG8_BAR; PG8_SCHED;
;             PG8_LDA(At, 1, 1); PG8_STAGE(PG8_SB(1, 0), b3, voffB); PG8_STAGE(PG8_SB(1, 1), b3 + hstepB, voffB); PG8_STAGE(PG8_SA(1, 0), a3, voffA);
;             PG8_WAIT_V(8); PG8_WAIT_L(0); PG8_BAR; PG8_MMA(1, 0, At, B0); PG8_MMA(1, 1, At, B1); PG8_BAR; PG8_SCHED;
;         }
;         if constexpr (ALIGN_EPI) { if (wr == 0) PG8_BAR; }
;         E(acc, cur, S, wr, wc, fr, fq);
;     __device__ __forceinline__ void out(const pg8::Unit& u, char*& o, int& ldo, int& kind) const {
;         if (u.pn < 24) { o = (char*)ws + WS_XBCP + ((size_t)u.pm * 256 * XBC + (size_t)u.pn * 256) * 2; ldo = XBC; kind = 0; }
;         else if (u.pn < 40) { o = (char*)ws + WS_Z + ((size_t)u.pm * 256 * DI + (size_t)(u.pn - 24) * 256) * 2; ldo = DI; kind = 0; }
;         else { o = (char*)ws + WS_DT + (size_t)u.pm * 256 * 128 * 4; ldo = 128; kind = 1; } }
	s_waitcnt lgkmcnt(0)
	v_mfma_f32_16x16x32_bf16 v[124:127], v[160:163], v[196:199], v[124:127]
	v_mfma_f32_16x16x32_bf16 v[120:123], v[168:171], v[196:199], v[120:123]
	v_mfma_f32_16x16x32_bf16 v[116:119], v[160:163], v[204:207], v[116:119]
	v_mfma_f32_16x16x32_bf16 v[112:115], v[168:171], v[204:207], v[112:115]
	v_mfma_f32_16x16x32_bf16 v[100:103], v[160:163], v[212:215], v[100:103]
	v_mfma_f32_16x16x32_bf16 v[96:99], v[168:171], v[212:215], v[96:99]
	v_mfma_f32_16x16x32_bf16 v[84:87], v[160:163], v[220:223], v[84:87]
	v_mfma_f32_16x16x32_bf16 v[80:83], v[168:171], v[220:223], v[80:83]
	v_mfma_f32_16x16x32_bf16 v[124:127], v[164:167], v[200:203], v[124:127]
	v_mfma_f32_16x16x32_bf16 v[120:123], v[172:175], v[200:203], v[120:123]
	v_mfma_f32_16x16x32_bf16 v[116:119], v[164:167], v[208:211], v[116:119]
	v_mfma_f32_16x16x32_bf16 v[112:115], v[172:175], v[208:211], v[112:115]
	v_mfma_f32_16x16x32_bf16 v[100:103], v[164:167], v[216:219], v[100:103]
	v_mfma_f32_16x16x32_bf16 v[96:99], v[172:175], v[216:219], v[96:99]
	v_mfma_f32_16x16x32_bf16 v[84:87], v[164:167], v[224:227], v[84:87]
	v_mfma_f32_16x16x32_bf16 v[80:83], v[172:175], v[224:227], v[80:83]
	v_mfma_f32_16x16x32_bf16 v[108:111], v[180:183], v[196:199], v[108:111]
	v_mfma_f32_16x16x32_bf16 v[104:107], v[188:191], v[196:199], v[104:107]
	v_mfma_f32_16x16x32_bf16 v[92:95], v[180:183], v[204:207], v[92:95]
	v_mfma_f32_16x16x32_bf16 v[88:91], v[188:191], v[204:207], v[88:91]
	v_mfma_f32_16x16x32_bf16 v[76:79], v[180:183], v[212:215], v[76:79]
	v_mfma_f32_16x16x32_bf16 v[72:75], v[188:191], v[212:215], v[72:75]
	v_mfma_f32_16x16x32_bf16 v[68:71], v[180:183], v[220:223], v[68:71]
	v_mfma_f32_16x16x32_bf16 v[64:67], v[188:191], v[220:223], v[64:67]
	v_mfma_f32_16x16x32_bf16 v[108:111], v[184:187], v[200:203], v[108:111]
	v_mfma_f32_16x16x32_bf16 v[104:107], v[192:195], v[200:203], v[104:107]
	v_mfma_f32_16x16x32_bf16 v[92:95], v[184:187], v[208:211], v[92:95]
	v_mfma_f32_16x16x32_bf16 v[88:91], v[192:195], v[208:211], v[88:91]
	v_mfma_f32_16x16x32_bf16 v[76:79], v[184:187], v[216:219], v[76:79]
	v_mfma_f32_16x16x32_bf16 v[72:75], v[192:195], v[216:219], v[72:75]
	v_mfma_f32_16x16x32_bf16 v[68:71], v[184:187], v[224:227], v[68:71]
	v_mfma_f32_16x16x32_bf16 v[64:67], v[192:195], v[224:227], v[64:67]
	s_barrier
	s_add_i32 s17, s17, s3
	v_lshl_add_u64 v[228:229], v[228:229], 0, s[24:25]
	s_mov_b32 m0, s17
	ds_read_b128 v[196:199], v139 offset:49152
	ds_read_b128 v[200:203], v139 offset:50176
	ds_read_b128 v[204:207], v139 offset:51200
	ds_read_b128 v[208:211], v139 offset:52224
	ds_read_b128 v[212:215], v139 offset:53248
	ds_read_b128 v[216:219], v139 offset:54272
	ds_read_b128 v[220:223], v139 offset:55296
	ds_read_b128 v[224:227], v139 offset:56320
	global_load_lds_dwordx4 v[228:229], off
	v_lshl_add_u64 v[228:229], v[230:231], 0, s[24:25]
	s_add_i32 m0, s17, 0x2000
	s_add_i32 s17, s27, s3
	global_load_lds_dwordx4 v[228:229], off
	v_lshl_add_u64 v[228:229], v[232:233], 0, s[24:25]
	s_mov_b32 m0, s17
	s_nop 0
	global_load_lds_dwordx4 v[228:229], off
	v_lshl_add_u64 v[228:229], v[234:235], 0, s[24:25]
	s_add_i32 m0, s17, 0x2000
	s_nop 0
	global_load_lds_dwordx4 v[228:229], off
	v_lshl_add_u64 v[228:229], v[236:237], 0, s[24:25]
	s_mov_b32 m0, s73
	s_nop 0
	global_load_lds_dwordx4 v[228:229], off
	v_lshl_add_u64 v[228:229], v[246:247], 0, s[24:25]
	s_mov_b32 m0, s74
	s_nop 0
	global_load_lds_dwordx4 v[228:229], off
	s_waitcnt vmcnt(8)
	s_waitcnt lgkmcnt(0)
	s_barrier
	s_waitcnt lgkmcnt(0)
	v_mfma_f32_16x16x32_bf16 v[60:63], v[160:163], v[196:199], v[60:63]
	v_mfma_f32_16x16x32_bf16 v[56:59], v[168:171], v[196:199], v[56:59]
	v_mfma_f32_16x16x32_bf16 v[52:55], v[160:163], v[204:207], v[52:55]
	v_mfma_f32_16x16x32_bf16 v[48:51], v[168:171], v[204:207], v[48:51]
	v_mfma_f32_16x16x32_bf16 v[36:39], v[160:163], v[212:215], v[36:39]
	v_mfma_f32_16x16x32_bf16 v[32:35], v[168:171], v[212:215], v[32:35]
	v_mfma_f32_16x16x32_bf16 v[20:23], v[160:163], v[220:223], v[20:23]
	v_mfma_f32_16x16x32_bf16 v[16:19], v[168:171], v[220:223], v[16:19]
	v_mfma_f32_16x16x32_bf16 v[60:63], v[164:167], v[200:203], v[60:63]
	v_mfma_f32_16x16x32_bf16 v[56:59], v[172:175], v[200:203], v[56:59]
	v_mfma_f32_16x16x32_bf16 v[52:55], v[164:167], v[208:211], v[52:55]
	v_mfma_f32_16x16x32_bf16 v[48:51], v[172:175], v[208:211], v[48:51]
	v_mfma_f32_16x16x32_bf16 v[36:39], v[164:167], v[216:219], v[36:39]
	v_mfma_f32_16x16x32_bf16 v[32:35], v[172:175], v[216:219], v[32:35]
	v_mfma_f32_16x16x32_bf16 v[20:23], v[164:167], v[224:227], v[20:23]
	v_mfma_f32_16x16x32_bf16 v[16:19], v[172:175], v[224:227], v[16:19]
	v_mfma_f32_16x16x32_bf16 v[44:47], v[180:183], v[196:199], v[44:47]
	v_mfma_f32_16x16x32_bf16 v[40:43], v[188:191], v[196:199], v[40:43]
	v_mfma_f32_16x16x32_bf16 v[28:31], v[180:183], v[204:207], v[28:31]
	v_mfma_f32_16x16x32_bf16 v[24:27], v[188:191], v[204:207], v[24:27]
	v_mfma_f32_16x16x32_bf16 v[12:15], v[180:183], v[212:215], v[12:15]
	v_mfma_f32_16x16x32_bf16 v[8:11], v[188:191], v[212:215], v[8:11]
	v_mfma_f32_16x16x32_bf16 v[4:7], v[180:183], v[220:223], v[4:7]
	v_mfma_f32_16x16x32_bf16 v[0:3], v[188:191], v[220:223], v[0:3]
	v_mfma_f32_16x16x32_bf16 v[44:47], v[184:187], v[200:203], v[44:47]
	v_mfma_f32_16x16x32_bf16 v[40:43], v[192:195], v[200:203], v[40:43]
	v_mfma_f32_16x16x32_bf16 v[28:31], v[184:187], v[208:211], v[28:31]
	v_mfma_f32_16x16x32_bf16 v[24:27], v[192:195], v[208:211], v[24:27]
	v_mfma_f32_16x16x32_bf16 v[12:15], v[184:187], v[216:219], v[12:15]
	v_mfma_f32_16x16x32_bf16 v[8:11], v[192:195], v[216:219], v[8:11]
	v_mfma_f32_16x16x32_bf16 v[4:7], v[184:187], v[224:227], v[4:7]
	v_mfma_f32_16x16x32_bf16 v[0:3], v[192:195], v[224:227], v[0:3]
	s_barrier
	s_add_i32 s76, s76, 2
	s_add_u32 s48, s48, 0x100
	s_addc_u32 s49, s49, 0
	s_cmp_gt_u32 s76, 29
	s_cbranch_scc0 .LBB0_299
	s_setprio 2
	s_sub_u32 s100, s30, 24
	s_cmp_lt_u32 s100, 16
	s_cselect_b32 s100, 1, 0
	s_ashr_i32 s45, s44, 31
	s_cmp_gt_i32 s30, 23
	s_mov_b64 s[48:49], -1
	s_cbranch_scc0 .LBB0_305
	s_cmp_gt_u32 s30, 39
	s_mov_b64 s[4:5], -1
	s_cbranch_scc0 .LBB0_303
	s_lshl_b64 s[4:5], s[44:45], 17
	v_readlane_b32 s46, v252, 60
	v_readlane_b32 s47, v252, 61
	s_add_u32 s46, s46, s4
	s_addc_u32 s47, s47, s5
	s_mov_b64 s[4:5], 0

; #define PG8_STAGE(bufoff, gbase, voff) do { _Pragma("unroll") for (int _i = 0; _i < 2; ++_i) \
;         __builtin_amdgcn_global_load_lds((const unsigned*)((const char*)(gbase) + (voff)[_i]), (LAS unsigned*)(lds + (bufoff) + ldsw + _i * 8192), 16, 0, 0); } while (0)
; #define PG8_LDA(dst, b, h) do { _Pragma("unroll") for (int m = 0; m < 4; ++m) _Pragma("unroll") for (int k = 0; k < 2; ++k) dst[m][k] = *(const LAS bf16x8*)(lds + PG8_SA(b, h) + aoff + m * 2048 + k * 1024); } while (0)
; #define PG8_LDB(dst, b, h) do { _Pragma("unroll") for (int n = 0; n < 2; ++n) _Pragma("unroll") for (int k = 0; k < 2; ++k) dst[n][k] = *(const LAS bf16x8*)(lds + PG8_SB(b, h) + boff + n * 2048 + k * 1024); } while (0)
; #define PG8_WAIT_V(n) asm volatile("s_waitcnt vmcnt(" #n ")" ::: "memory")
; #define PG8_WAIT_L(n) asm volatile("s_waitcnt lgkmcnt(" #n ")" ::: "memory")
; template <class Epi, class Sched, bool ALIGN_EPI>
; __device__ __forceinline__ void gemm_phase(LAS unsigned char* lds, const int wid, const int lda_, const int ldb_, const int K_, const Sched& S, const Epi& E) {
;     ...
;         const bool has_next = S.next(ui + 1, nxt);
;         const int nt = S.nt(cur);
;         const char* nA = has_next ? S.a(nxt) : cA; const char* nB = has_next ? S.b(nxt) : cB;
; #pragma unroll 1
;         for (int t = 0; t < nt; t += 2) {
;             const bool last = (t == nt - 2);
;             const char* a1 = cA + (size_t)(t + 1) * kstep;
;             const char* a2 = last ? nA : cA + (size_t)(t + 2) * kstep; const char* b2 = last ? nB : cB + (size_t)(t + 2) * kstep;
;             const char* a3 = a2 + kstep; const char* b3 = b2 + kstep;
;             PG8_LDB(B0, 0, 0); PG8_LDB(B1, 0, 1); PG8_SCHED; PG8_LDA(At, 0, 0); PG8_STAGE(PG8_SA(1, 1), a1 + hstepA, voffA);
;             PG8_WAIT_V(8); PG8_WAIT_L(0); PG8_BAR; PG8_MMA(0, 0, At, B0); PG8_MMA(0, 1, At, B1); PG8_BAR; PG8_SCHED;
;             PG8_LDA(At, 0, 1); PG8_STAGE(PG8_SB(0, 0), b2, voffB); PG8_STAGE(PG8_SB(0, 1), b2 + hstepB, voffB); PG8_STAGE(PG8_SA(0, 0), a2, voffA);
;     __device__ __forceinline__ const char* a(const pg8::Unit& u) const { return (const char*)ws + aoff + (size_t)u.pm * 256 * K_ * 2 + (u.kq < 0 ? 0 : u.kq * (K_ / 4) * 2); }
;     __device__ __forceinline__ const char* b(const pg8::Unit& u) const { return (const char*)ws + boff + (size_t)u.pn * 256 * K_ * 2 + (u.kq < 0 ? 0 : u.kq * (K_ / 4) * 2); }
.LBB0_670:
	s_xor_b64 s[44:45], s[4:5], -1
	s_cmp_gt_i32 s38, -1
	s_cselect_b64 s[50:51], -1, 0
	s_cmp_lt_i32 s38, 0
	s_cselect_b32 s35, 64, 16
	s_max_i32 s17, s75, 0
	s_ashr_i32 s43, s42, 31
	s_lshl_b32 s17, s17, 11
	s_lshl_b64 s[46:47], s[42:43], 21
	v_readlane_b32 s48, v252, 62
	v_readlane_b32 s49, v252, 63
	s_add_u32 s27, s48, s46
	s_addc_u32 s37, s49, s47
	s_add_u32 s46, s27, s17
	s_addc_u32 s47, s37, 0
	s_and_b64 s[48:49], s[4:5], exec
	s_cselect_b32 s37, s47, s95
	s_cselect_b32 s39, s46, s94
	s_ashr_i32 s41, s40, 31
	s_lshl_b64 s[48:49], s[40:41], 21
	s_add_u32 s27, s6, s48
	s_addc_u32 s41, s7, s49
	s_add_u32 s48, s27, s17
	s_addc_u32 s49, s41, 0
	s_and_b64 s[4:5], s[4:5], exec
	s_cselect_b32 s4, s49, s97
	s_cselect_b32 s5, s48, s96
	s_add_i32 s41, s35, -2
	s_add_u32 s94, s94, 0x80
	s_addc_u32 s95, s95, 0
	s_add_u32 s43, s96, 0x100
	s_mov_b32 s77, 0
	s_addc_u32 s76, s97, 0
	s_add_i32 s78, s77, 2
	s_add_u32 s17, s94, 0x80
	s_addc_u32 s27, s95, 0
	s_add_i32 s79, 0, 0x10000
	s_cmp_eq_u32 s41, s77
	s_cselect_b32 s97, s37, s27
	s_cselect_b32 s96, s39, s17
	v_add_u32_e32 v141, s79, v135
	s_cselect_b32 s81, s4, s76
	s_cselect_b32 s80, s5, s43
	s_add_i32 s17, 0, 0x14000
	ds_read_b128 v[156:159], v141
	ds_read_b128 v[160:163], v141 offset:1024
	ds_read_b128 v[164:167], v141 offset:2048
	ds_read_b128 v[168:171], v141 offset:3072
	v_add_u32_e32 v141, s17, v135
	ds_read_b128 v[172:175], v141
	ds_read_b128 v[180:183], v141 offset:1024
	ds_read_b128 v[184:187], v141 offset:2048
	ds_read_b128 v[188:191], v141 offset:3072
	v_lshl_add_u64 v[224:225], s[94:95], 0, v[152:153]
	s_add_i32 m0, s16, 0xc000
	ds_read_b128 v[192:195], v139
	ds_read_b128 v[196:199], v139 offset:1024
	ds_read_b128 v[200:203], v139 offset:2048
	ds_read_b128 v[204:207], v139 offset:3072
	ds_read_b128 v[208:211], v139 offset:4096
	ds_read_b128 v[212:215], v139 offset:5120
	ds_read_b128 v[216:219], v139 offset:6144
	ds_read_b128 v[220:223], v139 offset:7168
	global_load_lds_dwordx4 v[224:225], off
	v_lshl_add_u64 v[224:225], s[94:95], 0, v[154:155]
	s_add_i32 m0, s16, 0xe000
	s_nop 0
	global_load_lds_dwordx4 v[224:225], off
	s_waitcnt vmcnt(8)
	s_waitcnt lgkmcnt(0)
	s_barrier
	s_setprio 0
	s_waitcnt lgkmcnt(0)
	v_mfma_f32_16x16x32_bf16 v[124:127], v[156:159], v[192:195], 0
	v_mfma_f32_16x16x32_bf16 v[120:123], v[164:167], v[192:195], 0
	v_mfma_f32_16x16x32_bf16 v[116:119], v[156:159], v[200:203], 0
	v_mfma_f32_16x16x32_bf16 v[112:115], v[164:167], v[200:203], 0
	v_mfma_f32_16x16x32_bf16 v[100:103], v[156:159], v[208:211], 0
	v_mfma_f32_16x16x32_bf16 v[96:99], v[164:167], v[208:211], 0
	v_mfma_f32_16x16x32_bf16 v[84:87], v[156:159], v[216:219], 0
	v_mfma_f32_16x16x32_bf16 v[80:83], v[164:167], v[216:219], 0
	v_mfma_f32_16x16x32_bf16 v[124:127], v[160:163], v[196:199], v[124:127]
	v_mfma_f32_16x16x32_bf16 v[120:123], v[168:171], v[196:199], v[120:123]
	v_mfma_f32_16x16x32_bf16 v[116:119], v[160:163], v[204:207], v[116:119]
	v_mfma_f32_16x16x32_bf16 v[112:115], v[168:171], v[204:207], v[112:115]
	v_mfma_f32_16x16x32_bf16 v[100:103], v[160:163], v[212:215], v[100:103]
	v_mfma_f32_16x16x32_bf16 v[96:99], v[168:171], v[212:215], v[96:99]
	v_mfma_f32_16x16x32_bf16 v[84:87], v[160:163], v[220:223], v[84:87]
	v_mfma_f32_16x16x32_bf16 v[80:83], v[168:171], v[220:223], v[80:83]
	v_mfma_f32_16x16x32_bf16 v[108:111], v[172:175], v[192:195], 0
	v_mfma_f32_16x16x32_bf16 v[104:107], v[184:187], v[192:195], 0
	v_mfma_f32_16x16x32_bf16 v[92:95], v[172:175], v[200:203], 0
	v_mfma_f32_16x16x32_bf16 v[88:91], v[184:187], v[200:203], 0
	v_mfma_f32_16x16x32_bf16 v[76:79], v[172:175], v[208:211], 0
	v_mfma_f32_16x16x32_bf16 v[72:75], v[184:187], v[208:211], 0
	v_mfma_f32_16x16x32_bf16 v[68:71], v[172:175], v[216:219], 0
	v_mfma_f32_16x16x32_bf16 v[64:67], v[184:187], v[216:219], 0
	v_mfma_f32_16x16x32_bf16 v[108:111], v[180:183], v[196:199], v[108:111]
	v_mfma_f32_16x16x32_bf16 v[104:107], v[188:191], v[196:199], v[104:107]
	v_mfma_f32_16x16x32_bf16 v[92:95], v[180:183], v[204:207], v[92:95]
	v_mfma_f32_16x16x32_bf16 v[88:91], v[188:191], v[204:207], v[88:91]
	v_mfma_f32_16x16x32_bf16 v[76:79], v[180:183], v[212:215], v[76:79]
	v_mfma_f32_16x16x32_bf16 v[72:75], v[188:191], v[212:215], v[72:75]
	v_mfma_f32_16x16x32_bf16 v[68:71], v[180:183], v[220:223], v[68:71]
	v_mfma_f32_16x16x32_bf16 v[64:67], v[188:191], v[220:223], v[64:67]
	s_barrier
	s_add_i32 s27, s79, s3
	v_lshl_add_u64 v[224:225], s[80:81], 0, v[176:177]
	s_mov_b32 m0, s27
	ds_read_b128 v[192:195], v139 offset:16384
	ds_read_b128 v[196:199], v139 offset:17408
	ds_read_b128 v[200:203], v139 offset:18432
	ds_read_b128 v[204:207], v139 offset:19456
	ds_read_b128 v[208:211], v139 offset:20480
	ds_read_b128 v[212:215], v139 offset:21504
	ds_read_b128 v[216:219], v139 offset:22528
	ds_read_b128 v[220:223], v139 offset:23552
	global_load_lds_dwordx4 v[224:225], off
	s_add_i32 m0, s27, 0x2000
	v_lshl_add_u64 v[226:227], s[80:81], 0, v[132:133]
	s_add_u32 s80, s80, s30
	s_addc_u32 s81, s81, s31
	s_add_i32 s17, s17, s3
	global_load_lds_dwordx4 v[226:227], off
	v_lshl_add_u64 v[228:229], s[80:81], 0, v[176:177]
	s_mov_b32 m0, s17
	v_lshl_add_u64 v[230:231], s[80:81], 0, v[132:133]
	global_load_lds_dwordx4 v[228:229], off
	s_add_i32 m0, s17, 0x2000
	v_lshl_add_u64 v[232:233], s[96:97], 0, v[128:129]
	global_load_lds_dwordx4 v[230:231], off
	s_mov_b32 m0, s16
	v_lshl_add_u64 v[234:235], s[96:97], 0, v[130:131]
	global_load_lds_dwordx4 v[232:233], off
	s_mov_b32 m0, s14
	s_nop 0
	global_load_lds_dwordx4 v[234:235], off
	s_waitcnt vmcnt(8)
	s_waitcnt lgkmcnt(0)
	s_barrier
; #define PG8_STAGE(bufoff, gbase, voff) do { _Pragma("unroll") for (int _i = 0; _i < 2; ++_i) \
;         __builtin_amdgcn_global_load_lds((const unsigned*)((const char*)(gbase) + (voff)[_i]), (LAS unsigned*)(lds + (bufoff) + ldsw + _i * 8192), 16, 0, 0); } while (0)
; #define PG8_LDA(dst, b, h) do { _Pragma("unroll") for (int m = 0; m < 4; ++m) _Pragma("unroll") for (int k = 0; k < 2; ++k) dst[m][k] = *(const LAS bf16x8*)(lds + PG8_SA(b, h) + aoff + m * 2048 + k * 1024); } while (0)
; #define PG8_LDB(dst, b, h) do { _Pragma("unroll") for (int n = 0; n < 2; ++n) _Pragma("unroll") for (int k = 0; k < 2; ++k) dst[n][k] = *(const LAS bf16x8*)(lds + PG8_SB(b, h) + boff + n * 2048 + k * 1024); } while (0)
; #define PG8_MMA(ai, bj, At, Bt) do { __builtin_amdgcn_s_setprio(1); _Pragma("unroll") for (int m = 0; m < 4; ++m) _Pragma("unroll") for (int n = 0; n < 2; ++n) _Pragma("unroll") for (int k = 0; k < 2; ++k) \
;         acc[ai][bj][m][n] = __builtin_amdgcn_mfma_f32_16x16x32_bf16(Bt[n][k], At[m][k], acc[ai][bj][m][n], 0, 0, 0); __builtin_amdgcn_s_setprio(0); } while (0)
; #define PG8_WAIT_V(n) asm volatile("s_waitcnt vmcnt(" #n ")" ::: "memory")
; #define PG8_WAIT_L(n) asm volatile("s_waitcnt lgkmcnt(" #n ")" ::: "memory")
; #define PG8_BAR __builtin_amdgcn_s_barrier()
; #define PG8_SCHED __builtin_amdgcn_sched_barrier(0)
; template <class Epi, class Sched, bool ALIGN_EPI>
; __device__ __forceinline__ void gemm_phase(LAS unsigned char* lds, const int wid, const int lda_, const int ldb_, const int K_, const Sched& S, const Epi& E) {
;     ...
;             PG8_LDB(B0, 0, 0); PG8_LDB(B1, 0, 1); PG8_SCHED; PG8_LDA(At, 0, 0); PG8_STAGE(PG8_SA(1, 1), a1 + hstepA, voffA);
;             PG8_WAIT_V(8); PG8_WAIT_L(0); PG8_BAR; PG8_MMA(0, 0, At, B0); PG8_MMA(0, 1, At, B1); PG8_BAR; PG8_SCHED;
;             PG8_LDA(At, 0, 1); PG8_STAGE(PG8_SB(0, 0), b2, voffB); PG8_STAGE(PG8_SB(0, 1), b2 + hstepB, voffB); PG8_STAGE(PG8_SA(0, 0), a2, voffA);
;             PG8_WAIT_V(8); PG8_WAIT_L(0); PG8_BAR; PG8_MMA(1, 0, At, B0); PG8_MMA(1, 1, At, B1); PG8_BAR; PG8_SCHED;
	s_waitcnt lgkmcnt(0)
	v_mfma_f32_16x16x32_bf16 v[60:63], v[156:159], v[192:195], 0
	v_mfma_f32_16x16x32_bf16 v[56:59], v[164:167], v[192:195], 0
	v_mfma_f32_16x16x32_bf16 v[52:55], v[156:159], v[200:203], 0
	v_mfma_f32_16x16x32_bf16 v[48:51], v[164:167], v[200:203], 0
	v_mfma_f32_16x16x32_bf16 v[36:39], v[156:159], v[208:211], 0
	v_mfma_f32_16x16x32_bf16 v[32:35], v[164:167], v[208:211], 0
	v_mfma_f32_16x16x32_bf16 v[20:23], v[156:159], v[216:219], 0
	v_mfma_f32_16x16x32_bf16 v[16:19], v[164:167], v[216:219], 0
	v_mfma_f32_16x16x32_bf16 v[60:63], v[160:163], v[196:199], v[60:63]
	v_mfma_f32_16x16x32_bf16 v[56:59], v[168:171], v[196:199], v[56:59]
	v_mfma_f32_16x16x32_bf16 v[52:55], v[160:163], v[204:207], v[52:55]
	v_mfma_f32_16x16x32_bf16 v[48:51], v[168:171], v[204:207], v[48:51]
	v_mfma_f32_16x16x32_bf16 v[36:39], v[160:163], v[212:215], v[36:39]
	v_mfma_f32_16x16x32_bf16 v[32:35], v[168:171], v[212:215], v[32:35]
	v_mfma_f32_16x16x32_bf16 v[20:23], v[160:163], v[220:223], v[20:23]
	v_mfma_f32_16x16x32_bf16 v[16:19], v[168:171], v[220:223], v[16:19]
	v_mfma_f32_16x16x32_bf16 v[44:47], v[172:175], v[192:195], 0
	v_mfma_f32_16x16x32_bf16 v[40:43], v[184:187], v[192:195], 0
	v_mfma_f32_16x16x32_bf16 v[28:31], v[172:175], v[200:203], 0
	v_mfma_f32_16x16x32_bf16 v[24:27], v[184:187], v[200:203], 0
	v_mfma_f32_16x16x32_bf16 v[12:15], v[172:175], v[208:211], 0
	v_mfma_f32_16x16x32_bf16 v[8:11], v[184:187], v[208:211], 0
	v_mfma_f32_16x16x32_bf16 v[4:7], v[172:175], v[216:219], 0
	v_mfma_f32_16x16x32_bf16 v[0:3], v[184:187], v[216:219], 0
	v_mfma_f32_16x16x32_bf16 v[44:47], v[180:183], v[196:199], v[44:47]
	v_mfma_f32_16x16x32_bf16 v[40:43], v[188:191], v[196:199], v[40:43]
	v_mfma_f32_16x16x32_bf16 v[28:31], v[180:183], v[204:207], v[28:31]
	v_mfma_f32_16x16x32_bf16 v[24:27], v[188:191], v[204:207], v[24:27]
	v_mfma_f32_16x16x32_bf16 v[12:15], v[180:183], v[212:215], v[12:15]
	v_mfma_f32_16x16x32_bf16 v[8:11], v[188:191], v[212:215], v[8:11]
	v_mfma_f32_16x16x32_bf16 v[4:7], v[180:183], v[220:223], v[4:7]
	v_mfma_f32_16x16x32_bf16 v[0:3], v[188:191], v[220:223], v[0:3]
	s_barrier
	s_branch .Lgemm_join_671
.LBB0_671:
	s_add_i32 s78, s77, 2
	s_add_u32 s17, s94, 0x80
	s_addc_u32 s27, s95, 0
	s_add_i32 s79, 0, 0x10000
	s_cmp_eq_u32 s41, s77
	s_cselect_b32 s97, s37, s27
	s_cselect_b32 s96, s39, s17
	v_add_u32_e32 v141, s79, v135
	s_cselect_b32 s81, s4, s76
	s_cselect_b32 s80, s5, s43
	s_add_i32 s17, 0, 0x14000
	ds_read_b128 v[156:159], v141
	ds_read_b128 v[160:163], v141 offset:1024
	ds_read_b128 v[164:167], v141 offset:2048
	ds_read_b128 v[168:171], v141 offset:3072
	v_add_u32_e32 v141, s17, v135
	ds_read_b128 v[172:175], v141
	ds_read_b128 v[180:183], v141 offset:1024
	ds_read_b128 v[184:187], v141 offset:2048
	ds_read_b128 v[188:191], v141 offset:3072
	v_lshl_add_u64 v[224:225], s[94:95], 0, v[152:153]
	s_add_i32 m0, s16, 0xc000
	ds_read_b128 v[192:195], v139
	ds_read_b128 v[196:199], v139 offset:1024
	ds_read_b128 v[200:203], v139 offset:2048
	ds_read_b128 v[204:207], v139 offset:3072
	ds_read_b128 v[208:211], v139 offset:4096
	ds_read_b128 v[212:215], v139 offset:5120
	ds_read_b128 v[216:219], v139 offset:6144
	ds_read_b128 v[220:223], v139 offset:7168
	global_load_lds_dwordx4 v[224:225], off
	v_lshl_add_u64 v[224:225], s[94:95], 0, v[154:155]
	s_add_i32 m0, s16, 0xe000
	s_nop 0
	global_load_lds_dwordx4 v[224:225], off
	s_waitcnt vmcnt(8)
	s_waitcnt lgkmcnt(0)
	s_barrier
	s_waitcnt lgkmcnt(0)
	v_mfma_f32_16x16x32_bf16 v[124:127], v[156:159], v[192:195], v[124:127]
	v_mfma_f32_16x16x32_bf16 v[120:123], v[164:167], v[192:195], v[120:123]
	v_mfma_f32_16x16x32_bf16 v[116:119], v[156:159], v[200:203], v[116:119]
	v_mfma_f32_16x16x32_bf16 v[112:115], v[164:167], v[200:203], v[112:115]
	v_mfma_f32_16x16x32_bf16 v[100:103], v[156:159], v[208:211], v[100:103]
	v_mfma_f32_16x16x32_bf16 v[96:99], v[164:167], v[208:211], v[96:99]
	v_mfma_f32_16x16x32_bf16 v[84:87], v[156:159], v[216:219], v[84:87]
	v_mfma_f32_16x16x32_bf16 v[80:83], v[164:167], v[216:219], v[80:83]
	v_mfma_f32_16x16x32_bf16 v[124:127], v[160:163], v[196:199], v[124:127]
	v_mfma_f32_16x16x32_bf16 v[120:123], v[168:171], v[196:199], v[120:123]
	v_mfma_f32_16x16x32_bf16 v[116:119], v[160:163], v[204:207], v[116:119]
	v_mfma_f32_16x16x32_bf16 v[112:115], v[168:171], v[204:207], v[112:115]
	v_mfma_f32_16x16x32_bf16 v[100:103], v[160:163], v[212:215], v[100:103]
	v_mfma_f32_16x16x32_bf16 v[96:99], v[168:171], v[212:215], v[96:99]
	v_mfma_f32_16x16x32_bf16 v[84:87], v[160:163], v[220:223], v[84:87]
	v_mfma_f32_16x16x32_bf16 v[80:83], v[168:171], v[220:223], v[80:83]
	v_mfma_f32_16x16x32_bf16 v[108:111], v[172:175], v[192:195], v[108:111]
	v_mfma_f32_16x16x32_bf16 v[104:107], v[184:187], v[192:195], v[104:107]
	v_mfma_f32_16x16x32_bf16 v[92:95], v[172:175], v[200:203], v[92:95]
	v_mfma_f32_16x16x32_bf16 v[88:91], v[184:187], v[200:203], v[88:91]
	v_mfma_f32_16x16x32_bf16 v[76:79], v[172:175], v[208:211], v[76:79]
	v_mfma_f32_16x16x32_bf16 v[72:75], v[184:187], v[208:211], v[72:75]
	v_mfma_f32_16x16x32_bf16 v[68:71], v[172:175], v[216:219], v[68:71]
	v_mfma_f32_16x16x32_bf16 v[64:67], v[184:187], v[216:219], v[64:67]
	v_mfma_f32_16x16x32_bf16 v[108:111], v[180:183], v[196:199], v[108:111]
	v_mfma_f32_16x16x32_bf16 v[104:107], v[188:191], v[196:199], v[104:107]
	v_mfma_f32_16x16x32_bf16 v[92:95], v[180:183], v[204:207], v[92:95]
	v_mfma_f32_16x16x32_bf16 v[88:91], v[188:191], v[204:207], v[88:91]
	v_mfma_f32_16x16x32_bf16 v[76:79], v[180:183], v[212:215], v[76:79]
	v_mfma_f32_16x16x32_bf16 v[72:75], v[188:191], v[212:215], v[72:75]
	v_mfma_f32_16x16x32_bf16 v[68:71], v[180:183], v[220:223], v[68:71]
	v_mfma_f32_16x16x32_bf16 v[64:67], v[188:191], v[220:223], v[64:67]
	s_barrier
; #define PG8_STAGE(bufoff, gbase, voff) do { _Pragma("unroll") for (int _i = 0; _i < 2; ++_i) \
;         __builtin_amdgcn_global_load_lds((const unsigned*)((const char*)(gbase) + (voff)[_i]), (LAS unsigned*)(lds + (bufoff) + ldsw + _i * 8192), 16, 0, 0); } while (0)
; #define PG8_LDA(dst, b, h) do { _Pragma("unroll") for (int m = 0; m < 4; ++m) _Pragma("unroll") for (int k = 0; k < 2; ++k) dst[m][k] = *(const LAS bf16x8*)(lds + PG8_SA(b, h) + aoff + m * 2048 + k * 1024); } while (0)
; #define PG8_LDB(dst, b, h) do { _Pragma("unroll") for (int n = 0; n < 2; ++n) _Pragma("unroll") for (int k = 0; k < 2; ++k) dst[n][k] = *(const LAS bf16x8*)(lds + PG8_SB(b, h) + boff + n * 2048 + k * 1024); } while (0)
; #define PG8_MMA(ai, bj, At, Bt) do { __builtin_amdgcn_s_setprio(1); _Pragma("unroll") for (int m = 0; m < 4; ++m) _Pragma("unroll") for (int n = 0; n < 2; ++n) _Pragma("unroll") for (int k = 0; k < 2; ++k) \
;         acc[ai][bj][m][n] = __builtin_amdgcn_mfma_f32_16x16x32_bf16(Bt[n][k], At[m][k], acc[ai][bj][m][n], 0, 0, 0); __builtin_amdgcn_s_setprio(0); } while (0)
; #define PG8_WAIT_V(n) asm volatile("s_waitcnt vmcnt(" #n ")" ::: "memory")
; #define PG8_WAIT_L(n) asm volatile("s_waitcnt lgkmcnt(" #n ")" ::: "memory")
; #define PG8_BAR __builtin_amdgcn_s_barrier()
; #define PG8_SCHED __builtin_amdgcn_sched_barrier(0)
; template <class Epi, class Sched, bool ALIGN_EPI>
; __device__ __forceinline__ void gemm_phase(LAS unsigned char* lds, const int wid, const int lda_, const int ldb_, const int K_, const Sched& S, const Epi& E) {
;     ...
;             PG8_LDA(At, 0, 1); PG8_STAGE(PG8_SB(0, 0), b2, voffB); PG8_STAGE(PG8_SB(0, 1), b2 + hstepB, voffB); PG8_STAGE(PG8_SA(0, 0), a2, voffA);
;             PG8_WAIT_V(8); PG8_WAIT_L(0); PG8_BAR; PG8_MMA(1, 0, At, B0); PG8_MMA(1, 1, At, B1); PG8_BAR; PG8_SCHED;
;             PG8_LDB(B0, 1, 0); PG8_LDB(B1, 1, 1); PG8_SCHED; PG8_LDA(At, 1, 0); PG8_STAGE(PG8_SA(0, 1), a2 + hstepA, voffA);
	s_add_i32 s27, s79, s3
	v_lshl_add_u64 v[224:225], s[80:81], 0, v[176:177]
	s_mov_b32 m0, s27
	ds_read_b128 v[192:195], v139 offset:16384
	ds_read_b128 v[196:199], v139 offset:17408
	ds_read_b128 v[200:203], v139 offset:18432
	ds_read_b128 v[204:207], v139 offset:19456
	ds_read_b128 v[208:211], v139 offset:20480
	ds_read_b128 v[212:215], v139 offset:21504
	ds_read_b128 v[216:219], v139 offset:22528
	ds_read_b128 v[220:223], v139 offset:23552
	global_load_lds_dwordx4 v[224:225], off
	s_add_i32 m0, s27, 0x2000
	v_lshl_add_u64 v[226:227], s[80:81], 0, v[132:133]
	s_add_u32 s80, s80, s30
	s_addc_u32 s81, s81, s31
	s_add_i32 s17, s17, s3
	global_load_lds_dwordx4 v[226:227], off
	v_lshl_add_u64 v[228:229], s[80:81], 0, v[176:177]
	s_mov_b32 m0, s17
	v_lshl_add_u64 v[230:231], s[80:81], 0, v[132:133]
	global_load_lds_dwordx4 v[228:229], off
	s_add_i32 m0, s17, 0x2000
	v_lshl_add_u64 v[232:233], s[96:97], 0, v[128:129]
	global_load_lds_dwordx4 v[230:231], off
	s_mov_b32 m0, s16
	v_lshl_add_u64 v[234:235], s[96:97], 0, v[130:131]
	global_load_lds_dwordx4 v[232:233], off
	s_mov_b32 m0, s14
	s_nop 0
	global_load_lds_dwordx4 v[234:235], off
	s_waitcnt vmcnt(8)
	s_waitcnt lgkmcnt(0)
	s_barrier
	s_waitcnt lgkmcnt(0)
	v_mfma_f32_16x16x32_bf16 v[60:63], v[156:159], v[192:195], v[60:63]
	v_mfma_f32_16x16x32_bf16 v[56:59], v[164:167], v[192:195], v[56:59]
	v_mfma_f32_16x16x32_bf16 v[52:55], v[156:159], v[200:203], v[52:55]
	v_mfma_f32_16x16x32_bf16 v[48:51], v[164:167], v[200:203], v[48:51]
	v_mfma_f32_16x16x32_bf16 v[36:39], v[156:159], v[208:211], v[36:39]
	v_mfma_f32_16x16x32_bf16 v[32:35], v[164:167], v[208:211], v[32:35]
	v_mfma_f32_16x16x32_bf16 v[20:23], v[156:159], v[216:219], v[20:23]
	v_mfma_f32_16x16x32_bf16 v[16:19], v[164:167], v[216:219], v[16:19]
	v_mfma_f32_16x16x32_bf16 v[60:63], v[160:163], v[196:199], v[60:63]
	v_mfma_f32_16x16x32_bf16 v[56:59], v[168:171], v[196:199], v[56:59]
	v_mfma_f32_16x16x32_bf16 v[52:55], v[160:163], v[204:207], v[52:55]
	v_mfma_f32_16x16x32_bf16 v[48:51], v[168:171], v[204:207], v[48:51]
	v_mfma_f32_16x16x32_bf16 v[36:39], v[160:163], v[212:215], v[36:39]
	v_mfma_f32_16x16x32_bf16 v[32:35], v[168:171], v[212:215], v[32:35]
	v_mfma_f32_16x16x32_bf16 v[20:23], v[160:163], v[220:223], v[20:23]
	v_mfma_f32_16x16x32_bf16 v[16:19], v[168:171], v[220:223], v[16:19]
	v_mfma_f32_16x16x32_bf16 v[44:47], v[172:175], v[192:195], v[44:47]
	v_mfma_f32_16x16x32_bf16 v[40:43], v[184:187], v[192:195], v[40:43]
	v_mfma_f32_16x16x32_bf16 v[28:31], v[172:175], v[200:203], v[28:31]
	v_mfma_f32_16x16x32_bf16 v[24:27], v[184:187], v[200:203], v[24:27]
	v_mfma_f32_16x16x32_bf16 v[12:15], v[172:175], v[208:211], v[12:15]
	v_mfma_f32_16x16x32_bf16 v[8:11], v[184:187], v[208:211], v[8:11]
	v_mfma_f32_16x16x32_bf16 v[4:7], v[172:175], v[216:219], v[4:7]
	v_mfma_f32_16x16x32_bf16 v[0:3], v[184:187], v[216:219], v[0:3]
	v_mfma_f32_16x16x32_bf16 v[44:47], v[180:183], v[196:199], v[44:47]
	v_mfma_f32_16x16x32_bf16 v[40:43], v[188:191], v[196:199], v[40:43]
	v_mfma_f32_16x16x32_bf16 v[28:31], v[180:183], v[204:207], v[28:31]
	v_mfma_f32_16x16x32_bf16 v[24:27], v[188:191], v[204:207], v[24:27]
	v_mfma_f32_16x16x32_bf16 v[12:15], v[180:183], v[212:215], v[12:15]
	v_mfma_f32_16x16x32_bf16 v[8:11], v[188:191], v[212:215], v[8:11]
	v_mfma_f32_16x16x32_bf16 v[4:7], v[180:183], v[220:223], v[4:7]
	v_mfma_f32_16x16x32_bf16 v[0:3], v[188:191], v[220:223], v[0:3]
	s_barrier
.Lgemm_join_671:
	s_add_i32 s17, 0, 0x18000
	v_add_u32_e32 v141, s17, v135
	s_add_i32 s27, 0, 0x1c000
	ds_read_b128 v[156:159], v141
	ds_read_b128 v[160:163], v141 offset:1024
	ds_read_b128 v[164:167], v141 offset:2048
	ds_read_b128 v[168:171], v141 offset:3072
	v_add_u32_e32 v141, s27, v135
	ds_read_b128 v[172:175], v141
	ds_read_b128 v[180:183], v141 offset:1024
	ds_read_b128 v[184:187], v141 offset:2048
	ds_read_b128 v[188:191], v141 offset:3072
	s_add_u32 s80, s96, s10
	s_addc_u32 s81, s97, s11
	s_mov_b32 m0, s15
	v_lshl_add_u64 v[236:237], s[80:81], 0, v[128:129]
	ds_read_b128 v[192:195], v139 offset:32768
	ds_read_b128 v[196:199], v139 offset:33792
	ds_read_b128 v[200:203], v139 offset:34816
	ds_read_b128 v[204:207], v139 offset:35840
	ds_read_b128 v[208:211], v139 offset:36864
	ds_read_b128 v[212:215], v139 offset:37888
	ds_read_b128 v[216:219], v139 offset:38912
	ds_read_b128 v[220:223], v139 offset:39936
	global_load_lds_dwordx4 v[236:237], off
	v_lshl_add_u64 v[236:237], s[80:81], 0, v[130:131]
	s_mov_b32 m0, s26
	s_nop 0
	global_load_lds_dwordx4 v[236:237], off
	s_waitcnt vmcnt(8)
	s_waitcnt lgkmcnt(0)
	s_barrier
; #define PG8_STAGE(bufoff, gbase, voff) do { _Pragma("unroll") for (int _i = 0; _i < 2; ++_i) \
;         __builtin_amdgcn_global_load_lds((const unsigned*)((const char*)(gbase) + (voff)[_i]), (LAS unsigned*)(lds + (bufoff) + ldsw + _i * 8192), 16, 0, 0); } while (0)
; #define PG8_LDA(dst, b, h) do { _Pragma("unroll") for (int m = 0; m < 4; ++m) _Pragma("unroll") for (int k = 0; k < 2; ++k) dst[m][k] = *(const LAS bf16x8*)(lds + PG8_SA(b, h) + aoff + m * 2048 + k * 1024); } while (0)
; #define PG8_MMA(ai, bj, At, Bt) do { __builtin_amdgcn_s_setprio(1); _Pragma("unroll") for (int m = 0; m < 4; ++m) _Pragma("unroll") for (int n = 0; n < 2; ++n) _Pragma("unroll") for (int k = 0; k < 2; ++k) \
;         acc[ai][bj][m][n] = __builtin_amdgcn_mfma_f32_16x16x32_bf16(Bt[n][k], At[m][k], acc[ai][bj][m][n], 0, 0, 0); __builtin_amdgcn_s_setprio(0); } while (0)
; #define PG8_WAIT_V(n) asm volatile("s_waitcnt vmcnt(" #n ")" ::: "memory")
; #define PG8_WAIT_L(n) asm volatile("s_waitcnt lgkmcnt(" #n ")" ::: "memory")
; #define PG8_BAR __builtin_amdgcn_s_barrier()
; #define PG8_SCHED __builtin_amdgcn_sched_barrier(0)
; template <class Epi, class Sched, bool ALIGN_EPI>
; __device__ __forceinline__ void gemm_phase(LAS unsigned char* lds, const int wid, const int lda_, const int ldb_, const int K_, const Sched& S, const Epi& E) {
;     ...
;             PG8_WAIT_V(8); PG8_WAIT_L(0); PG8_BAR; PG8_MMA(0, 0, At, B0); PG8_MMA(0, 1, At, B1); PG8_BAR; PG8_SCHED;
;             PG8_LDA(At, 1, 1); PG8_STAGE(PG8_SB(1, 0), b3, voffB); PG8_STAGE(PG8_SB(1, 1), b3 + hstepB, voffB); PG8_STAGE(PG8_SA(1, 0), a3, voffA);
;             PG8_WAIT_V(8); PG8_WAIT_L(0); PG8_BAR; PG8_MMA(1, 0, At, B0); PG8_MMA(1, 1, At, B1); PG8_BAR; PG8_SCHED;
;         }
;         if constexpr (ALIGN_EPI) { if (wr == 0) PG8_BAR; }
;         E(acc, cur, S, wr, wc, fr, fq);
;     __device__ __forceinline__ void out(const pg8::Unit& u, char*& o, int& ldo, int& kind) const { ldo = D;
;         if (u.kq < 0) { o = (char*)ws + YOFF + ((size_t)u.pm * 256 * D + (size_t)u.pn * 256) * 2; kind = 0; }
;         else { o = (char*)ws + WS_PART + (((size_t)u.kq * MCTX + (size_t)(u.pm - 64) * 256) * D + (size_t)u.pn * 256) * 2; kind = 0; } }
	s_waitcnt lgkmcnt(0)
	v_mfma_f32_16x16x32_bf16 v[124:127], v[156:159], v[192:195], v[124:127]
	v_mfma_f32_16x16x32_bf16 v[120:123], v[164:167], v[192:195], v[120:123]
	v_mfma_f32_16x16x32_bf16 v[116:119], v[156:159], v[200:203], v[116:119]
	v_mfma_f32_16x16x32_bf16 v[112:115], v[164:167], v[200:203], v[112:115]
	v_mfma_f32_16x16x32_bf16 v[100:103], v[156:159], v[208:211], v[100:103]
	v_mfma_f32_16x16x32_bf16 v[96:99], v[164:167], v[208:211], v[96:99]
	v_mfma_f32_16x16x32_bf16 v[84:87], v[156:159], v[216:219], v[84:87]
	v_mfma_f32_16x16x32_bf16 v[80:83], v[164:167], v[216:219], v[80:83]
	v_mfma_f32_16x16x32_bf16 v[124:127], v[160:163], v[196:199], v[124:127]
	v_mfma_f32_16x16x32_bf16 v[120:123], v[168:171], v[196:199], v[120:123]
	v_mfma_f32_16x16x32_bf16 v[116:119], v[160:163], v[204:207], v[116:119]
	v_mfma_f32_16x16x32_bf16 v[112:115], v[168:171], v[204:207], v[112:115]
	v_mfma_f32_16x16x32_bf16 v[100:103], v[160:163], v[212:215], v[100:103]
	v_mfma_f32_16x16x32_bf16 v[96:99], v[168:171], v[212:215], v[96:99]
	v_mfma_f32_16x16x32_bf16 v[84:87], v[160:163], v[220:223], v[84:87]
	v_mfma_f32_16x16x32_bf16 v[80:83], v[168:171], v[220:223], v[80:83]
	v_mfma_f32_16x16x32_bf16 v[108:111], v[172:175], v[192:195], v[108:111]
	v_mfma_f32_16x16x32_bf16 v[104:107], v[184:187], v[192:195], v[104:107]
	v_mfma_f32_16x16x32_bf16 v[92:95], v[172:175], v[200:203], v[92:95]
	v_mfma_f32_16x16x32_bf16 v[88:91], v[184:187], v[200:203], v[88:91]
	v_mfma_f32_16x16x32_bf16 v[76:79], v[172:175], v[208:211], v[76:79]
	v_mfma_f32_16x16x32_bf16 v[72:75], v[184:187], v[208:211], v[72:75]
	v_mfma_f32_16x16x32_bf16 v[68:71], v[172:175], v[216:219], v[68:71]
	v_mfma_f32_16x16x32_bf16 v[64:67], v[184:187], v[216:219], v[64:67]
	v_mfma_f32_16x16x32_bf16 v[108:111], v[180:183], v[196:199], v[108:111]
	v_mfma_f32_16x16x32_bf16 v[104:107], v[188:191], v[196:199], v[104:107]
	v_mfma_f32_16x16x32_bf16 v[92:95], v[180:183], v[204:207], v[92:95]
	v_mfma_f32_16x16x32_bf16 v[88:91], v[188:191], v[204:207], v[88:91]
	v_mfma_f32_16x16x32_bf16 v[76:79], v[180:183], v[212:215], v[76:79]
	v_mfma_f32_16x16x32_bf16 v[72:75], v[188:191], v[212:215], v[72:75]
	v_mfma_f32_16x16x32_bf16 v[68:71], v[180:183], v[220:223], v[68:71]
	v_mfma_f32_16x16x32_bf16 v[64:67], v[188:191], v[220:223], v[64:67]
	s_barrier
	s_add_i32 s17, s17, s3
	v_lshl_add_u64 v[224:225], v[224:225], 0, s[24:25]
	s_mov_b32 m0, s17
	ds_read_b128 v[192:195], v139 offset:49152
	ds_read_b128 v[196:199], v139 offset:50176
	ds_read_b128 v[200:203], v139 offset:51200
	ds_read_b128 v[204:207], v139 offset:52224
	ds_read_b128 v[208:211], v139 offset:53248
	ds_read_b128 v[212:215], v139 offset:54272
	ds_read_b128 v[216:219], v139 offset:55296
	ds_read_b128 v[220:223], v139 offset:56320
	global_load_lds_dwordx4 v[224:225], off
	v_lshl_add_u64 v[224:225], v[226:227], 0, s[24:25]
	s_add_i32 m0, s17, 0x2000
	s_add_i32 s17, s27, s3
	global_load_lds_dwordx4 v[224:225], off
	v_lshl_add_u64 v[224:225], v[228:229], 0, s[24:25]
	s_mov_b32 m0, s17
	s_nop 0
	global_load_lds_dwordx4 v[224:225], off
	v_lshl_add_u64 v[224:225], v[230:231], 0, s[24:25]
	s_add_i32 m0, s17, 0x2000
	s_nop 0
	global_load_lds_dwordx4 v[224:225], off
	v_lshl_add_u64 v[224:225], v[232:233], 0, s[24:25]
	s_mov_b32 m0, s72
	s_nop 0
	global_load_lds_dwordx4 v[224:225], off
	v_lshl_add_u64 v[224:225], v[234:235], 0, s[24:25]
	s_mov_b32 m0, s73
	s_nop 0
	global_load_lds_dwordx4 v[224:225], off
	s_waitcnt vmcnt(8)
	s_waitcnt lgkmcnt(0)
	s_barrier
	s_waitcnt lgkmcnt(0)
	v_mfma_f32_16x16x32_bf16 v[60:63], v[156:159], v[192:195], v[60:63]
	v_mfma_f32_16x16x32_bf16 v[56:59], v[164:167], v[192:195], v[56:59]
	v_mfma_f32_16x16x32_bf16 v[52:55], v[156:159], v[200:203], v[52:55]
	v_mfma_f32_16x16x32_bf16 v[48:51], v[164:167], v[200:203], v[48:51]
	v_mfma_f32_16x16x32_bf16 v[36:39], v[156:159], v[208:211], v[36:39]
	v_mfma_f32_16x16x32_bf16 v[32:35], v[164:167], v[208:211], v[32:35]
	v_mfma_f32_16x16x32_bf16 v[20:23], v[156:159], v[216:219], v[20:23]
	v_mfma_f32_16x16x32_bf16 v[16:19], v[164:167], v[216:219], v[16:19]
	v_mfma_f32_16x16x32_bf16 v[60:63], v[160:163], v[196:199], v[60:63]
	v_mfma_f32_16x16x32_bf16 v[56:59], v[168:171], v[196:199], v[56:59]
	v_mfma_f32_16x16x32_bf16 v[52:55], v[160:163], v[204:207], v[52:55]
	v_mfma_f32_16x16x32_bf16 v[48:51], v[168:171], v[204:207], v[48:51]
	v_mfma_f32_16x16x32_bf16 v[36:39], v[160:163], v[212:215], v[36:39]
	v_mfma_f32_16x16x32_bf16 v[32:35], v[168:171], v[212:215], v[32:35]
	v_mfma_f32_16x16x32_bf16 v[20:23], v[160:163], v[220:223], v[20:23]
	v_mfma_f32_16x16x32_bf16 v[16:19], v[168:171], v[220:223], v[16:19]
	v_mfma_f32_16x16x32_bf16 v[44:47], v[172:175], v[192:195], v[44:47]
	v_mfma_f32_16x16x32_bf16 v[40:43], v[184:187], v[192:195], v[40:43]
	v_mfma_f32_16x16x32_bf16 v[28:31], v[172:175], v[200:203], v[28:31]
	v_mfma_f32_16x16x32_bf16 v[24:27], v[184:187], v[200:203], v[24:27]
	v_mfma_f32_16x16x32_bf16 v[12:15], v[172:175], v[208:211], v[12:15]
	v_mfma_f32_16x16x32_bf16 v[8:11], v[184:187], v[208:211], v[8:11]
	v_mfma_f32_16x16x32_bf16 v[4:7], v[172:175], v[216:219], v[4:7]
	v_mfma_f32_16x16x32_bf16 v[0:3], v[184:187], v[216:219], v[0:3]
	v_mfma_f32_16x16x32_bf16 v[44:47], v[180:183], v[196:199], v[44:47]
	v_mfma_f32_16x16x32_bf16 v[40:43], v[188:191], v[196:199], v[40:43]
	v_mfma_f32_16x16x32_bf16 v[28:31], v[180:183], v[204:207], v[28:31]
	v_mfma_f32_16x16x32_bf16 v[24:27], v[188:191], v[204:207], v[24:27]
	v_mfma_f32_16x16x32_bf16 v[12:15], v[180:183], v[212:215], v[12:15]
	v_mfma_f32_16x16x32_bf16 v[8:11], v[188:191], v[212:215], v[8:11]
	v_mfma_f32_16x16x32_bf16 v[4:7], v[180:183], v[220:223], v[4:7]
	v_mfma_f32_16x16x32_bf16 v[0:3], v[188:191], v[220:223], v[0:3]
	s_barrier
	s_add_u32 s94, s94, 0x100
	s_addc_u32 s95, s95, 0
	s_add_u32 s43, s43, 0x100
	s_addc_u32 s76, s76, 0
	s_cmp_ge_u32 s78, s35
	s_mov_b32 s77, s78
	s_cbranch_scc0 .LBB0_671
	s_setprio 2
	s_mov_b64 s[94:95], -1
	s_and_b64 vcc, exec, s[50:51]
	s_cbranch_vccz .LBB0_674
	s_mov_b32 s39, s92
	s_ashr_i32 s35, s34, 31
	s_ashr_i32 s37, s36, 31
	s_lshl_b64 s[4:5], s[34:35], 20
	s_lshl_b64 s[50:51], s[36:37], 9
	s_lshl_b64 s[38:39], s[38:39], 23
	v_readlane_b32 s76, v251, 28
	v_readlane_b32 s77, v251, 29
	s_add_u32 s17, s76, s50
	s_addc_u32 s27, s77, s51
	s_add_u32 s17, s17, s38
	s_addc_u32 s27, s27, s39
	s_add_u32 s4, s17, s4
	s_addc_u32 s5, s27, s5
	s_add_u32 s4, s4, 0xfc000000
	s_addc_u32 s5, s5, -1
	s_mov_b64 s[94:95], 0

; #define PG8_STAGE(bufoff, gbase, voff) do { _Pragma("unroll") for (int _i = 0; _i < 2; ++_i) \
;         __builtin_amdgcn_global_load_lds((const unsigned*)((const char*)(gbase) + (voff)[_i]), (LAS unsigned*)(lds + (bufoff) + ldsw + _i * 8192), 16, 0, 0); } while (0)
; #define PG8_LDA(dst, b, h) do { _Pragma("unroll") for (int m = 0; m < 4; ++m) _Pragma("unroll") for (int k = 0; k < 2; ++k) dst[m][k] = *(const LAS bf16x8*)(lds + PG8_SA(b, h) + aoff + m * 2048 + k * 1024); } while (0)
; #define PG8_LDB(dst, b, h) do { _Pragma("unroll") for (int n = 0; n < 2; ++n) _Pragma("unroll") for (int k = 0; k < 2; ++k) dst[n][k] = *(const LAS bf16x8*)(lds + PG8_SB(b, h) + boff + n * 2048 + k * 1024); } while (0)
; #define PG8_WAIT_V(n) asm volatile("s_waitcnt vmcnt(" #n ")" ::: "memory")
; template <class Epi, class Sched, bool ALIGN_EPI>
; __device__ __forceinline__ void gemm_phase(LAS unsigned char* lds, const int wid, const int lda_, const int ldb_, const int K_, const Sched& S, const Epi& E) {
;     ...
;         const bool has_next = S.next(ui + 1, nxt);
;         const int nt = S.nt(cur);
;         const char* nA = has_next ? S.a(nxt) : cA; const char* nB = has_next ? S.b(nxt) : cB;
; #pragma unroll 1
;         for (int t = 0; t < nt; t += 2) {
;             const bool last = (t == nt - 2);
;             const char* a1 = cA + (size_t)(t + 1) * kstep;
;             const char* a2 = last ? nA : cA + (size_t)(t + 2) * kstep; const char* b2 = last ? nB : cB + (size_t)(t + 2) * kstep;
;             const char* a3 = a2 + kstep; const char* b3 = b2 + kstep;
;             PG8_LDB(B0, 0, 0); PG8_LDB(B1, 0, 1); PG8_SCHED; PG8_LDA(At, 0, 0); PG8_STAGE(PG8_SA(1, 1), a1 + hstepA, voffA);
;             PG8_WAIT_V(8); PG8_WAIT_L(0); PG8_BAR; PG8_MMA(0, 0, At, B0); PG8_MMA(0, 1, At, B1); PG8_BAR; PG8_SCHED;
;             PG8_LDA(At, 0, 1); PG8_STAGE(PG8_SB(0, 0), b2, voffB); PG8_STAGE(PG8_SB(0, 1), b2 + hstepB, voffB); PG8_STAGE(PG8_SA(0, 0), a2, voffA);
;     __device__ __forceinline__ bool next(int i, pg8::Unit& u) const { return pg8::tile2d<72>(i, 16, u); }
;     __device__ __forceinline__ const char* a(const pg8::Unit& u) const { return (const char*)ws + WS_W1 + (size_t)(u.pm & 1) * 256 * 256 * 2; }
;     __device__ __forceinline__ const char* b(const pg8::Unit& u) const { return (const char*)ws + WS_A + ((size_t)u.pn * 256 * D + (size_t)(u.pm >> 1) * 256) * 2; }
.LBB0_696:
	v_mov_b64_e32 v[0:1], 0x480
	v_cmp_lt_i64_e32 vcc, s[4:5], v[0:1]
	s_lshl_b32 s4, s73, 17
	s_and_b32 s4, s4, 0x20000
	v_readlane_b32 s5, v253, 31
	s_add_u32 s34, s5, s4
	v_readlane_b32 s4, v253, 32
	s_addc_u32 s35, s4, 0
	s_and_b64 s[4:5], vcc, exec
	s_cselect_b32 s4, s35, s45
	s_cselect_b32 s5, s34, s44
	s_ashr_i32 s36, s73, 1
	s_ashr_i32 s31, s30, 31
	s_ashr_i32 s37, s36, 31
	s_lshl_b64 s[36:37], s[36:37], 9
	s_lshl_b64 s[42:43], s[30:31], 20
	v_readlane_b32 s46, v253, 52
	v_readlane_b32 s47, v253, 53
	s_add_u32 s31, s46, s42
	s_addc_u32 s42, s47, s43
	s_add_u32 s36, s31, s36
	s_addc_u32 s37, s42, s37
	s_and_b64 s[42:43], vcc, exec
	s_cselect_b32 s31, s37, s41
	s_cselect_b32 s76, s36, s40
	s_mov_b64 s[50:51], 0
	s_mov_b64 s[46:47], -1
	s_mov_b64 s[48:49], 0
	s_add_u32 s77, s44, s50
	s_addc_u32 s78, s45, s51
	s_add_u32 s79, s77, 0x100
	s_addc_u32 s80, s78, 0
	s_and_b64 s[42:43], s[48:49], exec
	s_cselect_b32 s95, s4, s80
	s_cselect_b32 s94, s5, s79
	s_add_u32 s42, s40, s50
	s_addc_u32 s43, s41, s51
	s_add_u32 s50, s42, 0x100
	s_addc_u32 s51, s43, 0
	s_add_i32 s93, 0, 0x10000
	s_and_b64 s[42:43], s[48:49], exec
	s_cselect_b32 s51, s31, s51
	s_cselect_b32 s50, s76, s50
	s_add_i32 s42, 0, 0x14000
	v_add_u32_e32 v141, s93, v135
	s_add_u32 vcc_lo, s77, s0
	ds_read_b128 v[152:155], v141
	ds_read_b128 v[156:159], v141 offset:1024
	ds_read_b128 v[160:163], v141 offset:2048
	ds_read_b128 v[164:167], v141 offset:3072
	v_add_u32_e32 v141, s42, v135
	s_addc_u32 vcc_hi, s78, s1
	s_add_i32 s87, s93, s3
	ds_read_b128 v[168:171], v141
	ds_read_b128 v[172:175], v141 offset:1024
	ds_read_b128 v[180:183], v141 offset:2048
	ds_read_b128 v[184:187], v141 offset:3072
	s_add_i32 m0, s16, 0xc000
	s_add_i32 s27, s16, 0xe000
	s_add_i32 s80, s87, 0x2000
	s_add_u32 s96, s50, s10
	s_addc_u32 s97, s51, s11
	s_add_i32 s86, s42, s3
	s_add_i32 s81, s86, 0x2000
	s_add_i32 s79, 0, 0x18000
	s_add_i32 s78, 0, 0x1c000
	s_add_u32 s48, s94, s0
	s_addc_u32 s49, s95, s1
	s_add_i32 s77, s79, s3
	s_add_i32 s93, s78, s3
	s_add_i32 s43, s77, 0x2000
	s_add_i32 s42, s93, 0x2000
	v_lshl_add_u64 v[220:221], vcc, 0, v[132:133]
	v_lshl_add_u64 v[220:221], v[220:221], 0, s[24:25]
	ds_read_b128 v[188:191], v139
	ds_read_b128 v[192:195], v139 offset:1024
	ds_read_b128 v[196:199], v139 offset:2048
	ds_read_b128 v[200:203], v139 offset:3072
	ds_read_b128 v[204:207], v139 offset:4096
	ds_read_b128 v[208:211], v139 offset:5120
	ds_read_b128 v[212:215], v139 offset:6144
	ds_read_b128 v[216:219], v139 offset:7168
	global_load_lds_dwordx4 v[220:221], off
	v_lshl_add_u64 v[220:221], vcc, 0, v[130:131]
	v_lshl_add_u64 v[220:221], v[220:221], 0, s[24:25]
	s_mov_b32 m0, s27
	s_nop 0
	global_load_lds_dwordx4 v[220:221], off
	s_waitcnt vmcnt(8)
	s_waitcnt lgkmcnt(0)
	s_barrier
	s_setprio 0
	s_waitcnt lgkmcnt(0)
	v_mfma_f32_16x16x32_bf16 v[124:127], v[152:155], v[188:191], 0
	v_mfma_f32_16x16x32_bf16 v[120:123], v[160:163], v[188:191], 0
	v_mfma_f32_16x16x32_bf16 v[116:119], v[152:155], v[196:199], 0
	v_mfma_f32_16x16x32_bf16 v[112:115], v[160:163], v[196:199], 0
	v_mfma_f32_16x16x32_bf16 v[100:103], v[152:155], v[204:207], 0
	v_mfma_f32_16x16x32_bf16 v[96:99], v[160:163], v[204:207], 0
	v_mfma_f32_16x16x32_bf16 v[84:87], v[152:155], v[212:215], 0
	v_mfma_f32_16x16x32_bf16 v[80:83], v[160:163], v[212:215], 0
	v_mfma_f32_16x16x32_bf16 v[124:127], v[156:159], v[192:195], v[124:127]
	v_mfma_f32_16x16x32_bf16 v[120:123], v[164:167], v[192:195], v[120:123]
	v_mfma_f32_16x16x32_bf16 v[116:119], v[156:159], v[200:203], v[116:119]
	v_mfma_f32_16x16x32_bf16 v[112:115], v[164:167], v[200:203], v[112:115]
	v_mfma_f32_16x16x32_bf16 v[100:103], v[156:159], v[208:211], v[100:103]
	v_mfma_f32_16x16x32_bf16 v[96:99], v[164:167], v[208:211], v[96:99]
	v_mfma_f32_16x16x32_bf16 v[84:87], v[156:159], v[216:219], v[84:87]
	v_mfma_f32_16x16x32_bf16 v[80:83], v[164:167], v[216:219], v[80:83]
	v_mfma_f32_16x16x32_bf16 v[108:111], v[168:171], v[188:191], 0
	v_mfma_f32_16x16x32_bf16 v[104:107], v[180:183], v[188:191], 0
	v_mfma_f32_16x16x32_bf16 v[92:95], v[168:171], v[196:199], 0
	v_mfma_f32_16x16x32_bf16 v[88:91], v[180:183], v[196:199], 0
	v_mfma_f32_16x16x32_bf16 v[76:79], v[168:171], v[204:207], 0
	v_mfma_f32_16x16x32_bf16 v[72:75], v[180:183], v[204:207], 0
	v_mfma_f32_16x16x32_bf16 v[68:71], v[168:171], v[212:215], 0
	v_mfma_f32_16x16x32_bf16 v[64:67], v[180:183], v[212:215], 0
	v_mfma_f32_16x16x32_bf16 v[108:111], v[172:175], v[192:195], v[108:111]
	v_mfma_f32_16x16x32_bf16 v[104:107], v[184:187], v[192:195], v[104:107]
	v_mfma_f32_16x16x32_bf16 v[92:95], v[172:175], v[200:203], v[92:95]
	v_mfma_f32_16x16x32_bf16 v[88:91], v[184:187], v[200:203], v[88:91]
	v_mfma_f32_16x16x32_bf16 v[76:79], v[172:175], v[208:211], v[76:79]
	v_mfma_f32_16x16x32_bf16 v[72:75], v[184:187], v[208:211], v[72:75]
	v_mfma_f32_16x16x32_bf16 v[68:71], v[172:175], v[216:219], v[68:71]
	v_mfma_f32_16x16x32_bf16 v[64:67], v[184:187], v[216:219], v[64:67]
	s_barrier
	s_mov_b32 m0, s87
	v_lshl_add_u64 v[220:221], s[50:51], 0, v[176:177]
	ds_read_b128 v[188:191], v139 offset:16384
	ds_read_b128 v[192:195], v139 offset:17408
	ds_read_b128 v[196:199], v139 offset:18432
	ds_read_b128 v[200:203], v139 offset:19456
	ds_read_b128 v[204:207], v139 offset:20480
	ds_read_b128 v[208:211], v139 offset:21504
	ds_read_b128 v[212:215], v139 offset:22528
	ds_read_b128 v[216:219], v139 offset:23552
	global_load_lds_dwordx4 v[220:221], off
	v_lshl_add_u64 v[222:223], s[50:51], 0, v[128:129]
	s_mov_b32 m0, s80
	v_lshl_add_u64 v[224:225], s[96:97], 0, v[176:177]
	global_load_lds_dwordx4 v[222:223], off
	s_mov_b32 m0, s86
	v_lshl_add_u64 v[226:227], s[96:97], 0, v[128:129]
	global_load_lds_dwordx4 v[224:225], off
	s_mov_b32 m0, s81
	v_lshl_add_u64 v[228:229], s[94:95], 0, v[132:133]
	global_load_lds_dwordx4 v[226:227], off
	s_mov_b32 m0, s16
	v_lshl_add_u64 v[230:231], s[94:95], 0, v[130:131]
	global_load_lds_dwordx4 v[228:229], off
	s_mov_b32 m0, s6
	s_nop 0
	global_load_lds_dwordx4 v[230:231], off
	s_waitcnt vmcnt(8)
	s_waitcnt lgkmcnt(0)
	s_barrier
; #define PG8_STAGE(bufoff, gbase, voff) do { _Pragma("unroll") for (int _i = 0; _i < 2; ++_i) \
;         __builtin_amdgcn_global_load_lds((const unsigned*)((const char*)(gbase) + (voff)[_i]), (LAS unsigned*)(lds + (bufoff) + ldsw + _i * 8192), 16, 0, 0); } while (0)
; #define PG8_LDA(dst, b, h) do { _Pragma("unroll") for (int m = 0; m < 4; ++m) _Pragma("unroll") for (int k = 0; k < 2; ++k) dst[m][k] = *(const LAS bf16x8*)(lds + PG8_SA(b, h) + aoff + m * 2048 + k * 1024); } while (0)
; #define PG8_LDB(dst, b, h) do { _Pragma("unroll") for (int n = 0; n < 2; ++n) _Pragma("unroll") for (int k = 0; k < 2; ++k) dst[n][k] = *(const LAS bf16x8*)(lds + PG8_SB(b, h) + boff + n * 2048 + k * 1024); } while (0)
; #define PG8_MMA(ai, bj, At, Bt) do { __builtin_amdgcn_s_setprio(1); _Pragma("unroll") for (int m = 0; m < 4; ++m) _Pragma("unroll") for (int n = 0; n < 2; ++n) _Pragma("unroll") for (int k = 0; k < 2; ++k) \
;         acc[ai][bj][m][n] = __builtin_amdgcn_mfma_f32_16x16x32_bf16(Bt[n][k], At[m][k], acc[ai][bj][m][n], 0, 0, 0); __builtin_amdgcn_s_setprio(0); } while (0)
; #define PG8_WAIT_V(n) asm volatile("s_waitcnt vmcnt(" #n ")" ::: "memory")
; #define PG8_WAIT_L(n) asm volatile("s_waitcnt lgkmcnt(" #n ")" ::: "memory")
; #define PG8_BAR __builtin_amdgcn_s_barrier()
; #define PG8_SCHED __builtin_amdgcn_sched_barrier(0)
; template <class Epi, class Sched, bool ALIGN_EPI>
; __device__ __forceinline__ void gemm_phase(LAS unsigned char* lds, const int wid, const int lda_, const int ldb_, const int K_, const Sched& S, const Epi& E) {
;     ...
;             PG8_LDB(B0, 0, 0); PG8_LDB(B1, 0, 1); PG8_SCHED; PG8_LDA(At, 0, 0); PG8_STAGE(PG8_SA(1, 1), a1 + hstepA, voffA);
;             PG8_WAIT_V(8); PG8_WAIT_L(0); PG8_BAR; PG8_MMA(0, 0, At, B0); PG8_MMA(0, 1, At, B1); PG8_BAR; PG8_SCHED;
;             PG8_LDA(At, 0, 1); PG8_STAGE(PG8_SB(0, 0), b2, voffB); PG8_STAGE(PG8_SB(0, 1), b2 + hstepB, voffB); PG8_STAGE(PG8_SA(0, 0), a2, voffA);
;             PG8_WAIT_V(8); PG8_WAIT_L(0); PG8_BAR; PG8_MMA(1, 0, At, B0); PG8_MMA(1, 1, At, B1); PG8_BAR; PG8_SCHED;
	s_waitcnt lgkmcnt(0)
	v_mfma_f32_16x16x32_bf16 v[60:63], v[152:155], v[188:191], 0
	v_mfma_f32_16x16x32_bf16 v[56:59], v[160:163], v[188:191], 0
	v_mfma_f32_16x16x32_bf16 v[52:55], v[152:155], v[196:199], 0
	v_mfma_f32_16x16x32_bf16 v[48:51], v[160:163], v[196:199], 0
	v_mfma_f32_16x16x32_bf16 v[36:39], v[152:155], v[204:207], 0
	v_mfma_f32_16x16x32_bf16 v[32:35], v[160:163], v[204:207], 0
	v_mfma_f32_16x16x32_bf16 v[20:23], v[152:155], v[212:215], 0
	v_mfma_f32_16x16x32_bf16 v[16:19], v[160:163], v[212:215], 0
	v_mfma_f32_16x16x32_bf16 v[60:63], v[156:159], v[192:195], v[60:63]
	v_mfma_f32_16x16x32_bf16 v[56:59], v[164:167], v[192:195], v[56:59]
	v_mfma_f32_16x16x32_bf16 v[52:55], v[156:159], v[200:203], v[52:55]
	v_mfma_f32_16x16x32_bf16 v[48:51], v[164:167], v[200:203], v[48:51]
	v_mfma_f32_16x16x32_bf16 v[36:39], v[156:159], v[208:211], v[36:39]
	v_mfma_f32_16x16x32_bf16 v[32:35], v[164:167], v[208:211], v[32:35]
	v_mfma_f32_16x16x32_bf16 v[20:23], v[156:159], v[216:219], v[20:23]
	v_mfma_f32_16x16x32_bf16 v[16:19], v[164:167], v[216:219], v[16:19]
	v_mfma_f32_16x16x32_bf16 v[44:47], v[168:171], v[188:191], 0
	v_mfma_f32_16x16x32_bf16 v[40:43], v[180:183], v[188:191], 0
	v_mfma_f32_16x16x32_bf16 v[28:31], v[168:171], v[196:199], 0
	v_mfma_f32_16x16x32_bf16 v[24:27], v[180:183], v[196:199], 0
	v_mfma_f32_16x16x32_bf16 v[12:15], v[168:171], v[204:207], 0
	v_mfma_f32_16x16x32_bf16 v[8:11], v[180:183], v[204:207], 0
	v_mfma_f32_16x16x32_bf16 v[4:7], v[168:171], v[212:215], 0
	v_mfma_f32_16x16x32_bf16 v[0:3], v[180:183], v[212:215], 0
	v_mfma_f32_16x16x32_bf16 v[44:47], v[172:175], v[192:195], v[44:47]
	v_mfma_f32_16x16x32_bf16 v[40:43], v[184:187], v[192:195], v[40:43]
	v_mfma_f32_16x16x32_bf16 v[28:31], v[172:175], v[200:203], v[28:31]
	v_mfma_f32_16x16x32_bf16 v[24:27], v[184:187], v[200:203], v[24:27]
	v_mfma_f32_16x16x32_bf16 v[12:15], v[172:175], v[208:211], v[12:15]
	v_mfma_f32_16x16x32_bf16 v[8:11], v[184:187], v[208:211], v[8:11]
	v_mfma_f32_16x16x32_bf16 v[4:7], v[172:175], v[216:219], v[4:7]
	v_mfma_f32_16x16x32_bf16 v[0:3], v[184:187], v[216:219], v[0:3]
	s_barrier
	s_branch .Lgemm_join_697
.LBB0_697:
	s_add_u32 s77, s44, s50
	s_addc_u32 s78, s45, s51
	s_add_u32 s79, s77, 0x100
	s_addc_u32 s80, s78, 0
	s_and_b64 s[42:43], s[48:49], exec
	s_cselect_b32 s95, s4, s80
	s_cselect_b32 s94, s5, s79
	s_add_u32 s42, s40, s50
	s_addc_u32 s43, s41, s51
	s_add_u32 s50, s42, 0x100
	s_addc_u32 s51, s43, 0
	s_add_i32 s93, 0, 0x10000
	s_and_b64 s[42:43], s[48:49], exec
	s_cselect_b32 s51, s31, s51
	s_cselect_b32 s50, s76, s50
	s_add_i32 s42, 0, 0x14000
	v_add_u32_e32 v141, s93, v135
	s_add_u32 vcc_lo, s77, s0
	ds_read_b128 v[152:155], v141
	ds_read_b128 v[156:159], v141 offset:1024
	ds_read_b128 v[160:163], v141 offset:2048
	ds_read_b128 v[164:167], v141 offset:3072
	v_add_u32_e32 v141, s42, v135
	s_addc_u32 vcc_hi, s78, s1
	s_add_i32 s87, s93, s3
	ds_read_b128 v[168:171], v141
	ds_read_b128 v[172:175], v141 offset:1024
	ds_read_b128 v[180:183], v141 offset:2048
	ds_read_b128 v[184:187], v141 offset:3072
	s_add_i32 m0, s16, 0xc000
	s_add_i32 s27, s16, 0xe000
	s_add_i32 s80, s87, 0x2000
	s_add_u32 s96, s50, s10
	s_addc_u32 s97, s51, s11
	s_add_i32 s86, s42, s3
	s_add_i32 s81, s86, 0x2000
	s_add_i32 s79, 0, 0x18000
	s_add_i32 s78, 0, 0x1c000
	s_add_u32 s48, s94, s0
	s_addc_u32 s49, s95, s1
	s_add_i32 s77, s79, s3
	s_add_i32 s93, s78, s3
	s_add_i32 s43, s77, 0x2000
	s_add_i32 s42, s93, 0x2000
	v_lshl_add_u64 v[220:221], vcc, 0, v[132:133]
	v_lshl_add_u64 v[220:221], v[220:221], 0, s[24:25]
	ds_read_b128 v[188:191], v139
	ds_read_b128 v[192:195], v139 offset:1024
	ds_read_b128 v[196:199], v139 offset:2048
	ds_read_b128 v[200:203], v139 offset:3072
	ds_read_b128 v[204:207], v139 offset:4096
	ds_read_b128 v[208:211], v139 offset:5120
	ds_read_b128 v[212:215], v139 offset:6144
	ds_read_b128 v[216:219], v139 offset:7168
	global_load_lds_dwordx4 v[220:221], off
	v_lshl_add_u64 v[220:221], vcc, 0, v[130:131]
	v_lshl_add_u64 v[220:221], v[220:221], 0, s[24:25]
	s_mov_b32 m0, s27
	s_nop 0
	global_load_lds_dwordx4 v[220:221], off
	s_waitcnt vmcnt(8)
	s_waitcnt lgkmcnt(0)
	s_barrier
	s_waitcnt lgkmcnt(0)
	v_mfma_f32_16x16x32_bf16 v[124:127], v[152:155], v[188:191], v[124:127]
	v_mfma_f32_16x16x32_bf16 v[120:123], v[160:163], v[188:191], v[120:123]
	v_mfma_f32_16x16x32_bf16 v[116:119], v[152:155], v[196:199], v[116:119]
	v_mfma_f32_16x16x32_bf16 v[112:115], v[160:163], v[196:199], v[112:115]
	v_mfma_f32_16x16x32_bf16 v[100:103], v[152:155], v[204:207], v[100:103]
	v_mfma_f32_16x16x32_bf16 v[96:99], v[160:163], v[204:207], v[96:99]
	v_mfma_f32_16x16x32_bf16 v[84:87], v[152:155], v[212:215], v[84:87]
	v_mfma_f32_16x16x32_bf16 v[80:83], v[160:163], v[212:215], v[80:83]
	v_mfma_f32_16x16x32_bf16 v[124:127], v[156:159], v[192:195], v[124:127]
	v_mfma_f32_16x16x32_bf16 v[120:123], v[164:167], v[192:195], v[120:123]
	v_mfma_f32_16x16x32_bf16 v[116:119], v[156:159], v[200:203], v[116:119]
	v_mfma_f32_16x16x32_bf16 v[112:115], v[164:167], v[200:203], v[112:115]
	v_mfma_f32_16x16x32_bf16 v[100:103], v[156:159], v[208:211], v[100:103]
	v_mfma_f32_16x16x32_bf16 v[96:99], v[164:167], v[208:211], v[96:99]
	v_mfma_f32_16x16x32_bf16 v[84:87], v[156:159], v[216:219], v[84:87]
	v_mfma_f32_16x16x32_bf16 v[80:83], v[164:167], v[216:219], v[80:83]
	v_mfma_f32_16x16x32_bf16 v[108:111], v[168:171], v[188:191], v[108:111]
	v_mfma_f32_16x16x32_bf16 v[104:107], v[180:183], v[188:191], v[104:107]
	v_mfma_f32_16x16x32_bf16 v[92:95], v[168:171], v[196:199], v[92:95]
	v_mfma_f32_16x16x32_bf16 v[88:91], v[180:183], v[196:199], v[88:91]
	v_mfma_f32_16x16x32_bf16 v[76:79], v[168:171], v[204:207], v[76:79]
	v_mfma_f32_16x16x32_bf16 v[72:75], v[180:183], v[204:207], v[72:75]
	v_mfma_f32_16x16x32_bf16 v[68:71], v[168:171], v[212:215], v[68:71]
	v_mfma_f32_16x16x32_bf16 v[64:67], v[180:183], v[212:215], v[64:67]
	v_mfma_f32_16x16x32_bf16 v[108:111], v[172:175], v[192:195], v[108:111]
	v_mfma_f32_16x16x32_bf16 v[104:107], v[184:187], v[192:195], v[104:107]
	v_mfma_f32_16x16x32_bf16 v[92:95], v[172:175], v[200:203], v[92:95]
	v_mfma_f32_16x16x32_bf16 v[88:91], v[184:187], v[200:203], v[88:91]
	v_mfma_f32_16x16x32_bf16 v[76:79], v[172:175], v[208:211], v[76:79]
	v_mfma_f32_16x16x32_bf16 v[72:75], v[184:187], v[208:211], v[72:75]
	v_mfma_f32_16x16x32_bf16 v[68:71], v[172:175], v[216:219], v[68:71]
	v_mfma_f32_16x16x32_bf16 v[64:67], v[184:187], v[216:219], v[64:67]
	s_barrier
; #define PG8_STAGE(bufoff, gbase, voff) do { _Pragma("unroll") for (int _i = 0; _i < 2; ++_i) \
;         __builtin_amdgcn_global_load_lds((const unsigned*)((const char*)(gbase) + (voff)[_i]), (LAS unsigned*)(lds + (bufoff) + ldsw + _i * 8192), 16, 0, 0); } while (0)
; #define PG8_LDA(dst, b, h) do { _Pragma("unroll") for (int m = 0; m < 4; ++m) _Pragma("unroll") for (int k = 0; k < 2; ++k) dst[m][k] = *(const LAS bf16x8*)(lds + PG8_SA(b, h) + aoff + m * 2048 + k * 1024); } while (0)
; #define PG8_LDB(dst, b, h) do { _Pragma("unroll") for (int n = 0; n < 2; ++n) _Pragma("unroll") for (int k = 0; k < 2; ++k) dst[n][k] = *(const LAS bf16x8*)(lds + PG8_SB(b, h) + boff + n * 2048 + k * 1024); } while (0)
; #define PG8_MMA(ai, bj, At, Bt) do { __builtin_amdgcn_s_setprio(1); _Pragma("unroll") for (int m = 0; m < 4; ++m) _Pragma("unroll") for (int n = 0; n < 2; ++n) _Pragma("unroll") for (int k = 0; k < 2; ++k) \
;         acc[ai][bj][m][n] = __builtin_amdgcn_mfma_f32_16x16x32_bf16(Bt[n][k], At[m][k], acc[ai][bj][m][n], 0, 0, 0); __builtin_amdgcn_s_setprio(0); } while (0)
; #define PG8_WAIT_V(n) asm volatile("s_waitcnt vmcnt(" #n ")" ::: "memory")
; #define PG8_WAIT_L(n) asm volatile("s_waitcnt lgkmcnt(" #n ")" ::: "memory")
; #define PG8_BAR __builtin_amdgcn_s_barrier()
; #define PG8_SCHED __builtin_amdgcn_sched_barrier(0)
; template <class Epi, class Sched, bool ALIGN_EPI>
; __device__ __forceinline__ void gemm_phase(LAS unsigned char* lds, const int wid, const int lda_, const int ldb_, const int K_, const Sched& S, const Epi& E) {
;     ...
;             PG8_LDA(At, 0, 1); PG8_STAGE(PG8_SB(0, 0), b2, voffB); PG8_STAGE(PG8_SB(0, 1), b2 + hstepB, voffB); PG8_STAGE(PG8_SA(0, 0), a2, voffA);
;             PG8_WAIT_V(8); PG8_WAIT_L(0); PG8_BAR; PG8_MMA(1, 0, At, B0); PG8_MMA(1, 1, At, B1); PG8_BAR; PG8_SCHED;
;             PG8_LDB(B0, 1, 0); PG8_LDB(B1, 1, 1); PG8_SCHED; PG8_LDA(At, 1, 0); PG8_STAGE(PG8_SA(0, 1), a2 + hstepA, voffA);
	s_mov_b32 m0, s87
	v_lshl_add_u64 v[220:221], s[50:51], 0, v[176:177]
	ds_read_b128 v[188:191], v139 offset:16384
	ds_read_b128 v[192:195], v139 offset:17408
	ds_read_b128 v[196:199], v139 offset:18432
	ds_read_b128 v[200:203], v139 offset:19456
	ds_read_b128 v[204:207], v139 offset:20480
	ds_read_b128 v[208:211], v139 offset:21504
	ds_read_b128 v[212:215], v139 offset:22528
	ds_read_b128 v[216:219], v139 offset:23552
	global_load_lds_dwordx4 v[220:221], off
	v_lshl_add_u64 v[222:223], s[50:51], 0, v[128:129]
	s_mov_b32 m0, s80
	v_lshl_add_u64 v[224:225], s[96:97], 0, v[176:177]
	global_load_lds_dwordx4 v[222:223], off
	s_mov_b32 m0, s86
	v_lshl_add_u64 v[226:227], s[96:97], 0, v[128:129]
	global_load_lds_dwordx4 v[224:225], off
	s_mov_b32 m0, s81
	v_lshl_add_u64 v[228:229], s[94:95], 0, v[132:133]
	global_load_lds_dwordx4 v[226:227], off
	s_mov_b32 m0, s16
	v_lshl_add_u64 v[230:231], s[94:95], 0, v[130:131]
	global_load_lds_dwordx4 v[228:229], off
	s_mov_b32 m0, s6
	s_nop 0
	global_load_lds_dwordx4 v[230:231], off
	s_waitcnt vmcnt(8)
	s_waitcnt lgkmcnt(0)
	s_barrier
	s_waitcnt lgkmcnt(0)
	v_mfma_f32_16x16x32_bf16 v[60:63], v[152:155], v[188:191], v[60:63]
	v_mfma_f32_16x16x32_bf16 v[56:59], v[160:163], v[188:191], v[56:59]
	v_mfma_f32_16x16x32_bf16 v[52:55], v[152:155], v[196:199], v[52:55]
	v_mfma_f32_16x16x32_bf16 v[48:51], v[160:163], v[196:199], v[48:51]
	v_mfma_f32_16x16x32_bf16 v[36:39], v[152:155], v[204:207], v[36:39]
	v_mfma_f32_16x16x32_bf16 v[32:35], v[160:163], v[204:207], v[32:35]
	v_mfma_f32_16x16x32_bf16 v[20:23], v[152:155], v[212:215], v[20:23]
	v_mfma_f32_16x16x32_bf16 v[16:19], v[160:163], v[212:215], v[16:19]
	v_mfma_f32_16x16x32_bf16 v[60:63], v[156:159], v[192:195], v[60:63]
	v_mfma_f32_16x16x32_bf16 v[56:59], v[164:167], v[192:195], v[56:59]
	v_mfma_f32_16x16x32_bf16 v[52:55], v[156:159], v[200:203], v[52:55]
	v_mfma_f32_16x16x32_bf16 v[48:51], v[164:167], v[200:203], v[48:51]
	v_mfma_f32_16x16x32_bf16 v[36:39], v[156:159], v[208:211], v[36:39]
	v_mfma_f32_16x16x32_bf16 v[32:35], v[164:167], v[208:211], v[32:35]
	v_mfma_f32_16x16x32_bf16 v[20:23], v[156:159], v[216:219], v[20:23]
	v_mfma_f32_16x16x32_bf16 v[16:19], v[164:167], v[216:219], v[16:19]
	v_mfma_f32_16x16x32_bf16 v[44:47], v[168:171], v[188:191], v[44:47]
	v_mfma_f32_16x16x32_bf16 v[40:43], v[180:183], v[188:191], v[40:43]
	v_mfma_f32_16x16x32_bf16 v[28:31], v[168:171], v[196:199], v[28:31]
	v_mfma_f32_16x16x32_bf16 v[24:27], v[180:183], v[196:199], v[24:27]
	v_mfma_f32_16x16x32_bf16 v[12:15], v[168:171], v[204:207], v[12:15]
	v_mfma_f32_16x16x32_bf16 v[8:11], v[180:183], v[204:207], v[8:11]
	v_mfma_f32_16x16x32_bf16 v[4:7], v[168:171], v[212:215], v[4:7]
	v_mfma_f32_16x16x32_bf16 v[0:3], v[180:183], v[212:215], v[0:3]
	v_mfma_f32_16x16x32_bf16 v[44:47], v[172:175], v[192:195], v[44:47]
	v_mfma_f32_16x16x32_bf16 v[40:43], v[184:187], v[192:195], v[40:43]
	v_mfma_f32_16x16x32_bf16 v[28:31], v[172:175], v[200:203], v[28:31]
	v_mfma_f32_16x16x32_bf16 v[24:27], v[184:187], v[200:203], v[24:27]
	v_mfma_f32_16x16x32_bf16 v[12:15], v[172:175], v[208:211], v[12:15]
	v_mfma_f32_16x16x32_bf16 v[8:11], v[184:187], v[208:211], v[8:11]
	v_mfma_f32_16x16x32_bf16 v[4:7], v[172:175], v[216:219], v[4:7]
	v_mfma_f32_16x16x32_bf16 v[0:3], v[184:187], v[216:219], v[0:3]
	s_barrier
.Lgemm_join_697:
	v_add_u32_e32 v141, s79, v135
	ds_read_b128 v[152:155], v141
	ds_read_b128 v[156:159], v141 offset:1024
	ds_read_b128 v[160:163], v141 offset:2048
	ds_read_b128 v[164:167], v141 offset:3072
	v_add_u32_e32 v141, s78, v135
	ds_read_b128 v[168:171], v141
	ds_read_b128 v[172:175], v141 offset:1024
	ds_read_b128 v[180:183], v141 offset:2048
	ds_read_b128 v[184:187], v141 offset:3072
	s_mov_b32 m0, s7
	v_lshl_add_u64 v[232:233], s[48:49], 0, v[132:133]
	ds_read_b128 v[188:191], v139 offset:32768
	ds_read_b128 v[192:195], v139 offset:33792
	ds_read_b128 v[196:199], v139 offset:34816
	ds_read_b128 v[200:203], v139 offset:35840
	ds_read_b128 v[204:207], v139 offset:36864
	ds_read_b128 v[208:211], v139 offset:37888
	ds_read_b128 v[212:215], v139 offset:38912
	ds_read_b128 v[216:219], v139 offset:39936
	global_load_lds_dwordx4 v[232:233], off
	v_lshl_add_u64 v[232:233], s[48:49], 0, v[130:131]
	s_mov_b32 m0, s14
	s_nop 0
	global_load_lds_dwordx4 v[232:233], off
	s_waitcnt vmcnt(8)
	s_waitcnt lgkmcnt(0)
	s_barrier
; #define PG8_STAGE(bufoff, gbase, voff) do { _Pragma("unroll") for (int _i = 0; _i < 2; ++_i) \
;         __builtin_amdgcn_global_load_lds((const unsigned*)((const char*)(gbase) + (voff)[_i]), (LAS unsigned*)(lds + (bufoff) + ldsw + _i * 8192), 16, 0, 0); } while (0)
; #define PG8_LDA(dst, b, h) do { _Pragma("unroll") for (int m = 0; m < 4; ++m) _Pragma("unroll") for (int k = 0; k < 2; ++k) dst[m][k] = *(const LAS bf16x8*)(lds + PG8_SA(b, h) + aoff + m * 2048 + k * 1024); } while (0)
; #define PG8_MMA(ai, bj, At, Bt) do { __builtin_amdgcn_s_setprio(1); _Pragma("unroll") for (int m = 0; m < 4; ++m) _Pragma("unroll") for (int n = 0; n < 2; ++n) _Pragma("unroll") for (int k = 0; k < 2; ++k) \
;         acc[ai][bj][m][n] = __builtin_amdgcn_mfma_f32_16x16x32_bf16(Bt[n][k], At[m][k], acc[ai][bj][m][n], 0, 0, 0); __builtin_amdgcn_s_setprio(0); } while (0)
; #define PG8_WAIT_V(n) asm volatile("s_waitcnt vmcnt(" #n ")" ::: "memory")
; #define PG8_WAIT_L(n) asm volatile("s_waitcnt lgkmcnt(" #n ")" ::: "memory")
; #define PG8_BAR __builtin_amdgcn_s_barrier()
; #define PG8_SCHED __builtin_amdgcn_sched_barrier(0)
; template <class Epi, class Sched, bool ALIGN_EPI>
; __device__ __forceinline__ void gemm_phase(LAS unsigned char* lds, const int wid, const int lda_, const int ldb_, const int K_, const Sched& S, const Epi& E) {
;     ...
;             PG8_WAIT_V(8); PG8_WAIT_L(0); PG8_BAR; PG8_MMA(0, 0, At, B0); PG8_MMA(0, 1, At, B1); PG8_BAR; PG8_SCHED;
;             PG8_LDA(At, 1, 1); PG8_STAGE(PG8_SB(1, 0), b3, voffB); PG8_STAGE(PG8_SB(1, 1), b3 + hstepB, voffB); PG8_STAGE(PG8_SA(1, 0), a3, voffA);
;             PG8_WAIT_V(8); PG8_WAIT_L(0); PG8_BAR; PG8_MMA(1, 0, At, B0); PG8_MMA(1, 1, At, B1); PG8_BAR; PG8_SCHED;
;         }
;         if constexpr (ALIGN_EPI) { if (wr == 0) PG8_BAR; }
;         E(acc, cur, S, wr, wc, fr, fq);
;     __device__ __forceinline__ void out(const pg8::Unit& u, char*& o, int& ldo, int& kind) const { const int g = u.pm >> 1, cs = u.pm & 1;
;         if (u.pn < 64) { const int b = u.pn >> 3, p0 = (u.pn & 7) * 256; o = (char*)ws + WS_PQT + (((size_t)(b * 2048 + g * 256)) * 4096 + (size_t)cs * 2048 + p0) * 2; ldo = 4096; }
;         else { const int b = u.pn - 64; o = (char*)ws + WS_PQTC + (((size_t)(b * 2048 + g * 256)) * 512 + (size_t)cs * 256) * 2; ldo = 512; }
;         kind = 0; }
	s_waitcnt lgkmcnt(0)
	v_mfma_f32_16x16x32_bf16 v[124:127], v[152:155], v[188:191], v[124:127]
	v_mfma_f32_16x16x32_bf16 v[120:123], v[160:163], v[188:191], v[120:123]
	v_mfma_f32_16x16x32_bf16 v[116:119], v[152:155], v[196:199], v[116:119]
	v_mfma_f32_16x16x32_bf16 v[112:115], v[160:163], v[196:199], v[112:115]
	v_mfma_f32_16x16x32_bf16 v[100:103], v[152:155], v[204:207], v[100:103]
	v_mfma_f32_16x16x32_bf16 v[96:99], v[160:163], v[204:207], v[96:99]
	v_mfma_f32_16x16x32_bf16 v[84:87], v[152:155], v[212:215], v[84:87]
	v_mfma_f32_16x16x32_bf16 v[80:83], v[160:163], v[212:215], v[80:83]
	v_mfma_f32_16x16x32_bf16 v[124:127], v[156:159], v[192:195], v[124:127]
	v_mfma_f32_16x16x32_bf16 v[120:123], v[164:167], v[192:195], v[120:123]
	v_mfma_f32_16x16x32_bf16 v[116:119], v[156:159], v[200:203], v[116:119]
	v_mfma_f32_16x16x32_bf16 v[112:115], v[164:167], v[200:203], v[112:115]
	v_mfma_f32_16x16x32_bf16 v[100:103], v[156:159], v[208:211], v[100:103]
	v_mfma_f32_16x16x32_bf16 v[96:99], v[164:167], v[208:211], v[96:99]
	v_mfma_f32_16x16x32_bf16 v[84:87], v[156:159], v[216:219], v[84:87]
	v_mfma_f32_16x16x32_bf16 v[80:83], v[164:167], v[216:219], v[80:83]
	v_mfma_f32_16x16x32_bf16 v[108:111], v[168:171], v[188:191], v[108:111]
	v_mfma_f32_16x16x32_bf16 v[104:107], v[180:183], v[188:191], v[104:107]
	v_mfma_f32_16x16x32_bf16 v[92:95], v[168:171], v[196:199], v[92:95]
	v_mfma_f32_16x16x32_bf16 v[88:91], v[180:183], v[196:199], v[88:91]
	v_mfma_f32_16x16x32_bf16 v[76:79], v[168:171], v[204:207], v[76:79]
	v_mfma_f32_16x16x32_bf16 v[72:75], v[180:183], v[204:207], v[72:75]
	v_mfma_f32_16x16x32_bf16 v[68:71], v[168:171], v[212:215], v[68:71]
	v_mfma_f32_16x16x32_bf16 v[64:67], v[180:183], v[212:215], v[64:67]
	v_mfma_f32_16x16x32_bf16 v[108:111], v[172:175], v[192:195], v[108:111]
	v_mfma_f32_16x16x32_bf16 v[104:107], v[184:187], v[192:195], v[104:107]
	v_mfma_f32_16x16x32_bf16 v[92:95], v[172:175], v[200:203], v[92:95]
	v_mfma_f32_16x16x32_bf16 v[88:91], v[184:187], v[200:203], v[88:91]
	v_mfma_f32_16x16x32_bf16 v[76:79], v[172:175], v[208:211], v[76:79]
	v_mfma_f32_16x16x32_bf16 v[72:75], v[184:187], v[208:211], v[72:75]
	v_mfma_f32_16x16x32_bf16 v[68:71], v[172:175], v[216:219], v[68:71]
	v_mfma_f32_16x16x32_bf16 v[64:67], v[184:187], v[216:219], v[64:67]
	s_barrier
	s_mov_b32 m0, s77
	v_lshl_add_u64 v[220:221], v[220:221], 0, s[24:25]
	ds_read_b128 v[188:191], v139 offset:49152
	ds_read_b128 v[192:195], v139 offset:50176
	ds_read_b128 v[196:199], v139 offset:51200
	ds_read_b128 v[200:203], v139 offset:52224
	ds_read_b128 v[204:207], v139 offset:53248
	ds_read_b128 v[208:211], v139 offset:54272
	ds_read_b128 v[212:215], v139 offset:55296
	ds_read_b128 v[216:219], v139 offset:56320
	global_load_lds_dwordx4 v[220:221], off
	v_lshl_add_u64 v[220:221], v[222:223], 0, s[24:25]
	s_mov_b32 m0, s43
	s_nop 0
	global_load_lds_dwordx4 v[220:221], off
	v_lshl_add_u64 v[220:221], v[224:225], 0, s[24:25]
	s_mov_b32 m0, s93
	s_nop 0
	global_load_lds_dwordx4 v[220:221], off
	v_lshl_add_u64 v[220:221], v[226:227], 0, s[24:25]
	s_mov_b32 m0, s42
	s_nop 0
	global_load_lds_dwordx4 v[220:221], off
	v_lshl_add_u64 v[220:221], v[228:229], 0, s[24:25]
	s_mov_b32 m0, s15
	s_nop 0
	global_load_lds_dwordx4 v[220:221], off
	v_lshl_add_u64 v[220:221], v[230:231], 0, s[24:25]
	s_mov_b32 m0, s26
	s_nop 0
	global_load_lds_dwordx4 v[220:221], off
	s_waitcnt vmcnt(8)
	s_waitcnt lgkmcnt(0)
	s_barrier
	s_waitcnt lgkmcnt(0)
	v_mfma_f32_16x16x32_bf16 v[60:63], v[152:155], v[188:191], v[60:63]
	v_mfma_f32_16x16x32_bf16 v[56:59], v[160:163], v[188:191], v[56:59]
	v_mfma_f32_16x16x32_bf16 v[52:55], v[152:155], v[196:199], v[52:55]
	v_mfma_f32_16x16x32_bf16 v[48:51], v[160:163], v[196:199], v[48:51]
	v_mfma_f32_16x16x32_bf16 v[36:39], v[152:155], v[204:207], v[36:39]
	v_mfma_f32_16x16x32_bf16 v[32:35], v[160:163], v[204:207], v[32:35]
	v_mfma_f32_16x16x32_bf16 v[20:23], v[152:155], v[212:215], v[20:23]
	v_mfma_f32_16x16x32_bf16 v[16:19], v[160:163], v[212:215], v[16:19]
	v_mfma_f32_16x16x32_bf16 v[60:63], v[156:159], v[192:195], v[60:63]
	v_mfma_f32_16x16x32_bf16 v[56:59], v[164:167], v[192:195], v[56:59]
	v_mfma_f32_16x16x32_bf16 v[52:55], v[156:159], v[200:203], v[52:55]
	v_mfma_f32_16x16x32_bf16 v[48:51], v[164:167], v[200:203], v[48:51]
	v_mfma_f32_16x16x32_bf16 v[36:39], v[156:159], v[208:211], v[36:39]
	v_mfma_f32_16x16x32_bf16 v[32:35], v[164:167], v[208:211], v[32:35]
	v_mfma_f32_16x16x32_bf16 v[20:23], v[156:159], v[216:219], v[20:23]
	v_mfma_f32_16x16x32_bf16 v[16:19], v[164:167], v[216:219], v[16:19]
	v_mfma_f32_16x16x32_bf16 v[44:47], v[168:171], v[188:191], v[44:47]
	v_mfma_f32_16x16x32_bf16 v[40:43], v[180:183], v[188:191], v[40:43]
	v_mfma_f32_16x16x32_bf16 v[28:31], v[168:171], v[196:199], v[28:31]
	v_mfma_f32_16x16x32_bf16 v[24:27], v[180:183], v[196:199], v[24:27]
	v_mfma_f32_16x16x32_bf16 v[12:15], v[168:171], v[204:207], v[12:15]
	v_mfma_f32_16x16x32_bf16 v[8:11], v[180:183], v[204:207], v[8:11]
	v_mfma_f32_16x16x32_bf16 v[4:7], v[168:171], v[212:215], v[4:7]
	v_mfma_f32_16x16x32_bf16 v[0:3], v[180:183], v[212:215], v[0:3]
	v_mfma_f32_16x16x32_bf16 v[44:47], v[172:175], v[192:195], v[44:47]
	v_mfma_f32_16x16x32_bf16 v[40:43], v[184:187], v[192:195], v[40:43]
	v_mfma_f32_16x16x32_bf16 v[28:31], v[172:175], v[200:203], v[28:31]
	v_mfma_f32_16x16x32_bf16 v[24:27], v[184:187], v[200:203], v[24:27]
	v_mfma_f32_16x16x32_bf16 v[12:15], v[172:175], v[208:211], v[12:15]
	v_mfma_f32_16x16x32_bf16 v[8:11], v[184:187], v[208:211], v[8:11]
	v_mfma_f32_16x16x32_bf16 v[4:7], v[172:175], v[216:219], v[4:7]
	v_mfma_f32_16x16x32_bf16 v[0:3], v[184:187], v[216:219], v[0:3]
	s_barrier
	s_andn2_b64 vcc, exec, s[46:47]
	s_mov_b64 s[48:49], -1
	s_mov_b64 s[46:47], 0
	s_mov_b64 s[50:51], 0x100
	s_cbranch_vccz .LBB0_697
	s_setprio 2
	s_ashr_i32 s43, s75, 1
	s_and_b32 s42, s75, 1
	s_cmp_gt_i32 s74, 63
	s_mov_b64 s[40:41], -1
	s_cbranch_scc0 .LBB0_700
	s_lshl_b32 s4, s74, 11
	s_lshl_b32 s5, s43, 8
	s_add_i32 s4, s4, s5
	s_add_i32 s4, s4, 0xfffe0000
	s_ashr_i32 s5, s4, 31
	s_lshl_b32 s31, s42, 9
	s_lshl_b64 s[4:5], s[4:5], 10
	v_readlane_b32 s17, v254, 2
	s_add_u32 s4, s17, s4
	v_readlane_b32 s17, v254, 3
	s_addc_u32 s5, s17, s5
	s_add_u32 s4, s4, s31
	s_addc_u32 s5, s5, 0
	s_mov_b64 s[40:41], 0

; #define PG8_STAGE(bufoff, gbase, voff) do { _Pragma("unroll") for (int _i = 0; _i < 2; ++_i) \
;         __builtin_amdgcn_global_load_lds((const unsigned*)((const char*)(gbase) + (voff)[_i]), (LAS unsigned*)(lds + (bufoff) + ldsw + _i * 8192), 16, 0, 0); } while (0)
; #define PG8_LDA(dst, b, h) do { _Pragma("unroll") for (int m = 0; m < 4; ++m) _Pragma("unroll") for (int k = 0; k < 2; ++k) dst[m][k] = *(const LAS bf16x8*)(lds + PG8_SA(b, h) + aoff + m * 2048 + k * 1024); } while (0)
; #define PG8_LDB(dst, b, h) do { _Pragma("unroll") for (int n = 0; n < 2; ++n) _Pragma("unroll") for (int k = 0; k < 2; ++k) dst[n][k] = *(const LAS bf16x8*)(lds + PG8_SB(b, h) + boff + n * 2048 + k * 1024); } while (0)
; #define PG8_MMA(ai, bj, At, Bt) do { __builtin_amdgcn_s_setprio(1); _Pragma("unroll") for (int m = 0; m < 4; ++m) _Pragma("unroll") for (int n = 0; n < 2; ++n) _Pragma("unroll") for (int k = 0; k < 2; ++k) \
;         acc[ai][bj][m][n] = __builtin_amdgcn_mfma_f32_16x16x32_bf16(Bt[n][k], At[m][k], acc[ai][bj][m][n], 0, 0, 0); __builtin_amdgcn_s_setprio(0); } while (0)
; template <class Epi, class Sched, bool ALIGN_EPI>
; __device__ __forceinline__ void gemm_phase(LAS unsigned char* lds, const int wid, const int lda_, const int ldb_, const int K_, const Sched& S, const Epi& E) {
;     ...
;         const bool has_next = S.next(ui + 1, nxt);
;         const int nt = S.nt(cur);
;         const char* nA = has_next ? S.a(nxt) : cA; const char* nB = has_next ? S.b(nxt) : cB;
; #pragma unroll 1
;         for (int t = 0; t < nt; t += 2) {
;             const bool last = (t == nt - 2);
;             const char* a1 = cA + (size_t)(t + 1) * kstep;
;             const char* a2 = last ? nA : cA + (size_t)(t + 2) * kstep; const char* b2 = last ? nB : cB + (size_t)(t + 2) * kstep;
;             const char* a3 = a2 + kstep; const char* b3 = b2 + kstep;
;             PG8_LDB(B0, 0, 0); PG8_LDB(B1, 0, 1); PG8_SCHED; PG8_LDA(At, 0, 0); PG8_STAGE(PG8_SA(1, 1), a1 + hstepA, voffA);
;             PG8_WAIT_V(8); PG8_WAIT_L(0); PG8_BAR; PG8_MMA(0, 0, At, B0); PG8_MMA(0, 1, At, B1); PG8_BAR; PG8_SCHED;
;             PG8_LDA(At, 0, 1); PG8_STAGE(PG8_SB(0, 0), b2, voffB); PG8_STAGE(PG8_SB(0, 1), b2 + hstepB, voffB); PG8_STAGE(PG8_SA(0, 0), a2, voffA);
;     __device__ __forceinline__ const char* a(const pg8::Unit& u) const { return (const char*)ws + (u.pm < 64 ? WS_W2 : WS_W2C); }
.LBB0_882:
	s_and_b64 s[4:5], s[4:5], exec
	s_cselect_b32 s4, s27, 0x380000
	s_add_u32 s44, s66, s4
	s_addc_u32 s45, s67, 0
	s_and_b64 s[4:5], s[50:51], exec
	s_cselect_b32 s4, s45, s47
	s_cselect_b32 s5, s44, s46
	s_add_u32 s42, s46, 0x80
	s_addc_u32 s43, s47, 0
	s_add_u32 s31, s48, 0x100
	v_lshl_add_u64 v[156:157], s[42:43], 0, v[152:153]
	v_lshl_add_u64 v[158:159], s[42:43], 0, v[154:155]
	s_addc_u32 s35, s49, 0
	s_mov_b32 s73, -2
	s_mov_b64 s[48:49], 0
	s_add_u32 s17, s46, s48
	s_addc_u32 s27, s47, s49
	s_add_u32 s17, s17, 0x100
	s_addc_u32 s27, s27, 0
	s_add_u32 s42, s31, s48
	s_addc_u32 s43, s35, s49
	s_add_i32 s74, 0, 0x10000
	s_cmpk_eq_i32 s48, 0x300
	s_cselect_b32 s51, s4, s27
	s_cselect_b32 s50, s5, s17
	v_add_u32_e32 v141, s74, v135
	s_cselect_b32 s43, s39, s43
	s_cselect_b32 s42, s38, s42
	s_add_i32 s17, 0, 0x14000
	ds_read_b128 v[160:163], v141
	ds_read_b128 v[164:167], v141 offset:1024
	ds_read_b128 v[168:171], v141 offset:2048
	ds_read_b128 v[172:175], v141 offset:3072
	v_add_u32_e32 v141, s17, v135
	ds_read_b128 v[180:183], v141
	ds_read_b128 v[184:187], v141 offset:1024
	ds_read_b128 v[188:191], v141 offset:2048
	ds_read_b128 v[192:195], v141 offset:3072
	v_lshl_add_u64 v[228:229], v[158:159], 0, s[48:49]
	s_add_i32 m0, s16, 0xc000
	ds_read_b128 v[196:199], v139
	ds_read_b128 v[200:203], v139 offset:1024
	ds_read_b128 v[204:207], v139 offset:2048
	ds_read_b128 v[208:211], v139 offset:3072
	ds_read_b128 v[212:215], v139 offset:4096
	ds_read_b128 v[216:219], v139 offset:5120
	ds_read_b128 v[220:223], v139 offset:6144
	ds_read_b128 v[224:227], v139 offset:7168
	global_load_lds_dwordx4 v[228:229], off
	v_lshl_add_u64 v[228:229], v[156:157], 0, s[48:49]
	s_add_i32 m0, s16, 0xe000
	s_nop 0
	global_load_lds_dwordx4 v[228:229], off
	s_waitcnt vmcnt(8)
	s_waitcnt lgkmcnt(0)
	s_barrier
	s_setprio 0
	s_waitcnt lgkmcnt(0)
	v_mfma_f32_16x16x32_bf16 v[124:127], v[160:163], v[196:199], 0
	v_mfma_f32_16x16x32_bf16 v[120:123], v[168:171], v[196:199], 0
	v_mfma_f32_16x16x32_bf16 v[116:119], v[160:163], v[204:207], 0
	v_mfma_f32_16x16x32_bf16 v[112:115], v[168:171], v[204:207], 0
	v_mfma_f32_16x16x32_bf16 v[100:103], v[160:163], v[212:215], 0
	v_mfma_f32_16x16x32_bf16 v[96:99], v[168:171], v[212:215], 0
	v_mfma_f32_16x16x32_bf16 v[84:87], v[160:163], v[220:223], 0
	v_mfma_f32_16x16x32_bf16 v[80:83], v[168:171], v[220:223], 0
	v_mfma_f32_16x16x32_bf16 v[124:127], v[164:167], v[200:203], v[124:127]
	v_mfma_f32_16x16x32_bf16 v[120:123], v[172:175], v[200:203], v[120:123]
	v_mfma_f32_16x16x32_bf16 v[116:119], v[164:167], v[208:211], v[116:119]
	v_mfma_f32_16x16x32_bf16 v[112:115], v[172:175], v[208:211], v[112:115]
	v_mfma_f32_16x16x32_bf16 v[100:103], v[164:167], v[216:219], v[100:103]
	v_mfma_f32_16x16x32_bf16 v[96:99], v[172:175], v[216:219], v[96:99]
	v_mfma_f32_16x16x32_bf16 v[84:87], v[164:167], v[224:227], v[84:87]
	v_mfma_f32_16x16x32_bf16 v[80:83], v[172:175], v[224:227], v[80:83]
	v_mfma_f32_16x16x32_bf16 v[108:111], v[180:183], v[196:199], 0
	v_mfma_f32_16x16x32_bf16 v[104:107], v[188:191], v[196:199], 0
	v_mfma_f32_16x16x32_bf16 v[92:95], v[180:183], v[204:207], 0
	v_mfma_f32_16x16x32_bf16 v[88:91], v[188:191], v[204:207], 0
	v_mfma_f32_16x16x32_bf16 v[76:79], v[180:183], v[212:215], 0
	v_mfma_f32_16x16x32_bf16 v[72:75], v[188:191], v[212:215], 0
	v_mfma_f32_16x16x32_bf16 v[68:71], v[180:183], v[220:223], 0
	v_mfma_f32_16x16x32_bf16 v[64:67], v[188:191], v[220:223], 0
	v_mfma_f32_16x16x32_bf16 v[108:111], v[184:187], v[200:203], v[108:111]
	v_mfma_f32_16x16x32_bf16 v[104:107], v[192:195], v[200:203], v[104:107]
	v_mfma_f32_16x16x32_bf16 v[92:95], v[184:187], v[208:211], v[92:95]
	v_mfma_f32_16x16x32_bf16 v[88:91], v[192:195], v[208:211], v[88:91]
	v_mfma_f32_16x16x32_bf16 v[76:79], v[184:187], v[216:219], v[76:79]
	v_mfma_f32_16x16x32_bf16 v[72:75], v[192:195], v[216:219], v[72:75]
	v_mfma_f32_16x16x32_bf16 v[68:71], v[184:187], v[224:227], v[68:71]
	v_mfma_f32_16x16x32_bf16 v[64:67], v[192:195], v[224:227], v[64:67]
	s_barrier
	s_add_i32 s27, s74, s3
	v_lshl_add_u64 v[228:229], s[42:43], 0, v[176:177]
	s_mov_b32 m0, s27
	ds_read_b128 v[196:199], v139 offset:16384
	ds_read_b128 v[200:203], v139 offset:17408
	ds_read_b128 v[204:207], v139 offset:18432
	ds_read_b128 v[208:211], v139 offset:19456
	ds_read_b128 v[212:215], v139 offset:20480
	ds_read_b128 v[216:219], v139 offset:21504
	ds_read_b128 v[220:223], v139 offset:22528
	ds_read_b128 v[224:227], v139 offset:23552
	global_load_lds_dwordx4 v[228:229], off
	s_add_i32 m0, s27, 0x2000
	v_lshl_add_u64 v[230:231], s[42:43], 0, v[132:133]
	s_add_u32 s42, s42, s10
	s_addc_u32 s43, s43, s11
	s_add_i32 s17, s17, s3
	global_load_lds_dwordx4 v[230:231], off
	v_lshl_add_u64 v[232:233], s[42:43], 0, v[176:177]
	s_mov_b32 m0, s17
	v_lshl_add_u64 v[234:235], s[42:43], 0, v[132:133]
	global_load_lds_dwordx4 v[232:233], off
	s_add_i32 m0, s17, 0x2000
	v_lshl_add_u64 v[236:237], s[50:51], 0, v[128:129]
	global_load_lds_dwordx4 v[234:235], off
	s_mov_b32 m0, s16
	v_lshl_add_u64 v[246:247], s[50:51], 0, v[130:131]
	global_load_lds_dwordx4 v[236:237], off
	s_mov_b32 m0, s6
	s_nop 0
	global_load_lds_dwordx4 v[246:247], off
	s_waitcnt vmcnt(8)
	s_waitcnt lgkmcnt(0)
	s_barrier
; #define PG8_STAGE(bufoff, gbase, voff) do { _Pragma("unroll") for (int _i = 0; _i < 2; ++_i) \
;         __builtin_amdgcn_global_load_lds((const unsigned*)((const char*)(gbase) + (voff)[_i]), (LAS unsigned*)(lds + (bufoff) + ldsw + _i * 8192), 16, 0, 0); } while (0)
; #define PG8_LDA(dst, b, h) do { _Pragma("unroll") for (int m = 0; m < 4; ++m) _Pragma("unroll") for (int k = 0; k < 2; ++k) dst[m][k] = *(const LAS bf16x8*)(lds + PG8_SA(b, h) + aoff + m * 2048 + k * 1024); } while (0)
; #define PG8_LDB(dst, b, h) do { _Pragma("unroll") for (int n = 0; n < 2; ++n) _Pragma("unroll") for (int k = 0; k < 2; ++k) dst[n][k] = *(const LAS bf16x8*)(lds + PG8_SB(b, h) + boff + n * 2048 + k * 1024); } while (0)
; #define PG8_MMA(ai, bj, At, Bt) do { __builtin_amdgcn_s_setprio(1); _Pragma("unroll") for (int m = 0; m < 4; ++m) _Pragma("unroll") for (int n = 0; n < 2; ++n) _Pragma("unroll") for (int k = 0; k < 2; ++k) \
;         acc[ai][bj][m][n] = __builtin_amdgcn_mfma_f32_16x16x32_bf16(Bt[n][k], At[m][k], acc[ai][bj][m][n], 0, 0, 0); __builtin_amdgcn_s_setprio(0); } while (0)
; #define PG8_WAIT_V(n) asm volatile("s_waitcnt vmcnt(" #n ")" ::: "memory")
; #define PG8_WAIT_L(n) asm volatile("s_waitcnt lgkmcnt(" #n ")" ::: "memory")
; #define PG8_BAR __builtin_amdgcn_s_barrier()
; #define PG8_SCHED __builtin_amdgcn_sched_barrier(0)
; template <class Epi, class Sched, bool ALIGN_EPI>
; __device__ __forceinline__ void gemm_phase(LAS unsigned char* lds, const int wid, const int lda_, const int ldb_, const int K_, const Sched& S, const Epi& E) {
;     ...
;             PG8_LDB(B0, 0, 0); PG8_LDB(B1, 0, 1); PG8_SCHED; PG8_LDA(At, 0, 0); PG8_STAGE(PG8_SA(1, 1), a1 + hstepA, voffA);
;             PG8_WAIT_V(8); PG8_WAIT_L(0); PG8_BAR; PG8_MMA(0, 0, At, B0); PG8_MMA(0, 1, At, B1); PG8_BAR; PG8_SCHED;
;             PG8_LDA(At, 0, 1); PG8_STAGE(PG8_SB(0, 0), b2, voffB); PG8_STAGE(PG8_SB(0, 1), b2 + hstepB, voffB); PG8_STAGE(PG8_SA(0, 0), a2, voffA);
;             PG8_WAIT_V(8); PG8_WAIT_L(0); PG8_BAR; PG8_MMA(1, 0, At, B0); PG8_MMA(1, 1, At, B1); PG8_BAR; PG8_SCHED;
	s_waitcnt lgkmcnt(0)
	v_mfma_f32_16x16x32_bf16 v[60:63], v[160:163], v[196:199], 0
	v_mfma_f32_16x16x32_bf16 v[56:59], v[168:171], v[196:199], 0
	v_mfma_f32_16x16x32_bf16 v[52:55], v[160:163], v[204:207], 0
	v_mfma_f32_16x16x32_bf16 v[48:51], v[168:171], v[204:207], 0
	v_mfma_f32_16x16x32_bf16 v[36:39], v[160:163], v[212:215], 0
	v_mfma_f32_16x16x32_bf16 v[32:35], v[168:171], v[212:215], 0
	v_mfma_f32_16x16x32_bf16 v[20:23], v[160:163], v[220:223], 0
	v_mfma_f32_16x16x32_bf16 v[16:19], v[168:171], v[220:223], 0
	v_mfma_f32_16x16x32_bf16 v[60:63], v[164:167], v[200:203], v[60:63]
	v_mfma_f32_16x16x32_bf16 v[56:59], v[172:175], v[200:203], v[56:59]
	v_mfma_f32_16x16x32_bf16 v[52:55], v[164:167], v[208:211], v[52:55]
	v_mfma_f32_16x16x32_bf16 v[48:51], v[172:175], v[208:211], v[48:51]
	v_mfma_f32_16x16x32_bf16 v[36:39], v[164:167], v[216:219], v[36:39]
	v_mfma_f32_16x16x32_bf16 v[32:35], v[172:175], v[216:219], v[32:35]
	v_mfma_f32_16x16x32_bf16 v[20:23], v[164:167], v[224:227], v[20:23]
	v_mfma_f32_16x16x32_bf16 v[16:19], v[172:175], v[224:227], v[16:19]
	v_mfma_f32_16x16x32_bf16 v[44:47], v[180:183], v[196:199], 0
	v_mfma_f32_16x16x32_bf16 v[40:43], v[188:191], v[196:199], 0
	v_mfma_f32_16x16x32_bf16 v[28:31], v[180:183], v[204:207], 0
	v_mfma_f32_16x16x32_bf16 v[24:27], v[188:191], v[204:207], 0
	v_mfma_f32_16x16x32_bf16 v[12:15], v[180:183], v[212:215], 0
	v_mfma_f32_16x16x32_bf16 v[8:11], v[188:191], v[212:215], 0
	v_mfma_f32_16x16x32_bf16 v[4:7], v[180:183], v[220:223], 0
	v_mfma_f32_16x16x32_bf16 v[0:3], v[188:191], v[220:223], 0
	v_mfma_f32_16x16x32_bf16 v[44:47], v[184:187], v[200:203], v[44:47]
	v_mfma_f32_16x16x32_bf16 v[40:43], v[192:195], v[200:203], v[40:43]
	v_mfma_f32_16x16x32_bf16 v[28:31], v[184:187], v[208:211], v[28:31]
	v_mfma_f32_16x16x32_bf16 v[24:27], v[192:195], v[208:211], v[24:27]
	v_mfma_f32_16x16x32_bf16 v[12:15], v[184:187], v[216:219], v[12:15]
	v_mfma_f32_16x16x32_bf16 v[8:11], v[192:195], v[216:219], v[8:11]
	v_mfma_f32_16x16x32_bf16 v[4:7], v[184:187], v[224:227], v[4:7]
	v_mfma_f32_16x16x32_bf16 v[0:3], v[192:195], v[224:227], v[0:3]
	s_barrier
	s_branch .Lgemm_join_883
.LBB0_883:
	s_add_u32 s17, s46, s48
	s_addc_u32 s27, s47, s49
	s_add_u32 s17, s17, 0x100
	s_addc_u32 s27, s27, 0
	s_add_u32 s42, s31, s48
	s_addc_u32 s43, s35, s49
	s_add_i32 s74, 0, 0x10000
	s_cmpk_eq_i32 s48, 0x300
	s_cselect_b32 s51, s4, s27
	s_cselect_b32 s50, s5, s17
	v_add_u32_e32 v141, s74, v135
	s_cselect_b32 s43, s39, s43
	s_cselect_b32 s42, s38, s42
	s_add_i32 s17, 0, 0x14000
	ds_read_b128 v[160:163], v141
	ds_read_b128 v[164:167], v141 offset:1024
	ds_read_b128 v[168:171], v141 offset:2048
	ds_read_b128 v[172:175], v141 offset:3072
	v_add_u32_e32 v141, s17, v135
	ds_read_b128 v[180:183], v141
	ds_read_b128 v[184:187], v141 offset:1024
	ds_read_b128 v[188:191], v141 offset:2048
	ds_read_b128 v[192:195], v141 offset:3072
	v_lshl_add_u64 v[228:229], v[158:159], 0, s[48:49]
	s_add_i32 m0, s16, 0xc000
	ds_read_b128 v[196:199], v139
	ds_read_b128 v[200:203], v139 offset:1024
	ds_read_b128 v[204:207], v139 offset:2048
	ds_read_b128 v[208:211], v139 offset:3072
	ds_read_b128 v[212:215], v139 offset:4096
	ds_read_b128 v[216:219], v139 offset:5120
	ds_read_b128 v[220:223], v139 offset:6144
	ds_read_b128 v[224:227], v139 offset:7168
	global_load_lds_dwordx4 v[228:229], off
	v_lshl_add_u64 v[228:229], v[156:157], 0, s[48:49]
	s_add_i32 m0, s16, 0xe000
	s_nop 0
	global_load_lds_dwordx4 v[228:229], off
	s_waitcnt vmcnt(8)
	s_waitcnt lgkmcnt(0)
	s_barrier
	s_waitcnt lgkmcnt(0)
	v_mfma_f32_16x16x32_bf16 v[124:127], v[160:163], v[196:199], v[124:127]
	v_mfma_f32_16x16x32_bf16 v[120:123], v[168:171], v[196:199], v[120:123]
	v_mfma_f32_16x16x32_bf16 v[116:119], v[160:163], v[204:207], v[116:119]
	v_mfma_f32_16x16x32_bf16 v[112:115], v[168:171], v[204:207], v[112:115]
	v_mfma_f32_16x16x32_bf16 v[100:103], v[160:163], v[212:215], v[100:103]
	v_mfma_f32_16x16x32_bf16 v[96:99], v[168:171], v[212:215], v[96:99]
	v_mfma_f32_16x16x32_bf16 v[84:87], v[160:163], v[220:223], v[84:87]
	v_mfma_f32_16x16x32_bf16 v[80:83], v[168:171], v[220:223], v[80:83]
	v_mfma_f32_16x16x32_bf16 v[124:127], v[164:167], v[200:203], v[124:127]
	v_mfma_f32_16x16x32_bf16 v[120:123], v[172:175], v[200:203], v[120:123]
	v_mfma_f32_16x16x32_bf16 v[116:119], v[164:167], v[208:211], v[116:119]
	v_mfma_f32_16x16x32_bf16 v[112:115], v[172:175], v[208:211], v[112:115]
	v_mfma_f32_16x16x32_bf16 v[100:103], v[164:167], v[216:219], v[100:103]
	v_mfma_f32_16x16x32_bf16 v[96:99], v[172:175], v[216:219], v[96:99]
	v_mfma_f32_16x16x32_bf16 v[84:87], v[164:167], v[224:227], v[84:87]
	v_mfma_f32_16x16x32_bf16 v[80:83], v[172:175], v[224:227], v[80:83]
	v_mfma_f32_16x16x32_bf16 v[108:111], v[180:183], v[196:199], v[108:111]
	v_mfma_f32_16x16x32_bf16 v[104:107], v[188:191], v[196:199], v[104:107]
	v_mfma_f32_16x16x32_bf16 v[92:95], v[180:183], v[204:207], v[92:95]
	v_mfma_f32_16x16x32_bf16 v[88:91], v[188:191], v[204:207], v[88:91]
	v_mfma_f32_16x16x32_bf16 v[76:79], v[180:183], v[212:215], v[76:79]
	v_mfma_f32_16x16x32_bf16 v[72:75], v[188:191], v[212:215], v[72:75]
	v_mfma_f32_16x16x32_bf16 v[68:71], v[180:183], v[220:223], v[68:71]
	v_mfma_f32_16x16x32_bf16 v[64:67], v[188:191], v[220:223], v[64:67]
	v_mfma_f32_16x16x32_bf16 v[108:111], v[184:187], v[200:203], v[108:111]
	v_mfma_f32_16x16x32_bf16 v[104:107], v[192:195], v[200:203], v[104:107]
	v_mfma_f32_16x16x32_bf16 v[92:95], v[184:187], v[208:211], v[92:95]
	v_mfma_f32_16x16x32_bf16 v[88:91], v[192:195], v[208:211], v[88:91]
	v_mfma_f32_16x16x32_bf16 v[76:79], v[184:187], v[216:219], v[76:79]
	v_mfma_f32_16x16x32_bf16 v[72:75], v[192:195], v[216:219], v[72:75]
	v_mfma_f32_16x16x32_bf16 v[68:71], v[184:187], v[224:227], v[68:71]
	v_mfma_f32_16x16x32_bf16 v[64:67], v[192:195], v[224:227], v[64:67]
	s_barrier
; #define PG8_STAGE(bufoff, gbase, voff) do { _Pragma("unroll") for (int _i = 0; _i < 2; ++_i) \
;         __builtin_amdgcn_global_load_lds((const unsigned*)((const char*)(gbase) + (voff)[_i]), (LAS unsigned*)(lds + (bufoff) + ldsw + _i * 8192), 16, 0, 0); } while (0)
; #define PG8_LDA(dst, b, h) do { _Pragma("unroll") for (int m = 0; m < 4; ++m) _Pragma("unroll") for (int k = 0; k < 2; ++k) dst[m][k] = *(const LAS bf16x8*)(lds + PG8_SA(b, h) + aoff + m * 2048 + k * 1024); } while (0)
; #define PG8_LDB(dst, b, h) do { _Pragma("unroll") for (int n = 0; n < 2; ++n) _Pragma("unroll") for (int k = 0; k < 2; ++k) dst[n][k] = *(const LAS bf16x8*)(lds + PG8_SB(b, h) + boff + n * 2048 + k * 1024); } while (0)
; #define PG8_MMA(ai, bj, At, Bt) do { __builtin_amdgcn_s_setprio(1); _Pragma("unroll") for (int m = 0; m < 4; ++m) _Pragma("unroll") for (int n = 0; n < 2; ++n) _Pragma("unroll") for (int k = 0; k < 2; ++k) \
;         acc[ai][bj][m][n] = __builtin_amdgcn_mfma_f32_16x16x32_bf16(Bt[n][k], At[m][k], acc[ai][bj][m][n], 0, 0, 0); __builtin_amdgcn_s_setprio(0); } while (0)
; #define PG8_WAIT_V(n) asm volatile("s_waitcnt vmcnt(" #n ")" ::: "memory")
; #define PG8_WAIT_L(n) asm volatile("s_waitcnt lgkmcnt(" #n ")" ::: "memory")
; #define PG8_BAR __builtin_amdgcn_s_barrier()
; #define PG8_SCHED __builtin_amdgcn_sched_barrier(0)
; template <class Epi, class Sched, bool ALIGN_EPI>
; __device__ __forceinline__ void gemm_phase(LAS unsigned char* lds, const int wid, const int lda_, const int ldb_, const int K_, const Sched& S, const Epi& E) {
;     ...
;             PG8_LDA(At, 0, 1); PG8_STAGE(PG8_SB(0, 0), b2, voffB); PG8_STAGE(PG8_SB(0, 1), b2 + hstepB, voffB); PG8_STAGE(PG8_SA(0, 0), a2, voffA);
;             PG8_WAIT_V(8); PG8_WAIT_L(0); PG8_BAR; PG8_MMA(1, 0, At, B0); PG8_MMA(1, 1, At, B1); PG8_BAR; PG8_SCHED;
;             PG8_LDB(B0, 1, 0); PG8_LDB(B1, 1, 1); PG8_SCHED; PG8_LDA(At, 1, 0); PG8_STAGE(PG8_SA(0, 1), a2 + hstepA, voffA);
	s_add_i32 s27, s74, s3
	v_lshl_add_u64 v[228:229], s[42:43], 0, v[176:177]
	s_mov_b32 m0, s27
	ds_read_b128 v[196:199], v139 offset:16384
	ds_read_b128 v[200:203], v139 offset:17408
	ds_read_b128 v[204:207], v139 offset:18432
	ds_read_b128 v[208:211], v139 offset:19456
	ds_read_b128 v[212:215], v139 offset:20480
	ds_read_b128 v[216:219], v139 offset:21504
	ds_read_b128 v[220:223], v139 offset:22528
	ds_read_b128 v[224:227], v139 offset:23552
	global_load_lds_dwordx4 v[228:229], off
	s_add_i32 m0, s27, 0x2000
	v_lshl_add_u64 v[230:231], s[42:43], 0, v[132:133]
	s_add_u32 s42, s42, s10
	s_addc_u32 s43, s43, s11
	s_add_i32 s17, s17, s3
	global_load_lds_dwordx4 v[230:231], off
	v_lshl_add_u64 v[232:233], s[42:43], 0, v[176:177]
	s_mov_b32 m0, s17
	v_lshl_add_u64 v[234:235], s[42:43], 0, v[132:133]
	global_load_lds_dwordx4 v[232:233], off
	s_add_i32 m0, s17, 0x2000
	v_lshl_add_u64 v[236:237], s[50:51], 0, v[128:129]
	global_load_lds_dwordx4 v[234:235], off
	s_mov_b32 m0, s16
	v_lshl_add_u64 v[246:247], s[50:51], 0, v[130:131]
	global_load_lds_dwordx4 v[236:237], off
	s_mov_b32 m0, s6
	s_nop 0
	global_load_lds_dwordx4 v[246:247], off
	s_waitcnt vmcnt(8)
	s_waitcnt lgkmcnt(0)
	s_barrier
	s_waitcnt lgkmcnt(0)
	v_mfma_f32_16x16x32_bf16 v[60:63], v[160:163], v[196:199], v[60:63]
	v_mfma_f32_16x16x32_bf16 v[56:59], v[168:171], v[196:199], v[56:59]
	v_mfma_f32_16x16x32_bf16 v[52:55], v[160:163], v[204:207], v[52:55]
	v_mfma_f32_16x16x32_bf16 v[48:51], v[168:171], v[204:207], v[48:51]
	v_mfma_f32_16x16x32_bf16 v[36:39], v[160:163], v[212:215], v[36:39]
	v_mfma_f32_16x16x32_bf16 v[32:35], v[168:171], v[212:215], v[32:35]
	v_mfma_f32_16x16x32_bf16 v[20:23], v[160:163], v[220:223], v[20:23]
	v_mfma_f32_16x16x32_bf16 v[16:19], v[168:171], v[220:223], v[16:19]
	v_mfma_f32_16x16x32_bf16 v[60:63], v[164:167], v[200:203], v[60:63]
	v_mfma_f32_16x16x32_bf16 v[56:59], v[172:175], v[200:203], v[56:59]
	v_mfma_f32_16x16x32_bf16 v[52:55], v[164:167], v[208:211], v[52:55]
	v_mfma_f32_16x16x32_bf16 v[48:51], v[172:175], v[208:211], v[48:51]
	v_mfma_f32_16x16x32_bf16 v[36:39], v[164:167], v[216:219], v[36:39]
	v_mfma_f32_16x16x32_bf16 v[32:35], v[172:175], v[216:219], v[32:35]
	v_mfma_f32_16x16x32_bf16 v[20:23], v[164:167], v[224:227], v[20:23]
	v_mfma_f32_16x16x32_bf16 v[16:19], v[172:175], v[224:227], v[16:19]
	v_mfma_f32_16x16x32_bf16 v[44:47], v[180:183], v[196:199], v[44:47]
	v_mfma_f32_16x16x32_bf16 v[40:43], v[188:191], v[196:199], v[40:43]
	v_mfma_f32_16x16x32_bf16 v[28:31], v[180:183], v[204:207], v[28:31]
	v_mfma_f32_16x16x32_bf16 v[24:27], v[188:191], v[204:207], v[24:27]
	v_mfma_f32_16x16x32_bf16 v[12:15], v[180:183], v[212:215], v[12:15]
	v_mfma_f32_16x16x32_bf16 v[8:11], v[188:191], v[212:215], v[8:11]
	v_mfma_f32_16x16x32_bf16 v[4:7], v[180:183], v[220:223], v[4:7]
	v_mfma_f32_16x16x32_bf16 v[0:3], v[188:191], v[220:223], v[0:3]
	v_mfma_f32_16x16x32_bf16 v[44:47], v[184:187], v[200:203], v[44:47]
	v_mfma_f32_16x16x32_bf16 v[40:43], v[192:195], v[200:203], v[40:43]
	v_mfma_f32_16x16x32_bf16 v[28:31], v[184:187], v[208:211], v[28:31]
	v_mfma_f32_16x16x32_bf16 v[24:27], v[192:195], v[208:211], v[24:27]
	v_mfma_f32_16x16x32_bf16 v[12:15], v[184:187], v[216:219], v[12:15]
	v_mfma_f32_16x16x32_bf16 v[8:11], v[192:195], v[216:219], v[8:11]
	v_mfma_f32_16x16x32_bf16 v[4:7], v[184:187], v[224:227], v[4:7]
	v_mfma_f32_16x16x32_bf16 v[0:3], v[192:195], v[224:227], v[0:3]
	s_barrier
.Lgemm_join_883:
	s_add_i32 s17, 0, 0x18000
	v_add_u32_e32 v141, s17, v135
	s_add_i32 s27, 0, 0x1c000
	ds_read_b128 v[160:163], v141
	ds_read_b128 v[164:167], v141 offset:1024
	ds_read_b128 v[168:171], v141 offset:2048
	ds_read_b128 v[172:175], v141 offset:3072
	v_add_u32_e32 v141, s27, v135
	ds_read_b128 v[180:183], v141
	ds_read_b128 v[184:187], v141 offset:1024
	ds_read_b128 v[188:191], v141 offset:2048
	ds_read_b128 v[192:195], v141 offset:3072
	s_add_u32 s42, s50, s0
	s_addc_u32 s43, s51, s1
	s_mov_b32 m0, s7
	v_lshl_add_u64 v[248:249], s[42:43], 0, v[128:129]
	ds_read_b128 v[196:199], v139 offset:32768
	ds_read_b128 v[200:203], v139 offset:33792
	ds_read_b128 v[204:207], v139 offset:34816
	ds_read_b128 v[208:211], v139 offset:35840
	ds_read_b128 v[212:215], v139 offset:36864
	ds_read_b128 v[216:219], v139 offset:37888
	ds_read_b128 v[220:223], v139 offset:38912
	ds_read_b128 v[224:227], v139 offset:39936
	global_load_lds_dwordx4 v[248:249], off
	v_lshl_add_u64 v[248:249], s[42:43], 0, v[130:131]
	s_mov_b32 m0, s14
	s_nop 0
	global_load_lds_dwordx4 v[248:249], off
	s_waitcnt vmcnt(8)
	s_waitcnt lgkmcnt(0)
	s_barrier
; #define PG8_STAGE(bufoff, gbase, voff) do { _Pragma("unroll") for (int _i = 0; _i < 2; ++_i) \
;         __builtin_amdgcn_global_load_lds((const unsigned*)((const char*)(gbase) + (voff)[_i]), (LAS unsigned*)(lds + (bufoff) + ldsw + _i * 8192), 16, 0, 0); } while (0)
; #define PG8_LDA(dst, b, h) do { _Pragma("unroll") for (int m = 0; m < 4; ++m) _Pragma("unroll") for (int k = 0; k < 2; ++k) dst[m][k] = *(const LAS bf16x8*)(lds + PG8_SA(b, h) + aoff + m * 2048 + k * 1024); } while (0)
; #define PG8_MMA(ai, bj, At, Bt) do { __builtin_amdgcn_s_setprio(1); _Pragma("unroll") for (int m = 0; m < 4; ++m) _Pragma("unroll") for (int n = 0; n < 2; ++n) _Pragma("unroll") for (int k = 0; k < 2; ++k) \
;         acc[ai][bj][m][n] = __builtin_amdgcn_mfma_f32_16x16x32_bf16(Bt[n][k], At[m][k], acc[ai][bj][m][n], 0, 0, 0); __builtin_amdgcn_s_setprio(0); } while (0)
; #define PG8_WAIT_V(n) asm volatile("s_waitcnt vmcnt(" #n ")" ::: "memory")
; #define PG8_WAIT_L(n) asm volatile("s_waitcnt lgkmcnt(" #n ")" ::: "memory")
; #define PG8_BAR __builtin_amdgcn_s_barrier()
; #define PG8_SCHED __builtin_amdgcn_sched_barrier(0)
; template <class Epi, class Sched, bool ALIGN_EPI>
; __device__ __forceinline__ void gemm_phase(LAS unsigned char* lds, const int wid, const int lda_, const int ldb_, const int K_, const Sched& S, const Epi& E) {
;     ...
;             PG8_WAIT_V(8); PG8_WAIT_L(0); PG8_BAR; PG8_MMA(0, 0, At, B0); PG8_MMA(0, 1, At, B1); PG8_BAR; PG8_SCHED;
;             PG8_LDA(At, 1, 1); PG8_STAGE(PG8_SB(1, 0), b3, voffB); PG8_STAGE(PG8_SB(1, 1), b3 + hstepB, voffB); PG8_STAGE(PG8_SA(1, 0), a3, voffA);
;             PG8_WAIT_V(8); PG8_WAIT_L(0); PG8_BAR; PG8_MMA(1, 0, At, B0); PG8_MMA(1, 1, At, B1); PG8_BAR; PG8_SCHED;
	s_waitcnt lgkmcnt(0)
	v_mfma_f32_16x16x32_bf16 v[124:127], v[160:163], v[196:199], v[124:127]
	v_mfma_f32_16x16x32_bf16 v[120:123], v[168:171], v[196:199], v[120:123]
	v_mfma_f32_16x16x32_bf16 v[116:119], v[160:163], v[204:207], v[116:119]
	v_mfma_f32_16x16x32_bf16 v[112:115], v[168:171], v[204:207], v[112:115]
	v_mfma_f32_16x16x32_bf16 v[100:103], v[160:163], v[212:215], v[100:103]
	v_mfma_f32_16x16x32_bf16 v[96:99], v[168:171], v[212:215], v[96:99]
	v_mfma_f32_16x16x32_bf16 v[84:87], v[160:163], v[220:223], v[84:87]
	v_mfma_f32_16x16x32_bf16 v[80:83], v[168:171], v[220:223], v[80:83]
	v_mfma_f32_16x16x32_bf16 v[124:127], v[164:167], v[200:203], v[124:127]
	v_mfma_f32_16x16x32_bf16 v[120:123], v[172:175], v[200:203], v[120:123]
	v_mfma_f32_16x16x32_bf16 v[116:119], v[164:167], v[208:211], v[116:119]
	v_mfma_f32_16x16x32_bf16 v[112:115], v[172:175], v[208:211], v[112:115]
	v_mfma_f32_16x16x32_bf16 v[100:103], v[164:167], v[216:219], v[100:103]
	v_mfma_f32_16x16x32_bf16 v[96:99], v[172:175], v[216:219], v[96:99]
	v_mfma_f32_16x16x32_bf16 v[84:87], v[164:167], v[224:227], v[84:87]
	v_mfma_f32_16x16x32_bf16 v[80:83], v[172:175], v[224:227], v[80:83]
	v_mfma_f32_16x16x32_bf16 v[108:111], v[180:183], v[196:199], v[108:111]
	v_mfma_f32_16x16x32_bf16 v[104:107], v[188:191], v[196:199], v[104:107]
	v_mfma_f32_16x16x32_bf16 v[92:95], v[180:183], v[204:207], v[92:95]
	v_mfma_f32_16x16x32_bf16 v[88:91], v[188:191], v[204:207], v[88:91]
	v_mfma_f32_16x16x32_bf16 v[76:79], v[180:183], v[212:215], v[76:79]
	v_mfma_f32_16x16x32_bf16 v[72:75], v[188:191], v[212:215], v[72:75]
	v_mfma_f32_16x16x32_bf16 v[68:71], v[180:183], v[220:223], v[68:71]
	v_mfma_f32_16x16x32_bf16 v[64:67], v[188:191], v[220:223], v[64:67]
	v_mfma_f32_16x16x32_bf16 v[108:111], v[184:187], v[200:203], v[108:111]
	v_mfma_f32_16x16x32_bf16 v[104:107], v[192:195], v[200:203], v[104:107]
	v_mfma_f32_16x16x32_bf16 v[92:95], v[184:187], v[208:211], v[92:95]
	v_mfma_f32_16x16x32_bf16 v[88:91], v[192:195], v[208:211], v[88:91]
	v_mfma_f32_16x16x32_bf16 v[76:79], v[184:187], v[216:219], v[76:79]
	v_mfma_f32_16x16x32_bf16 v[72:75], v[192:195], v[216:219], v[72:75]
	v_mfma_f32_16x16x32_bf16 v[68:71], v[184:187], v[224:227], v[68:71]
	v_mfma_f32_16x16x32_bf16 v[64:67], v[192:195], v[224:227], v[64:67]
	s_barrier
	s_add_i32 s17, s17, s3
	v_lshl_add_u64 v[228:229], v[228:229], 0, s[24:25]
	s_mov_b32 m0, s17
	ds_read_b128 v[196:199], v139 offset:49152
	ds_read_b128 v[200:203], v139 offset:50176
	ds_read_b128 v[204:207], v139 offset:51200
	ds_read_b128 v[208:211], v139 offset:52224
	ds_read_b128 v[212:215], v139 offset:53248
	ds_read_b128 v[216:219], v139 offset:54272
	ds_read_b128 v[220:223], v139 offset:55296
	ds_read_b128 v[224:227], v139 offset:56320
	global_load_lds_dwordx4 v[228:229], off
	v_lshl_add_u64 v[228:229], v[230:231], 0, s[24:25]
	s_add_i32 m0, s17, 0x2000
	s_add_i32 s17, s27, s3
	global_load_lds_dwordx4 v[228:229], off
	v_lshl_add_u64 v[228:229], v[232:233], 0, s[24:25]
	s_mov_b32 m0, s17
	s_nop 0
	global_load_lds_dwordx4 v[228:229], off
	v_lshl_add_u64 v[228:229], v[234:235], 0, s[24:25]
	s_add_i32 m0, s17, 0x2000
	s_nop 0
	global_load_lds_dwordx4 v[228:229], off
	v_lshl_add_u64 v[228:229], v[236:237], 0, s[24:25]
	s_mov_b32 m0, s15
	s_nop 0
	global_load_lds_dwordx4 v[228:229], off
	v_lshl_add_u64 v[228:229], v[246:247], 0, s[24:25]
	s_mov_b32 m0, s26
	s_nop 0
	global_load_lds_dwordx4 v[228:229], off
	s_waitcnt vmcnt(8)
	s_waitcnt lgkmcnt(0)
	s_barrier
	s_waitcnt lgkmcnt(0)
	v_mfma_f32_16x16x32_bf16 v[60:63], v[160:163], v[196:199], v[60:63]
	v_mfma_f32_16x16x32_bf16 v[56:59], v[168:171], v[196:199], v[56:59]
	v_mfma_f32_16x16x32_bf16 v[52:55], v[160:163], v[204:207], v[52:55]
	v_mfma_f32_16x16x32_bf16 v[48:51], v[168:171], v[204:207], v[48:51]
	v_mfma_f32_16x16x32_bf16 v[36:39], v[160:163], v[212:215], v[36:39]
	v_mfma_f32_16x16x32_bf16 v[32:35], v[168:171], v[212:215], v[32:35]
	v_mfma_f32_16x16x32_bf16 v[20:23], v[160:163], v[220:223], v[20:23]
	v_mfma_f32_16x16x32_bf16 v[16:19], v[168:171], v[220:223], v[16:19]
	v_mfma_f32_16x16x32_bf16 v[60:63], v[164:167], v[200:203], v[60:63]
	v_mfma_f32_16x16x32_bf16 v[56:59], v[172:175], v[200:203], v[56:59]
	v_mfma_f32_16x16x32_bf16 v[52:55], v[164:167], v[208:211], v[52:55]
	v_mfma_f32_16x16x32_bf16 v[48:51], v[172:175], v[208:211], v[48:51]
	v_mfma_f32_16x16x32_bf16 v[36:39], v[164:167], v[216:219], v[36:39]
	v_mfma_f32_16x16x32_bf16 v[32:35], v[172:175], v[216:219], v[32:35]
	v_mfma_f32_16x16x32_bf16 v[20:23], v[164:167], v[224:227], v[20:23]
	v_mfma_f32_16x16x32_bf16 v[16:19], v[172:175], v[224:227], v[16:19]
	v_mfma_f32_16x16x32_bf16 v[44:47], v[180:183], v[196:199], v[44:47]
	v_mfma_f32_16x16x32_bf16 v[40:43], v[188:191], v[196:199], v[40:43]
	v_mfma_f32_16x16x32_bf16 v[28:31], v[180:183], v[204:207], v[28:31]
	v_mfma_f32_16x16x32_bf16 v[24:27], v[188:191], v[204:207], v[24:27]
	v_mfma_f32_16x16x32_bf16 v[12:15], v[180:183], v[212:215], v[12:15]
	v_mfma_f32_16x16x32_bf16 v[8:11], v[188:191], v[212:215], v[8:11]
	v_mfma_f32_16x16x32_bf16 v[4:7], v[180:183], v[220:223], v[4:7]
	v_mfma_f32_16x16x32_bf16 v[0:3], v[188:191], v[220:223], v[0:3]
	v_mfma_f32_16x16x32_bf16 v[44:47], v[184:187], v[200:203], v[44:47]
	v_mfma_f32_16x16x32_bf16 v[40:43], v[192:195], v[200:203], v[40:43]
	v_mfma_f32_16x16x32_bf16 v[28:31], v[184:187], v[208:211], v[28:31]
	v_mfma_f32_16x16x32_bf16 v[24:27], v[192:195], v[208:211], v[24:27]
	v_mfma_f32_16x16x32_bf16 v[12:15], v[184:187], v[216:219], v[12:15]
	v_mfma_f32_16x16x32_bf16 v[8:11], v[192:195], v[216:219], v[8:11]
	v_mfma_f32_16x16x32_bf16 v[4:7], v[184:187], v[224:227], v[4:7]
	v_mfma_f32_16x16x32_bf16 v[0:3], v[192:195], v[224:227], v[0:3]
	s_barrier
; __device__ __forceinline__ unsigned cvt_pk_bf16(float lo, float hi) { const f32x2 v = {lo, hi}; return __builtin_bit_cast(unsigned, __builtin_convertvector(v, bf16x2_t)); }
; #define PG8_MMA(ai, bj, At, Bt) do { __builtin_amdgcn_s_setprio(1); _Pragma("unroll") for (int m = 0; m < 4; ++m) _Pragma("unroll") for (int n = 0; n < 2; ++n) _Pragma("unroll") for (int k = 0; k < 2; ++k) \
;         acc[ai][bj][m][n] = __builtin_amdgcn_mfma_f32_16x16x32_bf16(Bt[n][k], At[m][k], acc[ai][bj][m][n], 0, 0, 0); __builtin_amdgcn_s_setprio(0); } while (0)
; #define PG8_WAIT_V(n) asm volatile("s_waitcnt vmcnt(" #n ")" ::: "memory")
; #define PG8_WAIT_L(n) asm volatile("s_waitcnt lgkmcnt(" #n ")" ::: "memory")
;     template <class Sched> __device__ __forceinline__ void operator()(const f32x4 (&acc)[2][2][4][2], const Unit& u, const Sched& S, int wr, int wc, int fr, int fq) const {
;         const int rl0 = wr * 64 + fr, cl0 = wc * 32 + 8 * fq;
;         char* uo; int ldo, kind; S.out(u, uo, ldo, kind);
;         asm volatile("" : "+s"(ldo));
;         if (kind == 0) {
;             bf16_t* base = (bf16_t*)uo;
; #pragma unroll
;             for (int ai = 0; ai < 2; ++ai)
; #pragma unroll
;                 for (int m = 0; m < 4; ++m) { bf16_t* rowp = base + (size_t)(rl0 + ai * HALF + m * 16) * ldo + cl0;
; #pragma unroll
;                     for (int bj = 0; bj < 2; ++bj) { const f32x4 v0 = acc[ai][bj][m][0], v1 = acc[ai][bj][m][1];
;                         u32x4 w; w.x = cvt_pk_bf16(v0[0], v0[1]); w.y = cvt_pk_bf16(v0[2], v0[3]); w.z = cvt_pk_bf16(v1[0], v1[1]); w.w = cvt_pk_bf16(v1[2], v1[3]);
;                         *(u32x4*)(rowp + bj * HALF) = w; } }
; template <class Epi, class Sched, bool ALIGN_EPI>
; __device__ __forceinline__ void gemm_phase(LAS unsigned char* lds, const int wid, const int lda_, const int ldb_, const int K_, const Sched& S, const Epi& E) {
;     ...
;             PG8_WAIT_V(8); PG8_WAIT_L(0); PG8_BAR; PG8_MMA(1, 0, At, B0); PG8_MMA(1, 1, At, B1); PG8_BAR; PG8_SCHED;
;         }
;         if constexpr (ALIGN_EPI) { if (wr == 0) PG8_BAR; }
;         E(acc, cur, S, wr, wc, fr, fq);
;         if (u.pm < 64) { o = (char*)ws + WS_F + (((size_t)((u.pm >> 3) * 2048 + (u.pm & 7))) * D + (size_t)u.pn * 256) * 2; ldo = 8 * D; }
;         else { o = (char*)ws + WS_F + (((size_t)(MLAT + (u.pm - 64) * 256)) * D + (size_t)u.pn * 256) * 2; ldo = D; } }
	s_add_i32 s73, s73, 2
	s_add_u32 s48, s48, 0x100
	s_addc_u32 s49, s49, 0
	s_cmp_gt_u32 s73, 5
	s_cbranch_scc0 .LBB0_883
	s_setprio 2
	s_lshl_b32 s4, s41, 8
	s_and_b32 s5, s4, 0xfffff800
	s_and_b32 s17, s41, 7
	s_or_b32 s17, s5, s17
	s_ashr_i32 s5, s17, 31
	s_cmp_lt_i32 s41, 64
	s_cselect_b32 s4, s17, s4
	s_movk_i32 s17, 0x800
	s_cselect_b32 s5, s5, 0
	s_cselect_b32 s17, 0x4000, s17
	s_ashr_i32 s41, s40, 31
	s_lshl_b64 s[40:41], s[40:41], 9
	s_lshl_b64 s[4:5], s[4:5], 12
	v_readlane_b32 s27, v254, 19
	s_add_u32 s4, s27, s4
	v_readlane_b32 s27, v254, 20
	s_addc_u32 s5, s27, s5
	s_add_u32 s4, s4, s40
	s_addc_u32 s5, s5, s41
	v_lshl_add_u64 v[156:157], v[136:137], 1, s[4:5]
	v_mad_i64_i32 v[158:159], s[4:5], s17, v134, 0
	v_lshl_add_u64 v[158:159], v[158:159], 1, v[156:157]
	v_cvt_pk_bf16_f32 v108, v108, v109
	v_cvt_pk_bf16_f32 v109, v110, v111
	v_cvt_pk_bf16_f32 v110, v104, v105
	v_cvt_pk_bf16_f32 v111, v106, v107
	v_mad_i64_i32 v[104:105], s[4:5], s17, v138, 0
	v_cvt_pk_bf16_f32 v124, v124, v125
	v_cvt_pk_bf16_f32 v125, v126, v127
	v_cvt_pk_bf16_f32 v126, v120, v121
	v_cvt_pk_bf16_f32 v127, v122, v123
	global_store_dwordx4 v[158:159], v[108:111], off offset:256
	v_cvt_pk_bf16_f32 v92, v92, v93
	v_cvt_pk_bf16_f32 v93, v94, v95
	v_lshl_add_u64 v[108:109], v[104:105], 1, v[156:157]
	v_cvt_pk_bf16_f32 v94, v88, v89
	v_cvt_pk_bf16_f32 v95, v90, v91
	v_mad_i64_i32 v[88:89], s[4:5], s17, v140, 0
	global_store_dwordx4 v[158:159], v[124:127], off
	v_cvt_pk_bf16_f32 v104, v116, v117
	v_cvt_pk_bf16_f32 v105, v118, v119
	v_cvt_pk_bf16_f32 v106, v112, v113
	v_cvt_pk_bf16_f32 v107, v114, v115
	global_store_dwordx4 v[108:109], v[92:95], off offset:256
	v_cvt_pk_bf16_f32 v76, v76, v77
	v_cvt_pk_bf16_f32 v77, v78, v79
	v_lshl_add_u64 v[92:93], v[88:89], 1, v[156:157]
	v_cvt_pk_bf16_f32 v78, v72, v73
	v_cvt_pk_bf16_f32 v79, v74, v75
	v_mad_i64_i32 v[72:73], s[4:5], s17, v142, 0
	v_cvt_pk_bf16_f32 v68, v68, v69
	v_cvt_pk_bf16_f32 v69, v70, v71
	v_cvt_pk_bf16_f32 v70, v64, v65
	v_mad_i64_i32 v[64:65], s[4:5], s17, v144, 0
	global_store_dwordx4 v[108:109], v[104:107], off
	v_cvt_pk_bf16_f32 v88, v100, v101
	v_cvt_pk_bf16_f32 v89, v102, v103
	v_cvt_pk_bf16_f32 v90, v96, v97
	v_cvt_pk_bf16_f32 v91, v98, v99
	global_store_dwordx4 v[92:93], v[76:79], off offset:256
	v_cvt_pk_bf16_f32 v74, v80, v81
	v_cvt_pk_bf16_f32 v75, v82, v83
	v_lshl_add_u64 v[76:77], v[72:73], 1, v[156:157]
	v_cvt_pk_bf16_f32 v72, v84, v85
	v_cvt_pk_bf16_f32 v73, v86, v87
	v_cvt_pk_bf16_f32 v71, v66, v67
	v_lshl_add_u64 v[64:65], v[64:65], 1, v[156:157]
	v_cvt_pk_bf16_f32 v44, v44, v45
	v_cvt_pk_bf16_f32 v45, v46, v47
	v_cvt_pk_bf16_f32 v46, v40, v41
	v_cvt_pk_bf16_f32 v47, v42, v43
	v_mad_i64_i32 v[40:41], s[4:5], s17, v146, 0
	global_store_dwordx4 v[92:93], v[88:91], off
	global_store_dwordx4 v[76:77], v[72:75], off
	global_store_dwordx4 v[76:77], v[68:71], off offset:256
	v_cvt_pk_bf16_f32 v60, v60, v61
	v_cvt_pk_bf16_f32 v61, v62, v63
	v_cvt_pk_bf16_f32 v62, v56, v57
	v_cvt_pk_bf16_f32 v63, v58, v59
	global_store_dwordx4 v[64:65], v[44:47], off offset:256
	v_cvt_pk_bf16_f32 v28, v28, v29
	v_cvt_pk_bf16_f32 v29, v30, v31
	v_lshl_add_u64 v[44:45], v[40:41], 1, v[156:157]
	v_cvt_pk_bf16_f32 v30, v24, v25
	v_cvt_pk_bf16_f32 v31, v26, v27
	v_mad_i64_i32 v[24:25], s[4:5], s17, v148, 0
	global_store_dwordx4 v[64:65], v[60:63], off
	v_cvt_pk_bf16_f32 v40, v52, v53
	v_cvt_pk_bf16_f32 v41, v54, v55
	v_cvt_pk_bf16_f32 v42, v48, v49
	v_cvt_pk_bf16_f32 v43, v50, v51
	global_store_dwordx4 v[44:45], v[28:31], off offset:256
	v_cvt_pk_bf16_f32 v12, v12, v13
	v_cvt_pk_bf16_f32 v13, v14, v15
	v_lshl_add_u64 v[28:29], v[24:25], 1, v[156:157]
	v_cvt_pk_bf16_f32 v14, v8, v9
	v_cvt_pk_bf16_f32 v15, v10, v11
	v_mad_i64_i32 v[8:9], s[4:5], s17, v150, 0
	global_store_dwordx4 v[44:45], v[40:43], off
	v_cvt_pk_bf16_f32 v24, v36, v37
	v_cvt_pk_bf16_f32 v25, v38, v39
	v_cvt_pk_bf16_f32 v26, v32, v33
	v_cvt_pk_bf16_f32 v27, v34, v35
	global_store_dwordx4 v[28:29], v[12:15], off offset:256
	v_cvt_pk_bf16_f32 v10, v16, v17
	v_cvt_pk_bf16_f32 v11, v18, v19
	v_lshl_add_u64 v[12:13], v[8:9], 1, v[156:157]
	v_cvt_pk_bf16_f32 v8, v20, v21
	v_cvt_pk_bf16_f32 v9, v22, v23
	v_cvt_pk_bf16_f32 v4, v4, v5
	v_cvt_pk_bf16_f32 v5, v6, v7
	v_cvt_pk_bf16_f32 v6, v0, v1
	v_cvt_pk_bf16_f32 v7, v2, v3
	s_and_b64 vcc, exec, s[36:37]
	s_mov_b32 s40, s30
	s_mov_b32 s41, s34
	s_mov_b64 s[48:49], s[38:39]
	s_mov_b64 s[46:47], s[44:45]
	global_store_dwordx4 v[28:29], v[24:27], off
	global_store_dwordx4 v[12:13], v[8:11], off
	global_store_dwordx4 v[12:13], v[4:7], off offset:256
	s_cbranch_vccz .LBB0_868
	v_readlane_b32 s0, v253, 1
	s_waitcnt vmcnt(0)
	v_readlane_b32 s1, v253, 2
	v_readlane_b32 s72, v255, 28
	s_andn2_b64 vcc, exec, s[0:1]
	v_readlane_b32 s73, v255, 29
	s_cbranch_vccnz .LBB0_887
	s_barrier

; #define PG8_STAGE(bufoff, gbase, voff) do { _Pragma("unroll") for (int _i = 0; _i < 2; ++_i) \
;         __builtin_amdgcn_global_load_lds((const unsigned*)((const char*)(gbase) + (voff)[_i]), (LAS unsigned*)(lds + (bufoff) + ldsw + _i * 8192), 16, 0, 0); } while (0)
; #define PG8_LDA(dst, b, h) do { _Pragma("unroll") for (int m = 0; m < 4; ++m) _Pragma("unroll") for (int k = 0; k < 2; ++k) dst[m][k] = *(const LAS bf16x8*)(lds + PG8_SA(b, h) + aoff + m * 2048 + k * 1024); } while (0)
; #define PG8_LDB(dst, b, h) do { _Pragma("unroll") for (int n = 0; n < 2; ++n) _Pragma("unroll") for (int k = 0; k < 2; ++k) dst[n][k] = *(const LAS bf16x8*)(lds + PG8_SB(b, h) + boff + n * 2048 + k * 1024); } while (0)
; #define PG8_WAIT_V(n) asm volatile("s_waitcnt vmcnt(" #n ")" ::: "memory")
; #define PG8_WAIT_L(n) asm volatile("s_waitcnt lgkmcnt(" #n ")" ::: "memory")
; template <class Epi, class Sched, bool ALIGN_EPI>
; __device__ __forceinline__ void gemm_phase(LAS unsigned char* lds, const int wid, const int lda_, const int ldb_, const int K_, const Sched& S, const Epi& E) {
;     ...
;         const bool has_next = S.next(ui + 1, nxt);
;         const int nt = S.nt(cur);
;         const char* nA = has_next ? S.a(nxt) : cA; const char* nB = has_next ? S.b(nxt) : cB;
; #pragma unroll 1
;         for (int t = 0; t < nt; t += 2) {
;             const bool last = (t == nt - 2);
;             const char* a1 = cA + (size_t)(t + 1) * kstep;
;             const char* a2 = last ? nA : cA + (size_t)(t + 2) * kstep; const char* b2 = last ? nB : cB + (size_t)(t + 2) * kstep;
;             const char* a3 = a2 + kstep; const char* b3 = b2 + kstep;
;             PG8_LDB(B0, 0, 0); PG8_LDB(B1, 0, 1); PG8_SCHED; PG8_LDA(At, 0, 0); PG8_STAGE(PG8_SA(1, 1), a1 + hstepA, voffA);
;             PG8_WAIT_V(8); PG8_WAIT_L(0); PG8_BAR; PG8_MMA(0, 0, At, B0); PG8_MMA(0, 1, At, B1); PG8_BAR; PG8_SCHED;
;             PG8_LDA(At, 0, 1); PG8_STAGE(PG8_SB(0, 0), b2, voffB); PG8_STAGE(PG8_SB(0, 1), b2 + hstepB, voffB); PG8_STAGE(PG8_SA(0, 0), a2, voffA);
;     __device__ __forceinline__ const char* a(const pg8::Unit& u) const { return (const char*)ws + aoff + (size_t)u.pm * 256 * K_ * 2 + (u.kq < 0 ? 0 : u.kq * (K_ / 4) * 2); }
;     __device__ __forceinline__ const char* b(const pg8::Unit& u) const { return (const char*)ws + boff + (size_t)u.pn * 256 * K_ * 2 + (u.kq < 0 ? 0 : u.kq * (K_ / 4) * 2); }
.LBB0_961:
	s_xor_b64 s[36:37], s[4:5], -1
	s_cmp_gt_i32 s48, -1
	s_cselect_b64 s[50:51], -1, 0
	s_cmp_lt_i32 s48, 0
	s_cselect_b32 s45, 32, 8
	s_max_i32 s17, s75, 0
	s_ashr_i32 s35, s34, 31
	s_lshl_b32 s17, s17, 10
	s_lshl_b64 s[38:39], s[34:35], 20
	v_readlane_b32 s27, v254, 19
	s_add_u32 s27, s27, s38
	v_readlane_b32 s31, v254, 20
	s_addc_u32 s31, s31, s39
	s_add_u32 s38, s27, s17
	s_addc_u32 s39, s31, 0
	s_and_b64 s[40:41], s[4:5], exec
	s_cselect_b32 s35, s39, s95
	s_cselect_b32 s47, s38, s94
	s_ashr_i32 s31, s30, 31
	s_lshl_b64 s[40:41], s[30:31], 20
	s_add_u32 s27, s6, s40
	s_addc_u32 s31, s7, s41
	s_add_u32 s40, s27, s17
	s_addc_u32 s41, s31, 0
	s_and_b64 s[4:5], s[4:5], exec
	s_cselect_b32 s4, s41, s97
	s_cselect_b32 s5, s40, s96
	s_add_i32 s31, s45, -2
	s_add_u32 s94, s94, 0x80
	s_addc_u32 s95, s95, 0
	s_add_u32 s49, s96, 0x100
	s_mov_b32 s77, 0
	s_addc_u32 s76, s97, 0
	s_add_i32 s78, s77, 2
	s_add_u32 s17, s94, 0x80
	s_addc_u32 s27, s95, 0
	s_add_i32 s79, 0, 0x10000
	s_cmp_eq_u32 s31, s77
	s_cselect_b32 s97, s35, s27
	s_cselect_b32 s96, s47, s17
	v_add_u32_e32 v141, s79, v135
	s_cselect_b32 s43, s4, s76
	s_cselect_b32 s42, s5, s49
	s_add_i32 s17, 0, 0x14000
	ds_read_b128 v[156:159], v141
	ds_read_b128 v[160:163], v141 offset:1024
	ds_read_b128 v[164:167], v141 offset:2048
	ds_read_b128 v[168:171], v141 offset:3072
	v_add_u32_e32 v141, s17, v135
	ds_read_b128 v[172:175], v141
	ds_read_b128 v[180:183], v141 offset:1024
	ds_read_b128 v[184:187], v141 offset:2048
	ds_read_b128 v[188:191], v141 offset:3072
	v_lshl_add_u64 v[224:225], s[94:95], 0, v[152:153]
	s_add_i32 m0, s16, 0xc000
	ds_read_b128 v[192:195], v139
	ds_read_b128 v[196:199], v139 offset:1024
	ds_read_b128 v[200:203], v139 offset:2048
	ds_read_b128 v[204:207], v139 offset:3072
	ds_read_b128 v[208:211], v139 offset:4096
	ds_read_b128 v[212:215], v139 offset:5120
	ds_read_b128 v[216:219], v139 offset:6144
	ds_read_b128 v[220:223], v139 offset:7168
	global_load_lds_dwordx4 v[224:225], off
	v_lshl_add_u64 v[224:225], s[94:95], 0, v[154:155]
	s_add_i32 m0, s16, 0xe000
	s_nop 0
	global_load_lds_dwordx4 v[224:225], off
	s_waitcnt vmcnt(8)
	s_waitcnt lgkmcnt(0)
	s_barrier
	s_setprio 0
	s_waitcnt lgkmcnt(0)
	v_mfma_f32_16x16x32_bf16 v[124:127], v[156:159], v[192:195], 0
	v_mfma_f32_16x16x32_bf16 v[120:123], v[164:167], v[192:195], 0
	v_mfma_f32_16x16x32_bf16 v[116:119], v[156:159], v[200:203], 0
	v_mfma_f32_16x16x32_bf16 v[112:115], v[164:167], v[200:203], 0
	v_mfma_f32_16x16x32_bf16 v[100:103], v[156:159], v[208:211], 0
	v_mfma_f32_16x16x32_bf16 v[96:99], v[164:167], v[208:211], 0
	v_mfma_f32_16x16x32_bf16 v[84:87], v[156:159], v[216:219], 0
	v_mfma_f32_16x16x32_bf16 v[80:83], v[164:167], v[216:219], 0
	v_mfma_f32_16x16x32_bf16 v[124:127], v[160:163], v[196:199], v[124:127]
	v_mfma_f32_16x16x32_bf16 v[120:123], v[168:171], v[196:199], v[120:123]
	v_mfma_f32_16x16x32_bf16 v[116:119], v[160:163], v[204:207], v[116:119]
	v_mfma_f32_16x16x32_bf16 v[112:115], v[168:171], v[204:207], v[112:115]
	v_mfma_f32_16x16x32_bf16 v[100:103], v[160:163], v[212:215], v[100:103]
	v_mfma_f32_16x16x32_bf16 v[96:99], v[168:171], v[212:215], v[96:99]
	v_mfma_f32_16x16x32_bf16 v[84:87], v[160:163], v[220:223], v[84:87]
	v_mfma_f32_16x16x32_bf16 v[80:83], v[168:171], v[220:223], v[80:83]
	v_mfma_f32_16x16x32_bf16 v[108:111], v[172:175], v[192:195], 0
	v_mfma_f32_16x16x32_bf16 v[104:107], v[184:187], v[192:195], 0
	v_mfma_f32_16x16x32_bf16 v[92:95], v[172:175], v[200:203], 0
	v_mfma_f32_16x16x32_bf16 v[88:91], v[184:187], v[200:203], 0
	v_mfma_f32_16x16x32_bf16 v[76:79], v[172:175], v[208:211], 0
	v_mfma_f32_16x16x32_bf16 v[72:75], v[184:187], v[208:211], 0
	v_mfma_f32_16x16x32_bf16 v[68:71], v[172:175], v[216:219], 0
	v_mfma_f32_16x16x32_bf16 v[64:67], v[184:187], v[216:219], 0
	v_mfma_f32_16x16x32_bf16 v[108:111], v[180:183], v[196:199], v[108:111]
	v_mfma_f32_16x16x32_bf16 v[104:107], v[188:191], v[196:199], v[104:107]
	v_mfma_f32_16x16x32_bf16 v[92:95], v[180:183], v[204:207], v[92:95]
	v_mfma_f32_16x16x32_bf16 v[88:91], v[188:191], v[204:207], v[88:91]
	v_mfma_f32_16x16x32_bf16 v[76:79], v[180:183], v[212:215], v[76:79]
	v_mfma_f32_16x16x32_bf16 v[72:75], v[188:191], v[212:215], v[72:75]
	v_mfma_f32_16x16x32_bf16 v[68:71], v[180:183], v[220:223], v[68:71]
	v_mfma_f32_16x16x32_bf16 v[64:67], v[188:191], v[220:223], v[64:67]
	s_barrier
	s_add_i32 s27, s79, s3
	v_lshl_add_u64 v[224:225], s[42:43], 0, v[176:177]
	s_mov_b32 m0, s27
	ds_read_b128 v[192:195], v139 offset:16384
	ds_read_b128 v[196:199], v139 offset:17408
	ds_read_b128 v[200:203], v139 offset:18432
	ds_read_b128 v[204:207], v139 offset:19456
	ds_read_b128 v[208:211], v139 offset:20480
	ds_read_b128 v[212:215], v139 offset:21504
	ds_read_b128 v[216:219], v139 offset:22528
	ds_read_b128 v[220:223], v139 offset:23552
	global_load_lds_dwordx4 v[224:225], off
	s_add_i32 m0, s27, 0x2000
	v_lshl_add_u64 v[226:227], s[42:43], 0, v[128:129]
	s_add_u32 s42, s42, s10
	s_addc_u32 s43, s43, s11
	s_add_i32 s17, s17, s3
	global_load_lds_dwordx4 v[226:227], off
	v_lshl_add_u64 v[228:229], s[42:43], 0, v[176:177]
	s_mov_b32 m0, s17
	v_lshl_add_u64 v[230:231], s[42:43], 0, v[128:129]
	global_load_lds_dwordx4 v[228:229], off
	s_add_i32 m0, s17, 0x2000
	v_lshl_add_u64 v[232:233], s[96:97], 0, v[132:133]
	global_load_lds_dwordx4 v[230:231], off
	s_mov_b32 m0, s16
	v_lshl_add_u64 v[234:235], s[96:97], 0, v[130:131]
	global_load_lds_dwordx4 v[232:233], off
	s_mov_b32 m0, s14
	s_nop 0
	global_load_lds_dwordx4 v[234:235], off
	s_waitcnt vmcnt(8)
	s_waitcnt lgkmcnt(0)
	s_barrier
; #define PG8_STAGE(bufoff, gbase, voff) do { _Pragma("unroll") for (int _i = 0; _i < 2; ++_i) \
;         __builtin_amdgcn_global_load_lds((const unsigned*)((const char*)(gbase) + (voff)[_i]), (LAS unsigned*)(lds + (bufoff) + ldsw + _i * 8192), 16, 0, 0); } while (0)
; #define PG8_LDA(dst, b, h) do { _Pragma("unroll") for (int m = 0; m < 4; ++m) _Pragma("unroll") for (int k = 0; k < 2; ++k) dst[m][k] = *(const LAS bf16x8*)(lds + PG8_SA(b, h) + aoff + m * 2048 + k * 1024); } while (0)
; #define PG8_LDB(dst, b, h) do { _Pragma("unroll") for (int n = 0; n < 2; ++n) _Pragma("unroll") for (int k = 0; k < 2; ++k) dst[n][k] = *(const LAS bf16x8*)(lds + PG8_SB(b, h) + boff + n * 2048 + k * 1024); } while (0)
; #define PG8_MMA(ai, bj, At, Bt) do { __builtin_amdgcn_s_setprio(1); _Pragma("unroll") for (int m = 0; m < 4; ++m) _Pragma("unroll") for (int n = 0; n < 2; ++n) _Pragma("unroll") for (int k = 0; k < 2; ++k) \
;         acc[ai][bj][m][n] = __builtin_amdgcn_mfma_f32_16x16x32_bf16(Bt[n][k], At[m][k], acc[ai][bj][m][n], 0, 0, 0); __builtin_amdgcn_s_setprio(0); } while (0)
; #define PG8_WAIT_V(n) asm volatile("s_waitcnt vmcnt(" #n ")" ::: "memory")
; #define PG8_WAIT_L(n) asm volatile("s_waitcnt lgkmcnt(" #n ")" ::: "memory")
; #define PG8_BAR __builtin_amdgcn_s_barrier()
; #define PG8_SCHED __builtin_amdgcn_sched_barrier(0)
; template <class Epi, class Sched, bool ALIGN_EPI>
; __device__ __forceinline__ void gemm_phase(LAS unsigned char* lds, const int wid, const int lda_, const int ldb_, const int K_, const Sched& S, const Epi& E) {
;     ...
;             PG8_LDB(B0, 0, 0); PG8_LDB(B1, 0, 1); PG8_SCHED; PG8_LDA(At, 0, 0); PG8_STAGE(PG8_SA(1, 1), a1 + hstepA, voffA);
;             PG8_WAIT_V(8); PG8_WAIT_L(0); PG8_BAR; PG8_MMA(0, 0, At, B0); PG8_MMA(0, 1, At, B1); PG8_BAR; PG8_SCHED;
;             PG8_LDA(At, 0, 1); PG8_STAGE(PG8_SB(0, 0), b2, voffB); PG8_STAGE(PG8_SB(0, 1), b2 + hstepB, voffB); PG8_STAGE(PG8_SA(0, 0), a2, voffA);
;             PG8_WAIT_V(8); PG8_WAIT_L(0); PG8_BAR; PG8_MMA(1, 0, At, B0); PG8_MMA(1, 1, At, B1); PG8_BAR; PG8_SCHED;
	s_waitcnt lgkmcnt(0)
	v_mfma_f32_16x16x32_bf16 v[60:63], v[156:159], v[192:195], 0
	v_mfma_f32_16x16x32_bf16 v[56:59], v[164:167], v[192:195], 0
	v_mfma_f32_16x16x32_bf16 v[52:55], v[156:159], v[200:203], 0
	v_mfma_f32_16x16x32_bf16 v[48:51], v[164:167], v[200:203], 0
	v_mfma_f32_16x16x32_bf16 v[36:39], v[156:159], v[208:211], 0
	v_mfma_f32_16x16x32_bf16 v[32:35], v[164:167], v[208:211], 0
	v_mfma_f32_16x16x32_bf16 v[20:23], v[156:159], v[216:219], 0
	v_mfma_f32_16x16x32_bf16 v[16:19], v[164:167], v[216:219], 0
	v_mfma_f32_16x16x32_bf16 v[60:63], v[160:163], v[196:199], v[60:63]
	v_mfma_f32_16x16x32_bf16 v[56:59], v[168:171], v[196:199], v[56:59]
	v_mfma_f32_16x16x32_bf16 v[52:55], v[160:163], v[204:207], v[52:55]
	v_mfma_f32_16x16x32_bf16 v[48:51], v[168:171], v[204:207], v[48:51]
	v_mfma_f32_16x16x32_bf16 v[36:39], v[160:163], v[212:215], v[36:39]
	v_mfma_f32_16x16x32_bf16 v[32:35], v[168:171], v[212:215], v[32:35]
	v_mfma_f32_16x16x32_bf16 v[20:23], v[160:163], v[220:223], v[20:23]
	v_mfma_f32_16x16x32_bf16 v[16:19], v[168:171], v[220:223], v[16:19]
	v_mfma_f32_16x16x32_bf16 v[44:47], v[172:175], v[192:195], 0
	v_mfma_f32_16x16x32_bf16 v[40:43], v[184:187], v[192:195], 0
	v_mfma_f32_16x16x32_bf16 v[28:31], v[172:175], v[200:203], 0
	v_mfma_f32_16x16x32_bf16 v[24:27], v[184:187], v[200:203], 0
	v_mfma_f32_16x16x32_bf16 v[12:15], v[172:175], v[208:211], 0
	v_mfma_f32_16x16x32_bf16 v[8:11], v[184:187], v[208:211], 0
	v_mfma_f32_16x16x32_bf16 v[4:7], v[172:175], v[216:219], 0
	v_mfma_f32_16x16x32_bf16 v[0:3], v[184:187], v[216:219], 0
	v_mfma_f32_16x16x32_bf16 v[44:47], v[180:183], v[196:199], v[44:47]
	v_mfma_f32_16x16x32_bf16 v[40:43], v[188:191], v[196:199], v[40:43]
	v_mfma_f32_16x16x32_bf16 v[28:31], v[180:183], v[204:207], v[28:31]
	v_mfma_f32_16x16x32_bf16 v[24:27], v[188:191], v[204:207], v[24:27]
	v_mfma_f32_16x16x32_bf16 v[12:15], v[180:183], v[212:215], v[12:15]
	v_mfma_f32_16x16x32_bf16 v[8:11], v[188:191], v[212:215], v[8:11]
	v_mfma_f32_16x16x32_bf16 v[4:7], v[180:183], v[220:223], v[4:7]
	v_mfma_f32_16x16x32_bf16 v[0:3], v[188:191], v[220:223], v[0:3]
	s_barrier
	s_branch .Lgemm_join_962
.LBB0_962:
	s_add_i32 s78, s77, 2
	s_add_u32 s17, s94, 0x80
	s_addc_u32 s27, s95, 0
	s_add_i32 s79, 0, 0x10000
	s_cmp_eq_u32 s31, s77
	s_cselect_b32 s97, s35, s27
	s_cselect_b32 s96, s47, s17
	v_add_u32_e32 v141, s79, v135
	s_cselect_b32 s43, s4, s76
	s_cselect_b32 s42, s5, s49
	s_add_i32 s17, 0, 0x14000
	ds_read_b128 v[156:159], v141
	ds_read_b128 v[160:163], v141 offset:1024
	ds_read_b128 v[164:167], v141 offset:2048
	ds_read_b128 v[168:171], v141 offset:3072
	v_add_u32_e32 v141, s17, v135
	ds_read_b128 v[172:175], v141
	ds_read_b128 v[180:183], v141 offset:1024
	ds_read_b128 v[184:187], v141 offset:2048
	ds_read_b128 v[188:191], v141 offset:3072
	v_lshl_add_u64 v[224:225], s[94:95], 0, v[152:153]
	s_add_i32 m0, s16, 0xc000
	ds_read_b128 v[192:195], v139
	ds_read_b128 v[196:199], v139 offset:1024
	ds_read_b128 v[200:203], v139 offset:2048
	ds_read_b128 v[204:207], v139 offset:3072
	ds_read_b128 v[208:211], v139 offset:4096
	ds_read_b128 v[212:215], v139 offset:5120
	ds_read_b128 v[216:219], v139 offset:6144
	ds_read_b128 v[220:223], v139 offset:7168
	global_load_lds_dwordx4 v[224:225], off
	v_lshl_add_u64 v[224:225], s[94:95], 0, v[154:155]
	s_add_i32 m0, s16, 0xe000
	s_nop 0
	global_load_lds_dwordx4 v[224:225], off
	s_waitcnt vmcnt(8)
	s_waitcnt lgkmcnt(0)
	s_barrier
	s_waitcnt lgkmcnt(0)
	v_mfma_f32_16x16x32_bf16 v[124:127], v[156:159], v[192:195], v[124:127]
	v_mfma_f32_16x16x32_bf16 v[120:123], v[164:167], v[192:195], v[120:123]
	v_mfma_f32_16x16x32_bf16 v[116:119], v[156:159], v[200:203], v[116:119]
	v_mfma_f32_16x16x32_bf16 v[112:115], v[164:167], v[200:203], v[112:115]
	v_mfma_f32_16x16x32_bf16 v[100:103], v[156:159], v[208:211], v[100:103]
	v_mfma_f32_16x16x32_bf16 v[96:99], v[164:167], v[208:211], v[96:99]
	v_mfma_f32_16x16x32_bf16 v[84:87], v[156:159], v[216:219], v[84:87]
	v_mfma_f32_16x16x32_bf16 v[80:83], v[164:167], v[216:219], v[80:83]
	v_mfma_f32_16x16x32_bf16 v[124:127], v[160:163], v[196:199], v[124:127]
	v_mfma_f32_16x16x32_bf16 v[120:123], v[168:171], v[196:199], v[120:123]
	v_mfma_f32_16x16x32_bf16 v[116:119], v[160:163], v[204:207], v[116:119]
	v_mfma_f32_16x16x32_bf16 v[112:115], v[168:171], v[204:207], v[112:115]
	v_mfma_f32_16x16x32_bf16 v[100:103], v[160:163], v[212:215], v[100:103]
	v_mfma_f32_16x16x32_bf16 v[96:99], v[168:171], v[212:215], v[96:99]
	v_mfma_f32_16x16x32_bf16 v[84:87], v[160:163], v[220:223], v[84:87]
	v_mfma_f32_16x16x32_bf16 v[80:83], v[168:171], v[220:223], v[80:83]
	v_mfma_f32_16x16x32_bf16 v[108:111], v[172:175], v[192:195], v[108:111]
	v_mfma_f32_16x16x32_bf16 v[104:107], v[184:187], v[192:195], v[104:107]
	v_mfma_f32_16x16x32_bf16 v[92:95], v[172:175], v[200:203], v[92:95]
	v_mfma_f32_16x16x32_bf16 v[88:91], v[184:187], v[200:203], v[88:91]
	v_mfma_f32_16x16x32_bf16 v[76:79], v[172:175], v[208:211], v[76:79]
	v_mfma_f32_16x16x32_bf16 v[72:75], v[184:187], v[208:211], v[72:75]
	v_mfma_f32_16x16x32_bf16 v[68:71], v[172:175], v[216:219], v[68:71]
	v_mfma_f32_16x16x32_bf16 v[64:67], v[184:187], v[216:219], v[64:67]
	v_mfma_f32_16x16x32_bf16 v[108:111], v[180:183], v[196:199], v[108:111]
	v_mfma_f32_16x16x32_bf16 v[104:107], v[188:191], v[196:199], v[104:107]
	v_mfma_f32_16x16x32_bf16 v[92:95], v[180:183], v[204:207], v[92:95]
	v_mfma_f32_16x16x32_bf16 v[88:91], v[188:191], v[204:207], v[88:91]
	v_mfma_f32_16x16x32_bf16 v[76:79], v[180:183], v[212:215], v[76:79]
	v_mfma_f32_16x16x32_bf16 v[72:75], v[188:191], v[212:215], v[72:75]
	v_mfma_f32_16x16x32_bf16 v[68:71], v[180:183], v[220:223], v[68:71]
	v_mfma_f32_16x16x32_bf16 v[64:67], v[188:191], v[220:223], v[64:67]
	s_barrier
; #define PG8_STAGE(bufoff, gbase, voff) do { _Pragma("unroll") for (int _i = 0; _i < 2; ++_i) \
;         __builtin_amdgcn_global_load_lds((const unsigned*)((const char*)(gbase) + (voff)[_i]), (LAS unsigned*)(lds + (bufoff) + ldsw + _i * 8192), 16, 0, 0); } while (0)
; #define PG8_LDA(dst, b, h) do { _Pragma("unroll") for (int m = 0; m < 4; ++m) _Pragma("unroll") for (int k = 0; k < 2; ++k) dst[m][k] = *(const LAS bf16x8*)(lds + PG8_SA(b, h) + aoff + m * 2048 + k * 1024); } while (0)
; #define PG8_LDB(dst, b, h) do { _Pragma("unroll") for (int n = 0; n < 2; ++n) _Pragma("unroll") for (int k = 0; k < 2; ++k) dst[n][k] = *(const LAS bf16x8*)(lds + PG8_SB(b, h) + boff + n * 2048 + k * 1024); } while (0)
; #define PG8_MMA(ai, bj, At, Bt) do { __builtin_amdgcn_s_setprio(1); _Pragma("unroll") for (int m = 0; m < 4; ++m) _Pragma("unroll") for (int n = 0; n < 2; ++n) _Pragma("unroll") for (int k = 0; k < 2; ++k) \
;         acc[ai][bj][m][n] = __builtin_amdgcn_mfma_f32_16x16x32_bf16(Bt[n][k], At[m][k], acc[ai][bj][m][n], 0, 0, 0); __builtin_amdgcn_s_setprio(0); } while (0)
; #define PG8_WAIT_V(n) asm volatile("s_waitcnt vmcnt(" #n ")" ::: "memory")
; #define PG8_WAIT_L(n) asm volatile("s_waitcnt lgkmcnt(" #n ")" ::: "memory")
; #define PG8_BAR __builtin_amdgcn_s_barrier()
; #define PG8_SCHED __builtin_amdgcn_sched_barrier(0)
; template <class Epi, class Sched, bool ALIGN_EPI>
; __device__ __forceinline__ void gemm_phase(LAS unsigned char* lds, const int wid, const int lda_, const int ldb_, const int K_, const Sched& S, const Epi& E) {
;     ...
;             PG8_LDA(At, 0, 1); PG8_STAGE(PG8_SB(0, 0), b2, voffB); PG8_STAGE(PG8_SB(0, 1), b2 + hstepB, voffB); PG8_STAGE(PG8_SA(0, 0), a2, voffA);
;             PG8_WAIT_V(8); PG8_WAIT_L(0); PG8_BAR; PG8_MMA(1, 0, At, B0); PG8_MMA(1, 1, At, B1); PG8_BAR; PG8_SCHED;
;             PG8_LDB(B0, 1, 0); PG8_LDB(B1, 1, 1); PG8_SCHED; PG8_LDA(At, 1, 0); PG8_STAGE(PG8_SA(0, 1), a2 + hstepA, voffA);
	s_add_i32 s27, s79, s3
	v_lshl_add_u64 v[224:225], s[42:43], 0, v[176:177]
	s_mov_b32 m0, s27
	ds_read_b128 v[192:195], v139 offset:16384
	ds_read_b128 v[196:199], v139 offset:17408
	ds_read_b128 v[200:203], v139 offset:18432
	ds_read_b128 v[204:207], v139 offset:19456
	ds_read_b128 v[208:211], v139 offset:20480
	ds_read_b128 v[212:215], v139 offset:21504
	ds_read_b128 v[216:219], v139 offset:22528
	ds_read_b128 v[220:223], v139 offset:23552
	global_load_lds_dwordx4 v[224:225], off
	s_add_i32 m0, s27, 0x2000
	v_lshl_add_u64 v[226:227], s[42:43], 0, v[128:129]
	s_add_u32 s42, s42, s10
	s_addc_u32 s43, s43, s11
	s_add_i32 s17, s17, s3
	global_load_lds_dwordx4 v[226:227], off
	v_lshl_add_u64 v[228:229], s[42:43], 0, v[176:177]
	s_mov_b32 m0, s17
	v_lshl_add_u64 v[230:231], s[42:43], 0, v[128:129]
	global_load_lds_dwordx4 v[228:229], off
	s_add_i32 m0, s17, 0x2000
	v_lshl_add_u64 v[232:233], s[96:97], 0, v[132:133]
	global_load_lds_dwordx4 v[230:231], off
	s_mov_b32 m0, s16
	v_lshl_add_u64 v[234:235], s[96:97], 0, v[130:131]
	global_load_lds_dwordx4 v[232:233], off
	s_mov_b32 m0, s14
	s_nop 0
	global_load_lds_dwordx4 v[234:235], off
	s_waitcnt vmcnt(8)
	s_waitcnt lgkmcnt(0)
	s_barrier
	s_waitcnt lgkmcnt(0)
	v_mfma_f32_16x16x32_bf16 v[60:63], v[156:159], v[192:195], v[60:63]
	v_mfma_f32_16x16x32_bf16 v[56:59], v[164:167], v[192:195], v[56:59]
	v_mfma_f32_16x16x32_bf16 v[52:55], v[156:159], v[200:203], v[52:55]
	v_mfma_f32_16x16x32_bf16 v[48:51], v[164:167], v[200:203], v[48:51]
	v_mfma_f32_16x16x32_bf16 v[36:39], v[156:159], v[208:211], v[36:39]
	v_mfma_f32_16x16x32_bf16 v[32:35], v[164:167], v[208:211], v[32:35]
	v_mfma_f32_16x16x32_bf16 v[20:23], v[156:159], v[216:219], v[20:23]
	v_mfma_f32_16x16x32_bf16 v[16:19], v[164:167], v[216:219], v[16:19]
	v_mfma_f32_16x16x32_bf16 v[60:63], v[160:163], v[196:199], v[60:63]
	v_mfma_f32_16x16x32_bf16 v[56:59], v[168:171], v[196:199], v[56:59]
	v_mfma_f32_16x16x32_bf16 v[52:55], v[160:163], v[204:207], v[52:55]
	v_mfma_f32_16x16x32_bf16 v[48:51], v[168:171], v[204:207], v[48:51]
	v_mfma_f32_16x16x32_bf16 v[36:39], v[160:163], v[212:215], v[36:39]
	v_mfma_f32_16x16x32_bf16 v[32:35], v[168:171], v[212:215], v[32:35]
	v_mfma_f32_16x16x32_bf16 v[20:23], v[160:163], v[220:223], v[20:23]
	v_mfma_f32_16x16x32_bf16 v[16:19], v[168:171], v[220:223], v[16:19]
	v_mfma_f32_16x16x32_bf16 v[44:47], v[172:175], v[192:195], v[44:47]
	v_mfma_f32_16x16x32_bf16 v[40:43], v[184:187], v[192:195], v[40:43]
	v_mfma_f32_16x16x32_bf16 v[28:31], v[172:175], v[200:203], v[28:31]
	v_mfma_f32_16x16x32_bf16 v[24:27], v[184:187], v[200:203], v[24:27]
	v_mfma_f32_16x16x32_bf16 v[12:15], v[172:175], v[208:211], v[12:15]
	v_mfma_f32_16x16x32_bf16 v[8:11], v[184:187], v[208:211], v[8:11]
	v_mfma_f32_16x16x32_bf16 v[4:7], v[172:175], v[216:219], v[4:7]
	v_mfma_f32_16x16x32_bf16 v[0:3], v[184:187], v[216:219], v[0:3]
	v_mfma_f32_16x16x32_bf16 v[44:47], v[180:183], v[196:199], v[44:47]
	v_mfma_f32_16x16x32_bf16 v[40:43], v[188:191], v[196:199], v[40:43]
	v_mfma_f32_16x16x32_bf16 v[28:31], v[180:183], v[204:207], v[28:31]
	v_mfma_f32_16x16x32_bf16 v[24:27], v[188:191], v[204:207], v[24:27]
	v_mfma_f32_16x16x32_bf16 v[12:15], v[180:183], v[212:215], v[12:15]
	v_mfma_f32_16x16x32_bf16 v[8:11], v[188:191], v[212:215], v[8:11]
	v_mfma_f32_16x16x32_bf16 v[4:7], v[180:183], v[220:223], v[4:7]
	v_mfma_f32_16x16x32_bf16 v[0:3], v[188:191], v[220:223], v[0:3]
	s_barrier
.Lgemm_join_962:
	s_add_i32 s17, 0, 0x18000
	v_add_u32_e32 v141, s17, v135
	s_add_i32 s27, 0, 0x1c000
	ds_read_b128 v[156:159], v141
	ds_read_b128 v[160:163], v141 offset:1024
	ds_read_b128 v[164:167], v141 offset:2048
	ds_read_b128 v[168:171], v141 offset:3072
	v_add_u32_e32 v141, s27, v135
	ds_read_b128 v[172:175], v141
	ds_read_b128 v[180:183], v141 offset:1024
	ds_read_b128 v[184:187], v141 offset:2048
	ds_read_b128 v[188:191], v141 offset:3072
	s_add_u32 s42, s96, s0
	s_addc_u32 s43, s97, s1
	s_mov_b32 m0, s15
	v_lshl_add_u64 v[236:237], s[42:43], 0, v[132:133]
	ds_read_b128 v[192:195], v139 offset:32768
	ds_read_b128 v[196:199], v139 offset:33792
	ds_read_b128 v[200:203], v139 offset:34816
	ds_read_b128 v[204:207], v139 offset:35840
	ds_read_b128 v[208:211], v139 offset:36864
	ds_read_b128 v[212:215], v139 offset:37888
	ds_read_b128 v[216:219], v139 offset:38912
	ds_read_b128 v[220:223], v139 offset:39936
	global_load_lds_dwordx4 v[236:237], off
	v_lshl_add_u64 v[236:237], s[42:43], 0, v[130:131]
	s_mov_b32 m0, s26
	s_nop 0
	global_load_lds_dwordx4 v[236:237], off
	s_waitcnt vmcnt(8)
	s_waitcnt lgkmcnt(0)
	s_barrier
; #define PG8_STAGE(bufoff, gbase, voff) do { _Pragma("unroll") for (int _i = 0; _i < 2; ++_i) \
;         __builtin_amdgcn_global_load_lds((const unsigned*)((const char*)(gbase) + (voff)[_i]), (LAS unsigned*)(lds + (bufoff) + ldsw + _i * 8192), 16, 0, 0); } while (0)
; #define PG8_LDA(dst, b, h) do { _Pragma("unroll") for (int m = 0; m < 4; ++m) _Pragma("unroll") for (int k = 0; k < 2; ++k) dst[m][k] = *(const LAS bf16x8*)(lds + PG8_SA(b, h) + aoff + m * 2048 + k * 1024); } while (0)
; #define PG8_MMA(ai, bj, At, Bt) do { __builtin_amdgcn_s_setprio(1); _Pragma("unroll") for (int m = 0; m < 4; ++m) _Pragma("unroll") for (int n = 0; n < 2; ++n) _Pragma("unroll") for (int k = 0; k < 2; ++k) \
;         acc[ai][bj][m][n] = __builtin_amdgcn_mfma_f32_16x16x32_bf16(Bt[n][k], At[m][k], acc[ai][bj][m][n], 0, 0, 0); __builtin_amdgcn_s_setprio(0); } while (0)
; #define PG8_WAIT_V(n) asm volatile("s_waitcnt vmcnt(" #n ")" ::: "memory")
; #define PG8_WAIT_L(n) asm volatile("s_waitcnt lgkmcnt(" #n ")" ::: "memory")
; #define PG8_BAR __builtin_amdgcn_s_barrier()
; #define PG8_SCHED __builtin_amdgcn_sched_barrier(0)
; template <class Epi, class Sched, bool ALIGN_EPI>
; __device__ __forceinline__ void gemm_phase(LAS unsigned char* lds, const int wid, const int lda_, const int ldb_, const int K_, const Sched& S, const Epi& E) {
;     ...
;             PG8_WAIT_V(8); PG8_WAIT_L(0); PG8_BAR; PG8_MMA(0, 0, At, B0); PG8_MMA(0, 1, At, B1); PG8_BAR; PG8_SCHED;
;             PG8_LDA(At, 1, 1); PG8_STAGE(PG8_SB(1, 0), b3, voffB); PG8_STAGE(PG8_SB(1, 1), b3 + hstepB, voffB); PG8_STAGE(PG8_SA(1, 0), a3, voffA);
;             PG8_WAIT_V(8); PG8_WAIT_L(0); PG8_BAR; PG8_MMA(1, 0, At, B0); PG8_MMA(1, 1, At, B1); PG8_BAR; PG8_SCHED;
;     __device__ __forceinline__ void out(const pg8::Unit& u, char*& o, int& ldo, int& kind) const { ldo = D;
;     ...
;         else { o = (char*)ws + WS_PART + (((size_t)u.kq * MCTX + (size_t)(u.pm - 64) * 256) * D + (size_t)u.pn * 256) * 2; kind = 0; } }
	s_waitcnt lgkmcnt(0)
	v_mfma_f32_16x16x32_bf16 v[124:127], v[156:159], v[192:195], v[124:127]
	v_mfma_f32_16x16x32_bf16 v[120:123], v[164:167], v[192:195], v[120:123]
	v_mfma_f32_16x16x32_bf16 v[116:119], v[156:159], v[200:203], v[116:119]
	v_mfma_f32_16x16x32_bf16 v[112:115], v[164:167], v[200:203], v[112:115]
	v_mfma_f32_16x16x32_bf16 v[100:103], v[156:159], v[208:211], v[100:103]
	v_mfma_f32_16x16x32_bf16 v[96:99], v[164:167], v[208:211], v[96:99]
	v_mfma_f32_16x16x32_bf16 v[84:87], v[156:159], v[216:219], v[84:87]
	v_mfma_f32_16x16x32_bf16 v[80:83], v[164:167], v[216:219], v[80:83]
	v_mfma_f32_16x16x32_bf16 v[124:127], v[160:163], v[196:199], v[124:127]
	v_mfma_f32_16x16x32_bf16 v[120:123], v[168:171], v[196:199], v[120:123]
	v_mfma_f32_16x16x32_bf16 v[116:119], v[160:163], v[204:207], v[116:119]
	v_mfma_f32_16x16x32_bf16 v[112:115], v[168:171], v[204:207], v[112:115]
	v_mfma_f32_16x16x32_bf16 v[100:103], v[160:163], v[212:215], v[100:103]
	v_mfma_f32_16x16x32_bf16 v[96:99], v[168:171], v[212:215], v[96:99]
	v_mfma_f32_16x16x32_bf16 v[84:87], v[160:163], v[220:223], v[84:87]
	v_mfma_f32_16x16x32_bf16 v[80:83], v[168:171], v[220:223], v[80:83]
	v_mfma_f32_16x16x32_bf16 v[108:111], v[172:175], v[192:195], v[108:111]
	v_mfma_f32_16x16x32_bf16 v[104:107], v[184:187], v[192:195], v[104:107]
	v_mfma_f32_16x16x32_bf16 v[92:95], v[172:175], v[200:203], v[92:95]
	v_mfma_f32_16x16x32_bf16 v[88:91], v[184:187], v[200:203], v[88:91]
	v_mfma_f32_16x16x32_bf16 v[76:79], v[172:175], v[208:211], v[76:79]
	v_mfma_f32_16x16x32_bf16 v[72:75], v[184:187], v[208:211], v[72:75]
	v_mfma_f32_16x16x32_bf16 v[68:71], v[172:175], v[216:219], v[68:71]
	v_mfma_f32_16x16x32_bf16 v[64:67], v[184:187], v[216:219], v[64:67]
	v_mfma_f32_16x16x32_bf16 v[108:111], v[180:183], v[196:199], v[108:111]
	v_mfma_f32_16x16x32_bf16 v[104:107], v[188:191], v[196:199], v[104:107]
	v_mfma_f32_16x16x32_bf16 v[92:95], v[180:183], v[204:207], v[92:95]
	v_mfma_f32_16x16x32_bf16 v[88:91], v[188:191], v[204:207], v[88:91]
	v_mfma_f32_16x16x32_bf16 v[76:79], v[180:183], v[212:215], v[76:79]
	v_mfma_f32_16x16x32_bf16 v[72:75], v[188:191], v[212:215], v[72:75]
	v_mfma_f32_16x16x32_bf16 v[68:71], v[180:183], v[220:223], v[68:71]
	v_mfma_f32_16x16x32_bf16 v[64:67], v[188:191], v[220:223], v[64:67]
	s_barrier
	s_add_i32 s17, s17, s3
	v_lshl_add_u64 v[224:225], v[224:225], 0, s[24:25]
	s_mov_b32 m0, s17
	ds_read_b128 v[192:195], v139 offset:49152
	ds_read_b128 v[196:199], v139 offset:50176
	ds_read_b128 v[200:203], v139 offset:51200
	ds_read_b128 v[204:207], v139 offset:52224
	ds_read_b128 v[208:211], v139 offset:53248
	ds_read_b128 v[212:215], v139 offset:54272
	ds_read_b128 v[216:219], v139 offset:55296
	ds_read_b128 v[220:223], v139 offset:56320
	global_load_lds_dwordx4 v[224:225], off
	v_lshl_add_u64 v[224:225], v[226:227], 0, s[24:25]
	s_add_i32 m0, s17, 0x2000
	s_add_i32 s17, s27, s3
	global_load_lds_dwordx4 v[224:225], off
	v_lshl_add_u64 v[224:225], v[228:229], 0, s[24:25]
	s_mov_b32 m0, s17
	s_nop 0
	global_load_lds_dwordx4 v[224:225], off
	v_lshl_add_u64 v[224:225], v[230:231], 0, s[24:25]
	s_add_i32 m0, s17, 0x2000
	s_nop 0
	global_load_lds_dwordx4 v[224:225], off
	v_lshl_add_u64 v[224:225], v[232:233], 0, s[24:25]
	s_mov_b32 m0, s72
	s_nop 0
	global_load_lds_dwordx4 v[224:225], off
	v_lshl_add_u64 v[224:225], v[234:235], 0, s[24:25]
	s_mov_b32 m0, s73
	s_nop 0
	global_load_lds_dwordx4 v[224:225], off
	s_waitcnt vmcnt(8)
	s_waitcnt lgkmcnt(0)
	s_barrier
	s_waitcnt lgkmcnt(0)
	v_mfma_f32_16x16x32_bf16 v[60:63], v[156:159], v[192:195], v[60:63]
	v_mfma_f32_16x16x32_bf16 v[56:59], v[164:167], v[192:195], v[56:59]
	v_mfma_f32_16x16x32_bf16 v[52:55], v[156:159], v[200:203], v[52:55]
	v_mfma_f32_16x16x32_bf16 v[48:51], v[164:167], v[200:203], v[48:51]
	v_mfma_f32_16x16x32_bf16 v[36:39], v[156:159], v[208:211], v[36:39]
	v_mfma_f32_16x16x32_bf16 v[32:35], v[164:167], v[208:211], v[32:35]
	v_mfma_f32_16x16x32_bf16 v[20:23], v[156:159], v[216:219], v[20:23]
	v_mfma_f32_16x16x32_bf16 v[16:19], v[164:167], v[216:219], v[16:19]
	v_mfma_f32_16x16x32_bf16 v[60:63], v[160:163], v[196:199], v[60:63]
	v_mfma_f32_16x16x32_bf16 v[56:59], v[168:171], v[196:199], v[56:59]
	v_mfma_f32_16x16x32_bf16 v[52:55], v[160:163], v[204:207], v[52:55]
	v_mfma_f32_16x16x32_bf16 v[48:51], v[168:171], v[204:207], v[48:51]
	v_mfma_f32_16x16x32_bf16 v[36:39], v[160:163], v[212:215], v[36:39]
	v_mfma_f32_16x16x32_bf16 v[32:35], v[168:171], v[212:215], v[32:35]
	v_mfma_f32_16x16x32_bf16 v[20:23], v[160:163], v[220:223], v[20:23]
	v_mfma_f32_16x16x32_bf16 v[16:19], v[168:171], v[220:223], v[16:19]
	v_mfma_f32_16x16x32_bf16 v[44:47], v[172:175], v[192:195], v[44:47]
	v_mfma_f32_16x16x32_bf16 v[40:43], v[184:187], v[192:195], v[40:43]
	v_mfma_f32_16x16x32_bf16 v[28:31], v[172:175], v[200:203], v[28:31]
	v_mfma_f32_16x16x32_bf16 v[24:27], v[184:187], v[200:203], v[24:27]
	v_mfma_f32_16x16x32_bf16 v[12:15], v[172:175], v[208:211], v[12:15]
	v_mfma_f32_16x16x32_bf16 v[8:11], v[184:187], v[208:211], v[8:11]
	v_mfma_f32_16x16x32_bf16 v[4:7], v[172:175], v[216:219], v[4:7]
	v_mfma_f32_16x16x32_bf16 v[0:3], v[184:187], v[216:219], v[0:3]
	v_mfma_f32_16x16x32_bf16 v[44:47], v[180:183], v[196:199], v[44:47]
	v_mfma_f32_16x16x32_bf16 v[40:43], v[188:191], v[196:199], v[40:43]
	v_mfma_f32_16x16x32_bf16 v[28:31], v[180:183], v[204:207], v[28:31]
	v_mfma_f32_16x16x32_bf16 v[24:27], v[188:191], v[204:207], v[24:27]
	v_mfma_f32_16x16x32_bf16 v[12:15], v[180:183], v[212:215], v[12:15]
	v_mfma_f32_16x16x32_bf16 v[8:11], v[188:191], v[212:215], v[8:11]
	v_mfma_f32_16x16x32_bf16 v[4:7], v[180:183], v[220:223], v[4:7]
	v_mfma_f32_16x16x32_bf16 v[0:3], v[188:191], v[220:223], v[0:3]
	s_barrier
	s_add_u32 s94, s94, 0x100
	s_addc_u32 s95, s95, 0
	s_add_u32 s49, s49, 0x100
	s_addc_u32 s76, s76, 0
	s_cmp_ge_u32 s78, s45
	s_mov_b32 s77, s78
	s_cbranch_scc0 .LBB0_962
	s_setprio 2
	s_mov_b64 s[94:95], -1
	s_and_b64 vcc, exec, s[50:51]
	s_cbranch_vccz .LBB0_965
	s_mov_b32 s49, s92
	s_ashr_i32 s47, s46, 31
	s_ashr_i32 s45, s44, 31
	s_lshl_b64 s[4:5], s[46:47], 20
	s_lshl_b64 s[42:43], s[44:45], 9
	s_lshl_b64 s[48:49], s[48:49], 23
	v_readlane_b32 s50, v251, 28
	v_readlane_b32 s51, v251, 29
	s_add_u32 s17, s50, s42
	s_addc_u32 s27, s51, s43
	s_add_u32 s17, s17, s48
	s_addc_u32 s27, s27, s49
	s_add_u32 s4, s17, s4
	s_addc_u32 s5, s27, s5
	s_add_u32 s4, s4, 0xfc000000
	s_addc_u32 s5, s5, -1
	s_mov_b64 s[94:95], 0

; #define PG8_STAGE(bufoff, gbase, voff) do { _Pragma("unroll") for (int _i = 0; _i < 2; ++_i) \
;         __builtin_amdgcn_global_load_lds((const unsigned*)((const char*)(gbase) + (voff)[_i]), (LAS unsigned*)(lds + (bufoff) + ldsw + _i * 8192), 16, 0, 0); } while (0)
; #define PG8_LDA(dst, b, h) do { _Pragma("unroll") for (int m = 0; m < 4; ++m) _Pragma("unroll") for (int k = 0; k < 2; ++k) dst[m][k] = *(const LAS bf16x8*)(lds + PG8_SA(b, h) + aoff + m * 2048 + k * 1024); } while (0)
; #define PG8_LDB(dst, b, h) do { _Pragma("unroll") for (int n = 0; n < 2; ++n) _Pragma("unroll") for (int k = 0; k < 2; ++k) dst[n][k] = *(const LAS bf16x8*)(lds + PG8_SB(b, h) + boff + n * 2048 + k * 1024); } while (0)
; #define PG8_MMA(ai, bj, At, Bt) do { __builtin_amdgcn_s_setprio(1); _Pragma("unroll") for (int m = 0; m < 4; ++m) _Pragma("unroll") for (int n = 0; n < 2; ++n) _Pragma("unroll") for (int k = 0; k < 2; ++k) \
;         acc[ai][bj][m][n] = __builtin_amdgcn_mfma_f32_16x16x32_bf16(Bt[n][k], At[m][k], acc[ai][bj][m][n], 0, 0, 0); __builtin_amdgcn_s_setprio(0); } while (0)
; template <class Epi, class Sched, bool ALIGN_EPI>
; __device__ __forceinline__ void gemm_phase(LAS unsigned char* lds, const int wid, const int lda_, const int ldb_, const int K_, const Sched& S, const Epi& E) {
;     ...
;         const bool has_next = S.next(ui + 1, nxt);
;         const int nt = S.nt(cur);
;         const char* nA = has_next ? S.a(nxt) : cA; const char* nB = has_next ? S.b(nxt) : cB;
; #pragma unroll 1
;         for (int t = 0; t < nt; t += 2) {
;             const bool last = (t == nt - 2);
;             const char* a1 = cA + (size_t)(t + 1) * kstep;
;             const char* a2 = last ? nA : cA + (size_t)(t + 2) * kstep; const char* b2 = last ? nB : cB + (size_t)(t + 2) * kstep;
;             const char* a3 = a2 + kstep; const char* b3 = b2 + kstep;
;             PG8_LDB(B0, 0, 0); PG8_LDB(B1, 0, 1); PG8_SCHED; PG8_LDA(At, 0, 0); PG8_STAGE(PG8_SA(1, 1), a1 + hstepA, voffA);
;             PG8_WAIT_V(8); PG8_WAIT_L(0); PG8_BAR; PG8_MMA(0, 0, At, B0); PG8_MMA(0, 1, At, B1); PG8_BAR; PG8_SCHED;
;             PG8_LDA(At, 0, 1); PG8_STAGE(PG8_SB(0, 0), b2, voffB); PG8_STAGE(PG8_SB(0, 1), b2 + hstepB, voffB); PG8_STAGE(PG8_SA(0, 0), a2, voffA);
;             PG8_WAIT_V(8); PG8_WAIT_L(0); PG8_BAR; PG8_MMA(1, 0, At, B0); PG8_MMA(1, 1, At, B1); PG8_BAR; PG8_SCHED;
.LBB0_1119:
	v_mov_b64_e32 v[0:1], s[0:1]
	s_ashr_i32 s45, s44, 31
	v_cmp_lt_i64_e32 vcc, s[4:5], v[0:1]
	s_lshl_b64 s[4:5], s[44:45], 20
	v_readlane_b32 s46, v253, 52
	v_readlane_b32 s47, v253, 53
	s_add_u32 s46, s46, s4
	s_addc_u32 s47, s47, s5
	s_and_b64 s[4:5], vcc, exec
	s_cselect_b32 s4, s47, s41
	s_cselect_b32 s5, s46, s40
	s_ashr_i32 s43, s42, 31
	s_lshl_b64 s[48:49], s[42:43], 20
	s_add_u32 s48, s15, s48
	s_addc_u32 s49, s26, s49
	s_and_b64 s[76:77], vcc, exec
	s_cselect_b32 s43, s49, s51
	s_cselect_b32 s45, s48, s50
	s_add_u32 s76, s40, 0x80
	s_addc_u32 s77, s41, 0
	v_lshl_add_u64 v[156:157], s[76:77], 0, v[152:153]
	v_lshl_add_u64 v[158:159], s[76:77], 0, v[154:155]
	s_add_u32 s76, s50, 0x100
	s_addc_u32 s77, s51, 0
	s_mov_b32 s78, -2
	s_mov_b64 s[50:51], 0
	s_add_u32 s17, s40, s50
	s_addc_u32 s27, s41, s51
	s_add_u32 s17, s17, 0x100
	s_addc_u32 s27, s27, 0
	s_add_u32 s79, s76, s50
	s_addc_u32 s80, s77, s51
	s_add_i32 s86, 0, 0x10000
	s_cmpk_eq_i32 s50, 0xf00
	s_cselect_b32 s95, s4, s27
	s_cselect_b32 s94, s5, s17
	v_add_u32_e32 v141, s86, v135
	s_cselect_b32 s81, s43, s80
	s_cselect_b32 s80, s45, s79
	s_add_i32 s17, 0, 0x14000
	ds_read_b128 v[160:163], v141
	ds_read_b128 v[164:167], v141 offset:1024
	ds_read_b128 v[168:171], v141 offset:2048
	ds_read_b128 v[172:175], v141 offset:3072
	v_add_u32_e32 v141, s17, v135
	ds_read_b128 v[180:183], v141
	ds_read_b128 v[184:187], v141 offset:1024
	ds_read_b128 v[188:191], v141 offset:2048
	ds_read_b128 v[192:195], v141 offset:3072
	v_lshl_add_u64 v[228:229], v[158:159], 0, s[50:51]
	s_add_i32 m0, s16, 0xc000
	ds_read_b128 v[196:199], v139
	ds_read_b128 v[200:203], v139 offset:1024
	ds_read_b128 v[204:207], v139 offset:2048
	ds_read_b128 v[208:211], v139 offset:3072
	ds_read_b128 v[212:215], v139 offset:4096
	ds_read_b128 v[216:219], v139 offset:5120
	ds_read_b128 v[220:223], v139 offset:6144
	ds_read_b128 v[224:227], v139 offset:7168
	global_load_lds_dwordx4 v[228:229], off
	v_lshl_add_u64 v[228:229], v[156:157], 0, s[50:51]
	s_add_i32 m0, s16, 0xe000
	s_nop 0
	global_load_lds_dwordx4 v[228:229], off
	s_waitcnt vmcnt(8)
	s_waitcnt lgkmcnt(0)
	s_barrier
	s_setprio 0
	s_waitcnt lgkmcnt(0)
	v_mfma_f32_16x16x32_bf16 v[124:127], v[160:163], v[196:199], 0
	v_mfma_f32_16x16x32_bf16 v[120:123], v[168:171], v[196:199], 0
	v_mfma_f32_16x16x32_bf16 v[116:119], v[160:163], v[204:207], 0
	v_mfma_f32_16x16x32_bf16 v[112:115], v[168:171], v[204:207], 0
	v_mfma_f32_16x16x32_bf16 v[100:103], v[160:163], v[212:215], 0
	v_mfma_f32_16x16x32_bf16 v[96:99], v[168:171], v[212:215], 0
	v_mfma_f32_16x16x32_bf16 v[84:87], v[160:163], v[220:223], 0
	v_mfma_f32_16x16x32_bf16 v[80:83], v[168:171], v[220:223], 0
	v_mfma_f32_16x16x32_bf16 v[124:127], v[164:167], v[200:203], v[124:127]
	v_mfma_f32_16x16x32_bf16 v[120:123], v[172:175], v[200:203], v[120:123]
	v_mfma_f32_16x16x32_bf16 v[116:119], v[164:167], v[208:211], v[116:119]
	v_mfma_f32_16x16x32_bf16 v[112:115], v[172:175], v[208:211], v[112:115]
	v_mfma_f32_16x16x32_bf16 v[100:103], v[164:167], v[216:219], v[100:103]
	v_mfma_f32_16x16x32_bf16 v[96:99], v[172:175], v[216:219], v[96:99]
	v_mfma_f32_16x16x32_bf16 v[84:87], v[164:167], v[224:227], v[84:87]
	v_mfma_f32_16x16x32_bf16 v[80:83], v[172:175], v[224:227], v[80:83]
	v_mfma_f32_16x16x32_bf16 v[108:111], v[180:183], v[196:199], 0
	v_mfma_f32_16x16x32_bf16 v[104:107], v[188:191], v[196:199], 0
	v_mfma_f32_16x16x32_bf16 v[92:95], v[180:183], v[204:207], 0
	v_mfma_f32_16x16x32_bf16 v[88:91], v[188:191], v[204:207], 0
	v_mfma_f32_16x16x32_bf16 v[76:79], v[180:183], v[212:215], 0
	v_mfma_f32_16x16x32_bf16 v[72:75], v[188:191], v[212:215], 0
	v_mfma_f32_16x16x32_bf16 v[68:71], v[180:183], v[220:223], 0
	v_mfma_f32_16x16x32_bf16 v[64:67], v[188:191], v[220:223], 0
	v_mfma_f32_16x16x32_bf16 v[108:111], v[184:187], v[200:203], v[108:111]
	v_mfma_f32_16x16x32_bf16 v[104:107], v[192:195], v[200:203], v[104:107]
	v_mfma_f32_16x16x32_bf16 v[92:95], v[184:187], v[208:211], v[92:95]
	v_mfma_f32_16x16x32_bf16 v[88:91], v[192:195], v[208:211], v[88:91]
	v_mfma_f32_16x16x32_bf16 v[76:79], v[184:187], v[216:219], v[76:79]
	v_mfma_f32_16x16x32_bf16 v[72:75], v[192:195], v[216:219], v[72:75]
	v_mfma_f32_16x16x32_bf16 v[68:71], v[184:187], v[224:227], v[68:71]
	v_mfma_f32_16x16x32_bf16 v[64:67], v[192:195], v[224:227], v[64:67]
	s_barrier
	s_add_i32 s27, s86, s3
	v_lshl_add_u64 v[228:229], s[80:81], 0, v[176:177]
	s_mov_b32 m0, s27
	ds_read_b128 v[196:199], v139 offset:16384
	ds_read_b128 v[200:203], v139 offset:17408
	ds_read_b128 v[204:207], v139 offset:18432
	ds_read_b128 v[208:211], v139 offset:19456
	ds_read_b128 v[212:215], v139 offset:20480
	ds_read_b128 v[216:219], v139 offset:21504
	ds_read_b128 v[220:223], v139 offset:22528
	ds_read_b128 v[224:227], v139 offset:23552
	global_load_lds_dwordx4 v[228:229], off
	s_add_i32 m0, s27, 0x2000
	v_lshl_add_u64 v[230:231], s[80:81], 0, v[128:129]
	s_add_u32 s80, s80, s30
	s_addc_u32 s81, s81, s31
	s_add_i32 s17, s17, s3
	global_load_lds_dwordx4 v[230:231], off
	v_lshl_add_u64 v[232:233], s[80:81], 0, v[176:177]
	s_mov_b32 m0, s17
	v_lshl_add_u64 v[234:235], s[80:81], 0, v[128:129]
	global_load_lds_dwordx4 v[232:233], off
	s_add_i32 m0, s17, 0x2000
	v_lshl_add_u64 v[236:237], s[94:95], 0, v[132:133]
	global_load_lds_dwordx4 v[234:235], off
	s_mov_b32 m0, s16
	v_lshl_add_u64 v[246:247], s[94:95], 0, v[130:131]
	global_load_lds_dwordx4 v[236:237], off
	s_mov_b32 m0, s35
	s_nop 0
	global_load_lds_dwordx4 v[246:247], off
	s_waitcnt vmcnt(8)
	s_waitcnt lgkmcnt(0)
	s_barrier
; #define PG8_STAGE(bufoff, gbase, voff) do { _Pragma("unroll") for (int _i = 0; _i < 2; ++_i) \
;         __builtin_amdgcn_global_load_lds((const unsigned*)((const char*)(gbase) + (voff)[_i]), (LAS unsigned*)(lds + (bufoff) + ldsw + _i * 8192), 16, 0, 0); } while (0)
; #define PG8_LDA(dst, b, h) do { _Pragma("unroll") for (int m = 0; m < 4; ++m) _Pragma("unroll") for (int k = 0; k < 2; ++k) dst[m][k] = *(const LAS bf16x8*)(lds + PG8_SA(b, h) + aoff + m * 2048 + k * 1024); } while (0)
; #define PG8_LDB(dst, b, h) do { _Pragma("unroll") for (int n = 0; n < 2; ++n) _Pragma("unroll") for (int k = 0; k < 2; ++k) dst[n][k] = *(const LAS bf16x8*)(lds + PG8_SB(b, h) + boff + n * 2048 + k * 1024); } while (0)
; #define PG8_MMA(ai, bj, At, Bt) do { __builtin_amdgcn_s_setprio(1); _Pragma("unroll") for (int m = 0; m < 4; ++m) _Pragma("unroll") for (int n = 0; n < 2; ++n) _Pragma("unroll") for (int k = 0; k < 2; ++k) \
;         acc[ai][bj][m][n] = __builtin_amdgcn_mfma_f32_16x16x32_bf16(Bt[n][k], At[m][k], acc[ai][bj][m][n], 0, 0, 0); __builtin_amdgcn_s_setprio(0); } while (0)
; #define PG8_WAIT_V(n) asm volatile("s_waitcnt vmcnt(" #n ")" ::: "memory")
; #define PG8_WAIT_L(n) asm volatile("s_waitcnt lgkmcnt(" #n ")" ::: "memory")
; #define PG8_BAR __builtin_amdgcn_s_barrier()
; #define PG8_SCHED __builtin_amdgcn_sched_barrier(0)
; template <class Epi, class Sched, bool ALIGN_EPI>
; __device__ __forceinline__ void gemm_phase(LAS unsigned char* lds, const int wid, const int lda_, const int ldb_, const int K_, const Sched& S, const Epi& E) {
;     ...
;             PG8_LDB(B0, 0, 0); PG8_LDB(B1, 0, 1); PG8_SCHED; PG8_LDA(At, 0, 0); PG8_STAGE(PG8_SA(1, 1), a1 + hstepA, voffA);
;             PG8_WAIT_V(8); PG8_WAIT_L(0); PG8_BAR; PG8_MMA(0, 0, At, B0); PG8_MMA(0, 1, At, B1); PG8_BAR; PG8_SCHED;
;             PG8_LDA(At, 0, 1); PG8_STAGE(PG8_SB(0, 0), b2, voffB); PG8_STAGE(PG8_SB(0, 1), b2 + hstepB, voffB); PG8_STAGE(PG8_SA(0, 0), a2, voffA);
;             PG8_WAIT_V(8); PG8_WAIT_L(0); PG8_BAR; PG8_MMA(1, 0, At, B0); PG8_MMA(1, 1, At, B1); PG8_BAR; PG8_SCHED;
	s_waitcnt lgkmcnt(0)
	v_mfma_f32_16x16x32_bf16 v[60:63], v[160:163], v[196:199], 0
	v_mfma_f32_16x16x32_bf16 v[56:59], v[168:171], v[196:199], 0
	v_mfma_f32_16x16x32_bf16 v[52:55], v[160:163], v[204:207], 0
	v_mfma_f32_16x16x32_bf16 v[48:51], v[168:171], v[204:207], 0
	v_mfma_f32_16x16x32_bf16 v[36:39], v[160:163], v[212:215], 0
	v_mfma_f32_16x16x32_bf16 v[32:35], v[168:171], v[212:215], 0
	v_mfma_f32_16x16x32_bf16 v[20:23], v[160:163], v[220:223], 0
	v_mfma_f32_16x16x32_bf16 v[16:19], v[168:171], v[220:223], 0
	v_mfma_f32_16x16x32_bf16 v[60:63], v[164:167], v[200:203], v[60:63]
	v_mfma_f32_16x16x32_bf16 v[56:59], v[172:175], v[200:203], v[56:59]
	v_mfma_f32_16x16x32_bf16 v[52:55], v[164:167], v[208:211], v[52:55]
	v_mfma_f32_16x16x32_bf16 v[48:51], v[172:175], v[208:211], v[48:51]
	v_mfma_f32_16x16x32_bf16 v[36:39], v[164:167], v[216:219], v[36:39]
	v_mfma_f32_16x16x32_bf16 v[32:35], v[172:175], v[216:219], v[32:35]
	v_mfma_f32_16x16x32_bf16 v[20:23], v[164:167], v[224:227], v[20:23]
	v_mfma_f32_16x16x32_bf16 v[16:19], v[172:175], v[224:227], v[16:19]
	v_mfma_f32_16x16x32_bf16 v[44:47], v[180:183], v[196:199], 0
	v_mfma_f32_16x16x32_bf16 v[40:43], v[188:191], v[196:199], 0
	v_mfma_f32_16x16x32_bf16 v[28:31], v[180:183], v[204:207], 0
	v_mfma_f32_16x16x32_bf16 v[24:27], v[188:191], v[204:207], 0
	v_mfma_f32_16x16x32_bf16 v[12:15], v[180:183], v[212:215], 0
	v_mfma_f32_16x16x32_bf16 v[8:11], v[188:191], v[212:215], 0
	v_mfma_f32_16x16x32_bf16 v[4:7], v[180:183], v[220:223], 0
	v_mfma_f32_16x16x32_bf16 v[0:3], v[188:191], v[220:223], 0
	v_mfma_f32_16x16x32_bf16 v[44:47], v[184:187], v[200:203], v[44:47]
	v_mfma_f32_16x16x32_bf16 v[40:43], v[192:195], v[200:203], v[40:43]
	v_mfma_f32_16x16x32_bf16 v[28:31], v[184:187], v[208:211], v[28:31]
	v_mfma_f32_16x16x32_bf16 v[24:27], v[192:195], v[208:211], v[24:27]
	v_mfma_f32_16x16x32_bf16 v[12:15], v[184:187], v[216:219], v[12:15]
	v_mfma_f32_16x16x32_bf16 v[8:11], v[192:195], v[216:219], v[8:11]
	v_mfma_f32_16x16x32_bf16 v[4:7], v[184:187], v[224:227], v[4:7]
	v_mfma_f32_16x16x32_bf16 v[0:3], v[192:195], v[224:227], v[0:3]
	s_barrier
	s_branch .Lgemm_join_1120
.LBB0_1120:
	s_add_u32 s17, s40, s50
	s_addc_u32 s27, s41, s51
	s_add_u32 s17, s17, 0x100
	s_addc_u32 s27, s27, 0
	s_add_u32 s79, s76, s50
	s_addc_u32 s80, s77, s51
	s_add_i32 s86, 0, 0x10000
	s_cmpk_eq_i32 s50, 0xf00
	s_cselect_b32 s95, s4, s27
	s_cselect_b32 s94, s5, s17
	v_add_u32_e32 v141, s86, v135
	s_cselect_b32 s81, s43, s80
	s_cselect_b32 s80, s45, s79
	s_add_i32 s17, 0, 0x14000
	ds_read_b128 v[160:163], v141
	ds_read_b128 v[164:167], v141 offset:1024
	ds_read_b128 v[168:171], v141 offset:2048
	ds_read_b128 v[172:175], v141 offset:3072
	v_add_u32_e32 v141, s17, v135
	ds_read_b128 v[180:183], v141
	ds_read_b128 v[184:187], v141 offset:1024
	ds_read_b128 v[188:191], v141 offset:2048
	ds_read_b128 v[192:195], v141 offset:3072
	v_lshl_add_u64 v[228:229], v[158:159], 0, s[50:51]
	s_add_i32 m0, s16, 0xc000
	ds_read_b128 v[196:199], v139
	ds_read_b128 v[200:203], v139 offset:1024
	ds_read_b128 v[204:207], v139 offset:2048
	ds_read_b128 v[208:211], v139 offset:3072
	ds_read_b128 v[212:215], v139 offset:4096
	ds_read_b128 v[216:219], v139 offset:5120
	ds_read_b128 v[220:223], v139 offset:6144
	ds_read_b128 v[224:227], v139 offset:7168
	global_load_lds_dwordx4 v[228:229], off
	v_lshl_add_u64 v[228:229], v[156:157], 0, s[50:51]
	s_add_i32 m0, s16, 0xe000
	s_nop 0
	global_load_lds_dwordx4 v[228:229], off
	s_waitcnt vmcnt(8)
	s_waitcnt lgkmcnt(0)
	s_barrier
	s_waitcnt lgkmcnt(0)
	v_mfma_f32_16x16x32_bf16 v[124:127], v[160:163], v[196:199], v[124:127]
	v_mfma_f32_16x16x32_bf16 v[120:123], v[168:171], v[196:199], v[120:123]
	v_mfma_f32_16x16x32_bf16 v[116:119], v[160:163], v[204:207], v[116:119]
	v_mfma_f32_16x16x32_bf16 v[112:115], v[168:171], v[204:207], v[112:115]
	v_mfma_f32_16x16x32_bf16 v[100:103], v[160:163], v[212:215], v[100:103]
	v_mfma_f32_16x16x32_bf16 v[96:99], v[168:171], v[212:215], v[96:99]
	v_mfma_f32_16x16x32_bf16 v[84:87], v[160:163], v[220:223], v[84:87]
	v_mfma_f32_16x16x32_bf16 v[80:83], v[168:171], v[220:223], v[80:83]
	v_mfma_f32_16x16x32_bf16 v[124:127], v[164:167], v[200:203], v[124:127]
	v_mfma_f32_16x16x32_bf16 v[120:123], v[172:175], v[200:203], v[120:123]
	v_mfma_f32_16x16x32_bf16 v[116:119], v[164:167], v[208:211], v[116:119]
	v_mfma_f32_16x16x32_bf16 v[112:115], v[172:175], v[208:211], v[112:115]
	v_mfma_f32_16x16x32_bf16 v[100:103], v[164:167], v[216:219], v[100:103]
	v_mfma_f32_16x16x32_bf16 v[96:99], v[172:175], v[216:219], v[96:99]
	v_mfma_f32_16x16x32_bf16 v[84:87], v[164:167], v[224:227], v[84:87]
	v_mfma_f32_16x16x32_bf16 v[80:83], v[172:175], v[224:227], v[80:83]
	v_mfma_f32_16x16x32_bf16 v[108:111], v[180:183], v[196:199], v[108:111]
	v_mfma_f32_16x16x32_bf16 v[104:107], v[188:191], v[196:199], v[104:107]
	v_mfma_f32_16x16x32_bf16 v[92:95], v[180:183], v[204:207], v[92:95]
	v_mfma_f32_16x16x32_bf16 v[88:91], v[188:191], v[204:207], v[88:91]
	v_mfma_f32_16x16x32_bf16 v[76:79], v[180:183], v[212:215], v[76:79]
	v_mfma_f32_16x16x32_bf16 v[72:75], v[188:191], v[212:215], v[72:75]
	v_mfma_f32_16x16x32_bf16 v[68:71], v[180:183], v[220:223], v[68:71]
	v_mfma_f32_16x16x32_bf16 v[64:67], v[188:191], v[220:223], v[64:67]
	v_mfma_f32_16x16x32_bf16 v[108:111], v[184:187], v[200:203], v[108:111]
	v_mfma_f32_16x16x32_bf16 v[104:107], v[192:195], v[200:203], v[104:107]
	v_mfma_f32_16x16x32_bf16 v[92:95], v[184:187], v[208:211], v[92:95]
	v_mfma_f32_16x16x32_bf16 v[88:91], v[192:195], v[208:211], v[88:91]
	v_mfma_f32_16x16x32_bf16 v[76:79], v[184:187], v[216:219], v[76:79]
	v_mfma_f32_16x16x32_bf16 v[72:75], v[192:195], v[216:219], v[72:75]
	v_mfma_f32_16x16x32_bf16 v[68:71], v[184:187], v[224:227], v[68:71]
	v_mfma_f32_16x16x32_bf16 v[64:67], v[192:195], v[224:227], v[64:67]
	s_barrier
; #define PG8_STAGE(bufoff, gbase, voff) do { _Pragma("unroll") for (int _i = 0; _i < 2; ++_i) \
;         __builtin_amdgcn_global_load_lds((const unsigned*)((const char*)(gbase) + (voff)[_i]), (LAS unsigned*)(lds + (bufoff) + ldsw + _i * 8192), 16, 0, 0); } while (0)
; #define PG8_LDA(dst, b, h) do { _Pragma("unroll") for (int m = 0; m < 4; ++m) _Pragma("unroll") for (int k = 0; k < 2; ++k) dst[m][k] = *(const LAS bf16x8*)(lds + PG8_SA(b, h) + aoff + m * 2048 + k * 1024); } while (0)
; #define PG8_LDB(dst, b, h) do { _Pragma("unroll") for (int n = 0; n < 2; ++n) _Pragma("unroll") for (int k = 0; k < 2; ++k) dst[n][k] = *(const LAS bf16x8*)(lds + PG8_SB(b, h) + boff + n * 2048 + k * 1024); } while (0)
; #define PG8_MMA(ai, bj, At, Bt) do { __builtin_amdgcn_s_setprio(1); _Pragma("unroll") for (int m = 0; m < 4; ++m) _Pragma("unroll") for (int n = 0; n < 2; ++n) _Pragma("unroll") for (int k = 0; k < 2; ++k) \
;         acc[ai][bj][m][n] = __builtin_amdgcn_mfma_f32_16x16x32_bf16(Bt[n][k], At[m][k], acc[ai][bj][m][n], 0, 0, 0); __builtin_amdgcn_s_setprio(0); } while (0)
; #define PG8_WAIT_V(n) asm volatile("s_waitcnt vmcnt(" #n ")" ::: "memory")
; #define PG8_WAIT_L(n) asm volatile("s_waitcnt lgkmcnt(" #n ")" ::: "memory")
; #define PG8_BAR __builtin_amdgcn_s_barrier()
; #define PG8_SCHED __builtin_amdgcn_sched_barrier(0)
; template <class Epi, class Sched, bool ALIGN_EPI>
; __device__ __forceinline__ void gemm_phase(LAS unsigned char* lds, const int wid, const int lda_, const int ldb_, const int K_, const Sched& S, const Epi& E) {
;     ...
;             PG8_LDA(At, 0, 1); PG8_STAGE(PG8_SB(0, 0), b2, voffB); PG8_STAGE(PG8_SB(0, 1), b2 + hstepB, voffB); PG8_STAGE(PG8_SA(0, 0), a2, voffA);
;             PG8_WAIT_V(8); PG8_WAIT_L(0); PG8_BAR; PG8_MMA(1, 0, At, B0); PG8_MMA(1, 1, At, B1); PG8_BAR; PG8_SCHED;
;             PG8_LDB(B0, 1, 0); PG8_LDB(B1, 1, 1); PG8_SCHED; PG8_LDA(At, 1, 0); PG8_STAGE(PG8_SA(0, 1), a2 + hstepA, voffA);
	s_add_i32 s27, s86, s3
	v_lshl_add_u64 v[228:229], s[80:81], 0, v[176:177]
	s_mov_b32 m0, s27
	ds_read_b128 v[196:199], v139 offset:16384
	ds_read_b128 v[200:203], v139 offset:17408
	ds_read_b128 v[204:207], v139 offset:18432
	ds_read_b128 v[208:211], v139 offset:19456
	ds_read_b128 v[212:215], v139 offset:20480
	ds_read_b128 v[216:219], v139 offset:21504
	ds_read_b128 v[220:223], v139 offset:22528
	ds_read_b128 v[224:227], v139 offset:23552
	global_load_lds_dwordx4 v[228:229], off
	s_add_i32 m0, s27, 0x2000
	v_lshl_add_u64 v[230:231], s[80:81], 0, v[128:129]
	s_add_u32 s80, s80, s30
	s_addc_u32 s81, s81, s31
	s_add_i32 s17, s17, s3
	global_load_lds_dwordx4 v[230:231], off
	v_lshl_add_u64 v[232:233], s[80:81], 0, v[176:177]
	s_mov_b32 m0, s17
	v_lshl_add_u64 v[234:235], s[80:81], 0, v[128:129]
	global_load_lds_dwordx4 v[232:233], off
	s_add_i32 m0, s17, 0x2000
	v_lshl_add_u64 v[236:237], s[94:95], 0, v[132:133]
	global_load_lds_dwordx4 v[234:235], off
	s_mov_b32 m0, s16
	v_lshl_add_u64 v[246:247], s[94:95], 0, v[130:131]
	global_load_lds_dwordx4 v[236:237], off
	s_mov_b32 m0, s35
	s_nop 0
	global_load_lds_dwordx4 v[246:247], off
	s_waitcnt vmcnt(8)
	s_waitcnt lgkmcnt(0)
	s_barrier
	s_waitcnt lgkmcnt(0)
	v_mfma_f32_16x16x32_bf16 v[60:63], v[160:163], v[196:199], v[60:63]
	v_mfma_f32_16x16x32_bf16 v[56:59], v[168:171], v[196:199], v[56:59]
	v_mfma_f32_16x16x32_bf16 v[52:55], v[160:163], v[204:207], v[52:55]
	v_mfma_f32_16x16x32_bf16 v[48:51], v[168:171], v[204:207], v[48:51]
	v_mfma_f32_16x16x32_bf16 v[36:39], v[160:163], v[212:215], v[36:39]
	v_mfma_f32_16x16x32_bf16 v[32:35], v[168:171], v[212:215], v[32:35]
	v_mfma_f32_16x16x32_bf16 v[20:23], v[160:163], v[220:223], v[20:23]
	v_mfma_f32_16x16x32_bf16 v[16:19], v[168:171], v[220:223], v[16:19]
	v_mfma_f32_16x16x32_bf16 v[60:63], v[164:167], v[200:203], v[60:63]
	v_mfma_f32_16x16x32_bf16 v[56:59], v[172:175], v[200:203], v[56:59]
	v_mfma_f32_16x16x32_bf16 v[52:55], v[164:167], v[208:211], v[52:55]
	v_mfma_f32_16x16x32_bf16 v[48:51], v[172:175], v[208:211], v[48:51]
	v_mfma_f32_16x16x32_bf16 v[36:39], v[164:167], v[216:219], v[36:39]
	v_mfma_f32_16x16x32_bf16 v[32:35], v[172:175], v[216:219], v[32:35]
	v_mfma_f32_16x16x32_bf16 v[20:23], v[164:167], v[224:227], v[20:23]
	v_mfma_f32_16x16x32_bf16 v[16:19], v[172:175], v[224:227], v[16:19]
	v_mfma_f32_16x16x32_bf16 v[44:47], v[180:183], v[196:199], v[44:47]
	v_mfma_f32_16x16x32_bf16 v[40:43], v[188:191], v[196:199], v[40:43]
	v_mfma_f32_16x16x32_bf16 v[28:31], v[180:183], v[204:207], v[28:31]
	v_mfma_f32_16x16x32_bf16 v[24:27], v[188:191], v[204:207], v[24:27]
	v_mfma_f32_16x16x32_bf16 v[12:15], v[180:183], v[212:215], v[12:15]
	v_mfma_f32_16x16x32_bf16 v[8:11], v[188:191], v[212:215], v[8:11]
	v_mfma_f32_16x16x32_bf16 v[4:7], v[180:183], v[220:223], v[4:7]
	v_mfma_f32_16x16x32_bf16 v[0:3], v[188:191], v[220:223], v[0:3]
	v_mfma_f32_16x16x32_bf16 v[44:47], v[184:187], v[200:203], v[44:47]
	v_mfma_f32_16x16x32_bf16 v[40:43], v[192:195], v[200:203], v[40:43]
	v_mfma_f32_16x16x32_bf16 v[28:31], v[184:187], v[208:211], v[28:31]
	v_mfma_f32_16x16x32_bf16 v[24:27], v[192:195], v[208:211], v[24:27]
	v_mfma_f32_16x16x32_bf16 v[12:15], v[184:187], v[216:219], v[12:15]
	v_mfma_f32_16x16x32_bf16 v[8:11], v[192:195], v[216:219], v[8:11]
	v_mfma_f32_16x16x32_bf16 v[4:7], v[184:187], v[224:227], v[4:7]
	v_mfma_f32_16x16x32_bf16 v[0:3], v[192:195], v[224:227], v[0:3]
	s_barrier
.Lgemm_join_1120:
	s_add_i32 s17, 0, 0x18000
	v_add_u32_e32 v141, s17, v135
	s_add_i32 s27, 0, 0x1c000
	ds_read_b128 v[160:163], v141
	ds_read_b128 v[164:167], v141 offset:1024
	ds_read_b128 v[168:171], v141 offset:2048
	ds_read_b128 v[172:175], v141 offset:3072
	v_add_u32_e32 v141, s27, v135
	ds_read_b128 v[180:183], v141
	ds_read_b128 v[184:187], v141 offset:1024
	ds_read_b128 v[188:191], v141 offset:2048
	ds_read_b128 v[192:195], v141 offset:3072
	s_add_u32 s80, s94, s10
	s_addc_u32 s81, s95, s11
	s_mov_b32 m0, s39
	v_lshl_add_u64 v[248:249], s[80:81], 0, v[132:133]
	ds_read_b128 v[196:199], v139 offset:32768
	ds_read_b128 v[200:203], v139 offset:33792
	ds_read_b128 v[204:207], v139 offset:34816
	ds_read_b128 v[208:211], v139 offset:35840
	ds_read_b128 v[212:215], v139 offset:36864
	ds_read_b128 v[216:219], v139 offset:37888
	ds_read_b128 v[220:223], v139 offset:38912
	ds_read_b128 v[224:227], v139 offset:39936
	global_load_lds_dwordx4 v[248:249], off
	v_lshl_add_u64 v[248:249], s[80:81], 0, v[130:131]
	s_mov_b32 m0, s72
	s_nop 0
	global_load_lds_dwordx4 v[248:249], off
	s_waitcnt vmcnt(8)
	s_waitcnt lgkmcnt(0)
	s_barrier
; #define PG8_STAGE(bufoff, gbase, voff) do { _Pragma("unroll") for (int _i = 0; _i < 2; ++_i) \
;         __builtin_amdgcn_global_load_lds((const unsigned*)((const char*)(gbase) + (voff)[_i]), (LAS unsigned*)(lds + (bufoff) + ldsw + _i * 8192), 16, 0, 0); } while (0)
; #define PG8_LDA(dst, b, h) do { _Pragma("unroll") for (int m = 0; m < 4; ++m) _Pragma("unroll") for (int k = 0; k < 2; ++k) dst[m][k] = *(const LAS bf16x8*)(lds + PG8_SA(b, h) + aoff + m * 2048 + k * 1024); } while (0)
; #define PG8_MMA(ai, bj, At, Bt) do { __builtin_amdgcn_s_setprio(1); _Pragma("unroll") for (int m = 0; m < 4; ++m) _Pragma("unroll") for (int n = 0; n < 2; ++n) _Pragma("unroll") for (int k = 0; k < 2; ++k) \
;         acc[ai][bj][m][n] = __builtin_amdgcn_mfma_f32_16x16x32_bf16(Bt[n][k], At[m][k], acc[ai][bj][m][n], 0, 0, 0); __builtin_amdgcn_s_setprio(0); } while (0)
; #define PG8_WAIT_V(n) asm volatile("s_waitcnt vmcnt(" #n ")" ::: "memory")
; #define PG8_WAIT_L(n) asm volatile("s_waitcnt lgkmcnt(" #n ")" ::: "memory")
; #define PG8_BAR __builtin_amdgcn_s_barrier()
; #define PG8_SCHED __builtin_amdgcn_sched_barrier(0)
; template <class Epi, class Sched, bool ALIGN_EPI>
; __device__ __forceinline__ void gemm_phase(LAS unsigned char* lds, const int wid, const int lda_, const int ldb_, const int K_, const Sched& S, const Epi& E) {
;     ...
;             PG8_WAIT_V(8); PG8_WAIT_L(0); PG8_BAR; PG8_MMA(0, 0, At, B0); PG8_MMA(0, 1, At, B1); PG8_BAR; PG8_SCHED;
;             PG8_LDA(At, 1, 1); PG8_STAGE(PG8_SB(1, 0), b3, voffB); PG8_STAGE(PG8_SB(1, 1), b3 + hstepB, voffB); PG8_STAGE(PG8_SA(1, 0), a3, voffA);
;             PG8_WAIT_V(8); PG8_WAIT_L(0); PG8_BAR; PG8_MMA(1, 0, At, B0); PG8_MMA(1, 1, At, B1); PG8_BAR; PG8_SCHED;
	s_waitcnt lgkmcnt(0)
	v_mfma_f32_16x16x32_bf16 v[124:127], v[160:163], v[196:199], v[124:127]
	v_mfma_f32_16x16x32_bf16 v[120:123], v[168:171], v[196:199], v[120:123]
	v_mfma_f32_16x16x32_bf16 v[116:119], v[160:163], v[204:207], v[116:119]
	v_mfma_f32_16x16x32_bf16 v[112:115], v[168:171], v[204:207], v[112:115]
	v_mfma_f32_16x16x32_bf16 v[100:103], v[160:163], v[212:215], v[100:103]
	v_mfma_f32_16x16x32_bf16 v[96:99], v[168:171], v[212:215], v[96:99]
	v_mfma_f32_16x16x32_bf16 v[84:87], v[160:163], v[220:223], v[84:87]
	v_mfma_f32_16x16x32_bf16 v[80:83], v[168:171], v[220:223], v[80:83]
	v_mfma_f32_16x16x32_bf16 v[124:127], v[164:167], v[200:203], v[124:127]
	v_mfma_f32_16x16x32_bf16 v[120:123], v[172:175], v[200:203], v[120:123]
	v_mfma_f32_16x16x32_bf16 v[116:119], v[164:167], v[208:211], v[116:119]
	v_mfma_f32_16x16x32_bf16 v[112:115], v[172:175], v[208:211], v[112:115]
	v_mfma_f32_16x16x32_bf16 v[100:103], v[164:167], v[216:219], v[100:103]
	v_mfma_f32_16x16x32_bf16 v[96:99], v[172:175], v[216:219], v[96:99]
	v_mfma_f32_16x16x32_bf16 v[84:87], v[164:167], v[224:227], v[84:87]
	v_mfma_f32_16x16x32_bf16 v[80:83], v[172:175], v[224:227], v[80:83]
	v_mfma_f32_16x16x32_bf16 v[108:111], v[180:183], v[196:199], v[108:111]
	v_mfma_f32_16x16x32_bf16 v[104:107], v[188:191], v[196:199], v[104:107]
	v_mfma_f32_16x16x32_bf16 v[92:95], v[180:183], v[204:207], v[92:95]
	v_mfma_f32_16x16x32_bf16 v[88:91], v[188:191], v[204:207], v[88:91]
	v_mfma_f32_16x16x32_bf16 v[76:79], v[180:183], v[212:215], v[76:79]
	v_mfma_f32_16x16x32_bf16 v[72:75], v[188:191], v[212:215], v[72:75]
	v_mfma_f32_16x16x32_bf16 v[68:71], v[180:183], v[220:223], v[68:71]
	v_mfma_f32_16x16x32_bf16 v[64:67], v[188:191], v[220:223], v[64:67]
	v_mfma_f32_16x16x32_bf16 v[108:111], v[184:187], v[200:203], v[108:111]
	v_mfma_f32_16x16x32_bf16 v[104:107], v[192:195], v[200:203], v[104:107]
	v_mfma_f32_16x16x32_bf16 v[92:95], v[184:187], v[208:211], v[92:95]
	v_mfma_f32_16x16x32_bf16 v[88:91], v[192:195], v[208:211], v[88:91]
	v_mfma_f32_16x16x32_bf16 v[76:79], v[184:187], v[216:219], v[76:79]
	v_mfma_f32_16x16x32_bf16 v[72:75], v[192:195], v[216:219], v[72:75]
	v_mfma_f32_16x16x32_bf16 v[68:71], v[184:187], v[224:227], v[68:71]
	v_mfma_f32_16x16x32_bf16 v[64:67], v[192:195], v[224:227], v[64:67]
	s_barrier
	s_add_i32 s17, s17, s3
	v_lshl_add_u64 v[228:229], v[228:229], 0, s[24:25]
	s_mov_b32 m0, s17
	ds_read_b128 v[196:199], v139 offset:49152
	ds_read_b128 v[200:203], v139 offset:50176
	ds_read_b128 v[204:207], v139 offset:51200
	ds_read_b128 v[208:211], v139 offset:52224
	ds_read_b128 v[212:215], v139 offset:53248
	ds_read_b128 v[216:219], v139 offset:54272
	ds_read_b128 v[220:223], v139 offset:55296
	ds_read_b128 v[224:227], v139 offset:56320
	global_load_lds_dwordx4 v[228:229], off
	v_lshl_add_u64 v[228:229], v[230:231], 0, s[24:25]
	s_add_i32 m0, s17, 0x2000
	s_add_i32 s17, s27, s3
	global_load_lds_dwordx4 v[228:229], off
	v_lshl_add_u64 v[228:229], v[232:233], 0, s[24:25]
	s_mov_b32 m0, s17
	s_nop 0
	global_load_lds_dwordx4 v[228:229], off
	v_lshl_add_u64 v[228:229], v[234:235], 0, s[24:25]
	s_add_i32 m0, s17, 0x2000
	s_nop 0
	global_load_lds_dwordx4 v[228:229], off
	v_lshl_add_u64 v[228:229], v[236:237], 0, s[24:25]
	s_mov_b32 m0, s73
	s_nop 0
	global_load_lds_dwordx4 v[228:229], off
	v_lshl_add_u64 v[228:229], v[246:247], 0, s[24:25]
	s_mov_b32 m0, s74
	s_nop 0
	global_load_lds_dwordx4 v[228:229], off
	s_waitcnt vmcnt(8)
	s_waitcnt lgkmcnt(0)
	s_barrier
	s_waitcnt lgkmcnt(0)
	v_mfma_f32_16x16x32_bf16 v[60:63], v[160:163], v[196:199], v[60:63]
	v_mfma_f32_16x16x32_bf16 v[56:59], v[168:171], v[196:199], v[56:59]
	v_mfma_f32_16x16x32_bf16 v[52:55], v[160:163], v[204:207], v[52:55]
	v_mfma_f32_16x16x32_bf16 v[48:51], v[168:171], v[204:207], v[48:51]
	v_mfma_f32_16x16x32_bf16 v[36:39], v[160:163], v[212:215], v[36:39]
	v_mfma_f32_16x16x32_bf16 v[32:35], v[168:171], v[212:215], v[32:35]
	v_mfma_f32_16x16x32_bf16 v[20:23], v[160:163], v[220:223], v[20:23]
	v_mfma_f32_16x16x32_bf16 v[16:19], v[168:171], v[220:223], v[16:19]
	v_mfma_f32_16x16x32_bf16 v[60:63], v[164:167], v[200:203], v[60:63]
	v_mfma_f32_16x16x32_bf16 v[56:59], v[172:175], v[200:203], v[56:59]
	v_mfma_f32_16x16x32_bf16 v[52:55], v[164:167], v[208:211], v[52:55]
	v_mfma_f32_16x16x32_bf16 v[48:51], v[172:175], v[208:211], v[48:51]
	v_mfma_f32_16x16x32_bf16 v[36:39], v[164:167], v[216:219], v[36:39]
	v_mfma_f32_16x16x32_bf16 v[32:35], v[172:175], v[216:219], v[32:35]
	v_mfma_f32_16x16x32_bf16 v[20:23], v[164:167], v[224:227], v[20:23]
	v_mfma_f32_16x16x32_bf16 v[16:19], v[172:175], v[224:227], v[16:19]
	v_mfma_f32_16x16x32_bf16 v[44:47], v[180:183], v[196:199], v[44:47]
	v_mfma_f32_16x16x32_bf16 v[40:43], v[188:191], v[196:199], v[40:43]
	v_mfma_f32_16x16x32_bf16 v[28:31], v[180:183], v[204:207], v[28:31]
	v_mfma_f32_16x16x32_bf16 v[24:27], v[188:191], v[204:207], v[24:27]
	v_mfma_f32_16x16x32_bf16 v[12:15], v[180:183], v[212:215], v[12:15]
	v_mfma_f32_16x16x32_bf16 v[8:11], v[188:191], v[212:215], v[8:11]
	v_mfma_f32_16x16x32_bf16 v[4:7], v[180:183], v[220:223], v[4:7]
	v_mfma_f32_16x16x32_bf16 v[0:3], v[188:191], v[220:223], v[0:3]
	v_mfma_f32_16x16x32_bf16 v[44:47], v[184:187], v[200:203], v[44:47]
	v_mfma_f32_16x16x32_bf16 v[40:43], v[192:195], v[200:203], v[40:43]
	v_mfma_f32_16x16x32_bf16 v[28:31], v[184:187], v[208:211], v[28:31]
	v_mfma_f32_16x16x32_bf16 v[24:27], v[192:195], v[208:211], v[24:27]
	v_mfma_f32_16x16x32_bf16 v[12:15], v[184:187], v[216:219], v[12:15]
	v_mfma_f32_16x16x32_bf16 v[8:11], v[192:195], v[216:219], v[8:11]
	v_mfma_f32_16x16x32_bf16 v[4:7], v[184:187], v[224:227], v[4:7]
	v_mfma_f32_16x16x32_bf16 v[0:3], v[192:195], v[224:227], v[0:3]
	s_barrier
; __device__ __forceinline__ unsigned cvt_pk_bf16(float lo, float hi) { const f32x2 v = {lo, hi}; return __builtin_bit_cast(unsigned, __builtin_convertvector(v, bf16x2_t)); }
;     template <class Sched> __device__ __forceinline__ void operator()(const f32x4 (&acc)[2][2][4][2], const Unit& u, const Sched& S, int wr, int wc, int fr, int fq) const {
;     ...
;                 for (int m = 0; m < 4; ++m) { bf16_t* rowp = base + (size_t)(rl0 + ai * HALF + m * 16) * ldo + cl0;
; #pragma unroll
;                     for (int bj = 0; bj < 2; ++bj) { const f32x4 v0 = acc[ai][bj][m][0], v1 = acc[ai][bj][m][1];
;                         u32x4 w; w.x = cvt_pk_bf16(v0[0], v0[1]); w.y = cvt_pk_bf16(v0[2], v0[3]); w.z = cvt_pk_bf16(v1[0], v1[1]); w.w = cvt_pk_bf16(v1[2], v1[3]);
;                         *(u32x4*)(rowp + bj * HALF) = w; } }
	s_add_i32 s78, s78, 2
	s_add_u32 s50, s50, 0x100
	s_addc_u32 s51, s51, 0
	s_cmp_gt_u32 s78, 29
	s_cbranch_scc0 .LBB0_1120
	s_setprio 2
	s_sub_i32 s4, s38, 22
	s_ashr_i32 s5, s38, 31
	s_cmp_lt_i32 s38, 22
	s_cselect_b32 s5, s5, 0
	s_cselect_b32 s4, s38, s4
	s_mov_b32 s17, 0x2bc00000
	s_cselect_b32 s17, 0x1f600000, s17
	s_lshl_b64 s[4:5], s[4:5], 9
	s_add_u32 s4, s66, s4
	s_addc_u32 s5, s67, s5
	s_add_u32 s4, s4, s17
	s_addc_u32 s5, s5, 0
	s_mul_i32 s27, s34, 0x2c0000
	s_mul_hi_i32 s17, s34, 0x2c0000
	s_add_u32 s4, s4, s27
	s_addc_u32 s5, s5, s17
	s_movk_i32 s17, 0x1600
	v_lshl_add_u64 v[156:157], v[136:137], 1, s[4:5]
	v_mad_i64_i32 v[158:159], s[4:5], s17, v134, 0
	v_lshl_add_u64 v[158:159], v[158:159], 1, v[156:157]
	v_cvt_pk_bf16_f32 v108, v108, v109
	v_cvt_pk_bf16_f32 v109, v110, v111
	v_cvt_pk_bf16_f32 v110, v104, v105
	v_cvt_pk_bf16_f32 v111, v106, v107
	v_mad_i64_i32 v[104:105], s[4:5], s17, v138, 0
	v_cvt_pk_bf16_f32 v124, v124, v125
	v_cvt_pk_bf16_f32 v125, v126, v127
	v_cvt_pk_bf16_f32 v126, v120, v121
	v_cvt_pk_bf16_f32 v127, v122, v123
	global_store_dwordx4 v[158:159], v[108:111], off offset:256
	v_cvt_pk_bf16_f32 v92, v92, v93
	v_cvt_pk_bf16_f32 v93, v94, v95
	v_lshl_add_u64 v[108:109], v[104:105], 1, v[156:157]
	v_cvt_pk_bf16_f32 v94, v88, v89
	v_cvt_pk_bf16_f32 v95, v90, v91
	v_mad_i64_i32 v[88:89], s[4:5], s17, v140, 0
	global_store_dwordx4 v[158:159], v[124:127], off
	v_cvt_pk_bf16_f32 v104, v116, v117
	v_cvt_pk_bf16_f32 v105, v118, v119
	v_cvt_pk_bf16_f32 v106, v112, v113
	v_cvt_pk_bf16_f32 v107, v114, v115
	global_store_dwordx4 v[108:109], v[92:95], off offset:256
	v_cvt_pk_bf16_f32 v76, v76, v77
	v_cvt_pk_bf16_f32 v77, v78, v79
	v_lshl_add_u64 v[92:93], v[88:89], 1, v[156:157]
	v_cvt_pk_bf16_f32 v78, v72, v73
	v_cvt_pk_bf16_f32 v79, v74, v75
	v_mad_i64_i32 v[72:73], s[4:5], s17, v142, 0
	v_cvt_pk_bf16_f32 v68, v68, v69
	v_cvt_pk_bf16_f32 v69, v70, v71
	v_cvt_pk_bf16_f32 v70, v64, v65
	v_mad_i64_i32 v[64:65], s[4:5], s17, v144, 0
	global_store_dwordx4 v[108:109], v[104:107], off
	v_cvt_pk_bf16_f32 v88, v100, v101
	v_cvt_pk_bf16_f32 v89, v102, v103
	v_cvt_pk_bf16_f32 v90, v96, v97
	v_cvt_pk_bf16_f32 v91, v98, v99
	global_store_dwordx4 v[92:93], v[76:79], off offset:256
	v_cvt_pk_bf16_f32 v74, v80, v81
	v_cvt_pk_bf16_f32 v75, v82, v83
	v_lshl_add_u64 v[76:77], v[72:73], 1, v[156:157]
	v_cvt_pk_bf16_f32 v72, v84, v85
	v_cvt_pk_bf16_f32 v73, v86, v87
	v_cvt_pk_bf16_f32 v71, v66, v67
	v_lshl_add_u64 v[64:65], v[64:65], 1, v[156:157]
	v_cvt_pk_bf16_f32 v44, v44, v45
	v_cvt_pk_bf16_f32 v45, v46, v47
	v_cvt_pk_bf16_f32 v46, v40, v41
	v_cvt_pk_bf16_f32 v47, v42, v43
	v_mad_i64_i32 v[40:41], s[4:5], s17, v146, 0
	global_store_dwordx4 v[92:93], v[88:91], off
	global_store_dwordx4 v[76:77], v[72:75], off
	global_store_dwordx4 v[76:77], v[68:71], off offset:256
	v_cvt_pk_bf16_f32 v60, v60, v61
	v_cvt_pk_bf16_f32 v61, v62, v63
	v_cvt_pk_bf16_f32 v62, v56, v57
	v_cvt_pk_bf16_f32 v63, v58, v59
	global_store_dwordx4 v[64:65], v[44:47], off offset:256
	v_cvt_pk_bf16_f32 v28, v28, v29
	v_cvt_pk_bf16_f32 v29, v30, v31
	v_lshl_add_u64 v[44:45], v[40:41], 1, v[156:157]
	v_cvt_pk_bf16_f32 v30, v24, v25
	v_cvt_pk_bf16_f32 v31, v26, v27
	v_mad_i64_i32 v[24:25], s[4:5], s17, v148, 0
	global_store_dwordx4 v[64:65], v[60:63], off
	v_cvt_pk_bf16_f32 v40, v52, v53
	v_cvt_pk_bf16_f32 v41, v54, v55
	v_cvt_pk_bf16_f32 v42, v48, v49
	v_cvt_pk_bf16_f32 v43, v50, v51
	global_store_dwordx4 v[44:45], v[28:31], off offset:256
	v_cvt_pk_bf16_f32 v12, v12, v13
	v_cvt_pk_bf16_f32 v13, v14, v15
	v_lshl_add_u64 v[28:29], v[24:25], 1, v[156:157]
	v_cvt_pk_bf16_f32 v14, v8, v9
	v_cvt_pk_bf16_f32 v15, v10, v11
	v_mad_i64_i32 v[8:9], s[4:5], s17, v150, 0
	global_store_dwordx4 v[44:45], v[40:43], off
	v_cvt_pk_bf16_f32 v24, v36, v37
	v_cvt_pk_bf16_f32 v25, v38, v39
	v_cvt_pk_bf16_f32 v26, v32, v33
	v_cvt_pk_bf16_f32 v27, v34, v35
	global_store_dwordx4 v[28:29], v[12:15], off offset:256
	v_cvt_pk_bf16_f32 v10, v16, v17
	v_cvt_pk_bf16_f32 v11, v18, v19
	v_lshl_add_u64 v[12:13], v[8:9], 1, v[156:157]
	v_cvt_pk_bf16_f32 v8, v20, v21
	v_cvt_pk_bf16_f32 v9, v22, v23
	v_cvt_pk_bf16_f32 v4, v4, v5
	v_cvt_pk_bf16_f32 v5, v6, v7
	v_cvt_pk_bf16_f32 v6, v0, v1
	v_cvt_pk_bf16_f32 v7, v2, v3
	s_and_b64 vcc, exec, s[36:37]
	s_mov_b32 s38, s42
	s_mov_b32 s34, s44
	s_mov_b64 s[50:51], s[48:49]
	s_mov_b64 s[40:41], s[46:47]
	global_store_dwordx4 v[28:29], v[24:27], off
	global_store_dwordx4 v[12:13], v[8:11], off
	global_store_dwordx4 v[12:13], v[4:7], off offset:256
	s_cbranch_vccz .LBB0_1117
	v_readlane_b32 s4, v253, 1
	s_waitcnt vmcnt(0)
	v_readlane_b32 s5, v253, 2
	s_andn2_b64 vcc, exec, s[4:5]
	s_cbranch_vccnz .LBB0_1124
	s_barrier

; #define PG8_STAGE(bufoff, gbase, voff) do { _Pragma("unroll") for (int _i = 0; _i < 2; ++_i) \
;         __builtin_amdgcn_global_load_lds((const unsigned*)((const char*)(gbase) + (voff)[_i]), (LAS unsigned*)(lds + (bufoff) + ldsw + _i * 8192), 16, 0, 0); } while (0)
; #define PG8_LDA(dst, b, h) do { _Pragma("unroll") for (int m = 0; m < 4; ++m) _Pragma("unroll") for (int k = 0; k < 2; ++k) dst[m][k] = *(const LAS bf16x8*)(lds + PG8_SA(b, h) + aoff + m * 2048 + k * 1024); } while (0)
; #define PG8_LDB(dst, b, h) do { _Pragma("unroll") for (int n = 0; n < 2; ++n) _Pragma("unroll") for (int k = 0; k < 2; ++k) dst[n][k] = *(const LAS bf16x8*)(lds + PG8_SB(b, h) + boff + n * 2048 + k * 1024); } while (0)
; #define PG8_MMA(ai, bj, At, Bt) do { __builtin_amdgcn_s_setprio(1); _Pragma("unroll") for (int m = 0; m < 4; ++m) _Pragma("unroll") for (int n = 0; n < 2; ++n) _Pragma("unroll") for (int k = 0; k < 2; ++k) \
;         acc[ai][bj][m][n] = __builtin_amdgcn_mfma_f32_16x16x32_bf16(Bt[n][k], At[m][k], acc[ai][bj][m][n], 0, 0, 0); __builtin_amdgcn_s_setprio(0); } while (0)
; template <class Epi, class Sched, bool ALIGN_EPI>
; __device__ __forceinline__ void gemm_phase(LAS unsigned char* lds, const int wid, const int lda_, const int ldb_, const int K_, const Sched& S, const Epi& E) {
;     ...
;         const bool has_next = S.next(ui + 1, nxt);
;         const int nt = S.nt(cur);
;         const char* nA = has_next ? S.a(nxt) : cA; const char* nB = has_next ? S.b(nxt) : cB;
; #pragma unroll 1
;         for (int t = 0; t < nt; t += 2) {
;             const bool last = (t == nt - 2);
;             const char* a1 = cA + (size_t)(t + 1) * kstep;
;             const char* a2 = last ? nA : cA + (size_t)(t + 2) * kstep; const char* b2 = last ? nB : cB + (size_t)(t + 2) * kstep;
;             const char* a3 = a2 + kstep; const char* b3 = b2 + kstep;
;             PG8_LDB(B0, 0, 0); PG8_LDB(B1, 0, 1); PG8_SCHED; PG8_LDA(At, 0, 0); PG8_STAGE(PG8_SA(1, 1), a1 + hstepA, voffA);
;             PG8_WAIT_V(8); PG8_WAIT_L(0); PG8_BAR; PG8_MMA(0, 0, At, B0); PG8_MMA(0, 1, At, B1); PG8_BAR; PG8_SCHED;
;             PG8_LDA(At, 0, 1); PG8_STAGE(PG8_SB(0, 0), b2, voffB); PG8_STAGE(PG8_SB(0, 1), b2 + hstepB, voffB); PG8_STAGE(PG8_SA(0, 0), a2, voffA);
;             PG8_WAIT_V(8); PG8_WAIT_L(0); PG8_BAR; PG8_MMA(1, 0, At, B0); PG8_MMA(1, 1, At, B1); PG8_BAR; PG8_SCHED;
.LBB0_1340:
	s_cmp_gt_i32 s38, -1
	s_cselect_b64 s[44:45], -1, 0
	s_cmp_lt_i32 s38, 0
	s_cselect_b32 s4, 0x58, 22
	s_add_i32 s5, s4, -2
	s_add_u32 s46, s46, 0x80
	s_addc_u32 s47, s47, 0
	s_add_u32 s31, s48, 0x100
	s_mov_b32 s39, 0
	s_addc_u32 s35, s49, 0
	s_add_i32 s76, s39, 2
	s_add_u32 s17, s46, 0x80
	s_addc_u32 s27, s47, 0
	s_add_i32 s77, 0, 0x10000
	s_cmp_eq_u32 s5, s39
	s_cselect_b32 s49, s43, s27
	s_cselect_b32 s48, s42, s17
	v_add_u32_e32 v141, s77, v135
	s_cselect_b32 s79, s37, s35
	s_cselect_b32 s78, s36, s31
	s_add_i32 s17, 0, 0x14000
	ds_read_b128 v[156:159], v141
	ds_read_b128 v[160:163], v141 offset:1024
	ds_read_b128 v[164:167], v141 offset:2048
	ds_read_b128 v[168:171], v141 offset:3072
	v_add_u32_e32 v141, s17, v135
	ds_read_b128 v[172:175], v141
	ds_read_b128 v[180:183], v141 offset:1024
	ds_read_b128 v[184:187], v141 offset:2048
	ds_read_b128 v[188:191], v141 offset:3072
	v_lshl_add_u64 v[224:225], s[46:47], 0, v[152:153]
	s_add_i32 m0, s16, 0xc000
	ds_read_b128 v[192:195], v139
	ds_read_b128 v[196:199], v139 offset:1024
	ds_read_b128 v[200:203], v139 offset:2048
	ds_read_b128 v[204:207], v139 offset:3072
	ds_read_b128 v[208:211], v139 offset:4096
	ds_read_b128 v[212:215], v139 offset:5120
	ds_read_b128 v[216:219], v139 offset:6144
	ds_read_b128 v[220:223], v139 offset:7168
	global_load_lds_dwordx4 v[224:225], off
	v_lshl_add_u64 v[224:225], s[46:47], 0, v[154:155]
	s_add_i32 m0, s16, 0xe000
	s_nop 0
	global_load_lds_dwordx4 v[224:225], off
	s_waitcnt vmcnt(8)
	s_waitcnt lgkmcnt(0)
	s_barrier
	s_setprio 0
	s_waitcnt lgkmcnt(0)
	v_mfma_f32_16x16x32_bf16 v[124:127], v[156:159], v[192:195], 0
	v_mfma_f32_16x16x32_bf16 v[120:123], v[164:167], v[192:195], 0
	v_mfma_f32_16x16x32_bf16 v[116:119], v[156:159], v[200:203], 0
	v_mfma_f32_16x16x32_bf16 v[112:115], v[164:167], v[200:203], 0
	v_mfma_f32_16x16x32_bf16 v[100:103], v[156:159], v[208:211], 0
	v_mfma_f32_16x16x32_bf16 v[96:99], v[164:167], v[208:211], 0
	v_mfma_f32_16x16x32_bf16 v[84:87], v[156:159], v[216:219], 0
	v_mfma_f32_16x16x32_bf16 v[80:83], v[164:167], v[216:219], 0
	v_mfma_f32_16x16x32_bf16 v[124:127], v[160:163], v[196:199], v[124:127]
	v_mfma_f32_16x16x32_bf16 v[120:123], v[168:171], v[196:199], v[120:123]
	v_mfma_f32_16x16x32_bf16 v[116:119], v[160:163], v[204:207], v[116:119]
	v_mfma_f32_16x16x32_bf16 v[112:115], v[168:171], v[204:207], v[112:115]
	v_mfma_f32_16x16x32_bf16 v[100:103], v[160:163], v[212:215], v[100:103]
	v_mfma_f32_16x16x32_bf16 v[96:99], v[168:171], v[212:215], v[96:99]
	v_mfma_f32_16x16x32_bf16 v[84:87], v[160:163], v[220:223], v[84:87]
	v_mfma_f32_16x16x32_bf16 v[80:83], v[168:171], v[220:223], v[80:83]
	v_mfma_f32_16x16x32_bf16 v[108:111], v[172:175], v[192:195], 0
	v_mfma_f32_16x16x32_bf16 v[104:107], v[184:187], v[192:195], 0
	v_mfma_f32_16x16x32_bf16 v[92:95], v[172:175], v[200:203], 0
	v_mfma_f32_16x16x32_bf16 v[88:91], v[184:187], v[200:203], 0
	v_mfma_f32_16x16x32_bf16 v[76:79], v[172:175], v[208:211], 0
	v_mfma_f32_16x16x32_bf16 v[72:75], v[184:187], v[208:211], 0
	v_mfma_f32_16x16x32_bf16 v[68:71], v[172:175], v[216:219], 0
	v_mfma_f32_16x16x32_bf16 v[64:67], v[184:187], v[216:219], 0
	v_mfma_f32_16x16x32_bf16 v[108:111], v[180:183], v[196:199], v[108:111]
	v_mfma_f32_16x16x32_bf16 v[104:107], v[188:191], v[196:199], v[104:107]
	v_mfma_f32_16x16x32_bf16 v[92:95], v[180:183], v[204:207], v[92:95]
	v_mfma_f32_16x16x32_bf16 v[88:91], v[188:191], v[204:207], v[88:91]
	v_mfma_f32_16x16x32_bf16 v[76:79], v[180:183], v[212:215], v[76:79]
	v_mfma_f32_16x16x32_bf16 v[72:75], v[188:191], v[212:215], v[72:75]
	v_mfma_f32_16x16x32_bf16 v[68:71], v[180:183], v[220:223], v[68:71]
	v_mfma_f32_16x16x32_bf16 v[64:67], v[188:191], v[220:223], v[64:67]
	s_barrier
	s_add_i32 s27, s77, s3
	v_lshl_add_u64 v[224:225], s[78:79], 0, v[176:177]
	s_mov_b32 m0, s27
	ds_read_b128 v[192:195], v139 offset:16384
	ds_read_b128 v[196:199], v139 offset:17408
	ds_read_b128 v[200:203], v139 offset:18432
	ds_read_b128 v[204:207], v139 offset:19456
	ds_read_b128 v[208:211], v139 offset:20480
	ds_read_b128 v[212:215], v139 offset:21504
	ds_read_b128 v[216:219], v139 offset:22528
	ds_read_b128 v[220:223], v139 offset:23552
	global_load_lds_dwordx4 v[224:225], off
	s_add_i32 m0, s27, 0x2000
	v_lshl_add_u64 v[226:227], s[78:79], 0, v[132:133]
	s_add_u32 s78, s78, s10
	s_addc_u32 s79, s79, s11
	s_add_i32 s17, s17, s3
	global_load_lds_dwordx4 v[226:227], off
	v_lshl_add_u64 v[228:229], s[78:79], 0, v[176:177]
	s_mov_b32 m0, s17
	v_lshl_add_u64 v[230:231], s[78:79], 0, v[132:133]
	global_load_lds_dwordx4 v[228:229], off
	s_add_i32 m0, s17, 0x2000
	v_lshl_add_u64 v[232:233], s[48:49], 0, v[128:129]
	global_load_lds_dwordx4 v[230:231], off
	s_mov_b32 m0, s16
	v_lshl_add_u64 v[234:235], s[48:49], 0, v[130:131]
	global_load_lds_dwordx4 v[232:233], off
	s_mov_b32 m0, s14
	s_nop 0
	global_load_lds_dwordx4 v[234:235], off
	s_waitcnt vmcnt(8)
	s_waitcnt lgkmcnt(0)
	s_barrier
; #define PG8_STAGE(bufoff, gbase, voff) do { _Pragma("unroll") for (int _i = 0; _i < 2; ++_i) \
;         __builtin_amdgcn_global_load_lds((const unsigned*)((const char*)(gbase) + (voff)[_i]), (LAS unsigned*)(lds + (bufoff) + ldsw + _i * 8192), 16, 0, 0); } while (0)
; #define PG8_LDA(dst, b, h) do { _Pragma("unroll") for (int m = 0; m < 4; ++m) _Pragma("unroll") for (int k = 0; k < 2; ++k) dst[m][k] = *(const LAS bf16x8*)(lds + PG8_SA(b, h) + aoff + m * 2048 + k * 1024); } while (0)
; #define PG8_LDB(dst, b, h) do { _Pragma("unroll") for (int n = 0; n < 2; ++n) _Pragma("unroll") for (int k = 0; k < 2; ++k) dst[n][k] = *(const LAS bf16x8*)(lds + PG8_SB(b, h) + boff + n * 2048 + k * 1024); } while (0)
; #define PG8_MMA(ai, bj, At, Bt) do { __builtin_amdgcn_s_setprio(1); _Pragma("unroll") for (int m = 0; m < 4; ++m) _Pragma("unroll") for (int n = 0; n < 2; ++n) _Pragma("unroll") for (int k = 0; k < 2; ++k) \
;         acc[ai][bj][m][n] = __builtin_amdgcn_mfma_f32_16x16x32_bf16(Bt[n][k], At[m][k], acc[ai][bj][m][n], 0, 0, 0); __builtin_amdgcn_s_setprio(0); } while (0)
; #define PG8_WAIT_V(n) asm volatile("s_waitcnt vmcnt(" #n ")" ::: "memory")
; #define PG8_WAIT_L(n) asm volatile("s_waitcnt lgkmcnt(" #n ")" ::: "memory")
; #define PG8_BAR __builtin_amdgcn_s_barrier()
; #define PG8_SCHED __builtin_amdgcn_sched_barrier(0)
; template <class Epi, class Sched, bool ALIGN_EPI>
; __device__ __forceinline__ void gemm_phase(LAS unsigned char* lds, const int wid, const int lda_, const int ldb_, const int K_, const Sched& S, const Epi& E) {
;     ...
;             PG8_LDB(B0, 0, 0); PG8_LDB(B1, 0, 1); PG8_SCHED; PG8_LDA(At, 0, 0); PG8_STAGE(PG8_SA(1, 1), a1 + hstepA, voffA);
;             PG8_WAIT_V(8); PG8_WAIT_L(0); PG8_BAR; PG8_MMA(0, 0, At, B0); PG8_MMA(0, 1, At, B1); PG8_BAR; PG8_SCHED;
;             PG8_LDA(At, 0, 1); PG8_STAGE(PG8_SB(0, 0), b2, voffB); PG8_STAGE(PG8_SB(0, 1), b2 + hstepB, voffB); PG8_STAGE(PG8_SA(0, 0), a2, voffA);
;             PG8_WAIT_V(8); PG8_WAIT_L(0); PG8_BAR; PG8_MMA(1, 0, At, B0); PG8_MMA(1, 1, At, B1); PG8_BAR; PG8_SCHED;
	s_waitcnt lgkmcnt(0)
	v_mfma_f32_16x16x32_bf16 v[60:63], v[156:159], v[192:195], 0
	v_mfma_f32_16x16x32_bf16 v[56:59], v[164:167], v[192:195], 0
	v_mfma_f32_16x16x32_bf16 v[52:55], v[156:159], v[200:203], 0
	v_mfma_f32_16x16x32_bf16 v[48:51], v[164:167], v[200:203], 0
	v_mfma_f32_16x16x32_bf16 v[36:39], v[156:159], v[208:211], 0
	v_mfma_f32_16x16x32_bf16 v[32:35], v[164:167], v[208:211], 0
	v_mfma_f32_16x16x32_bf16 v[20:23], v[156:159], v[216:219], 0
	v_mfma_f32_16x16x32_bf16 v[16:19], v[164:167], v[216:219], 0
	v_mfma_f32_16x16x32_bf16 v[60:63], v[160:163], v[196:199], v[60:63]
	v_mfma_f32_16x16x32_bf16 v[56:59], v[168:171], v[196:199], v[56:59]
	v_mfma_f32_16x16x32_bf16 v[52:55], v[160:163], v[204:207], v[52:55]
	v_mfma_f32_16x16x32_bf16 v[48:51], v[168:171], v[204:207], v[48:51]
	v_mfma_f32_16x16x32_bf16 v[36:39], v[160:163], v[212:215], v[36:39]
	v_mfma_f32_16x16x32_bf16 v[32:35], v[168:171], v[212:215], v[32:35]
	v_mfma_f32_16x16x32_bf16 v[20:23], v[160:163], v[220:223], v[20:23]
	v_mfma_f32_16x16x32_bf16 v[16:19], v[168:171], v[220:223], v[16:19]
	v_mfma_f32_16x16x32_bf16 v[44:47], v[172:175], v[192:195], 0
	v_mfma_f32_16x16x32_bf16 v[40:43], v[184:187], v[192:195], 0
	v_mfma_f32_16x16x32_bf16 v[28:31], v[172:175], v[200:203], 0
	v_mfma_f32_16x16x32_bf16 v[24:27], v[184:187], v[200:203], 0
	v_mfma_f32_16x16x32_bf16 v[12:15], v[172:175], v[208:211], 0
	v_mfma_f32_16x16x32_bf16 v[8:11], v[184:187], v[208:211], 0
	v_mfma_f32_16x16x32_bf16 v[4:7], v[172:175], v[216:219], 0
	v_mfma_f32_16x16x32_bf16 v[0:3], v[184:187], v[216:219], 0
	v_mfma_f32_16x16x32_bf16 v[44:47], v[180:183], v[196:199], v[44:47]
	v_mfma_f32_16x16x32_bf16 v[40:43], v[188:191], v[196:199], v[40:43]
	v_mfma_f32_16x16x32_bf16 v[28:31], v[180:183], v[204:207], v[28:31]
	v_mfma_f32_16x16x32_bf16 v[24:27], v[188:191], v[204:207], v[24:27]
	v_mfma_f32_16x16x32_bf16 v[12:15], v[180:183], v[212:215], v[12:15]
	v_mfma_f32_16x16x32_bf16 v[8:11], v[188:191], v[212:215], v[8:11]
	v_mfma_f32_16x16x32_bf16 v[4:7], v[180:183], v[220:223], v[4:7]
	v_mfma_f32_16x16x32_bf16 v[0:3], v[188:191], v[220:223], v[0:3]
	s_barrier
	s_branch .Lgemm_join_1341
.LBB0_1341:
	s_add_i32 s76, s39, 2
	s_add_u32 s17, s46, 0x80
	s_addc_u32 s27, s47, 0
	s_add_i32 s77, 0, 0x10000
	s_cmp_eq_u32 s5, s39
	s_cselect_b32 s49, s43, s27
	s_cselect_b32 s48, s42, s17
	v_add_u32_e32 v141, s77, v135
	s_cselect_b32 s79, s37, s35
	s_cselect_b32 s78, s36, s31
	s_add_i32 s17, 0, 0x14000
	ds_read_b128 v[156:159], v141
	ds_read_b128 v[160:163], v141 offset:1024
	ds_read_b128 v[164:167], v141 offset:2048
	ds_read_b128 v[168:171], v141 offset:3072
	v_add_u32_e32 v141, s17, v135
	ds_read_b128 v[172:175], v141
	ds_read_b128 v[180:183], v141 offset:1024
	ds_read_b128 v[184:187], v141 offset:2048
	ds_read_b128 v[188:191], v141 offset:3072
	v_lshl_add_u64 v[224:225], s[46:47], 0, v[152:153]
	s_add_i32 m0, s16, 0xc000
	ds_read_b128 v[192:195], v139
	ds_read_b128 v[196:199], v139 offset:1024
	ds_read_b128 v[200:203], v139 offset:2048
	ds_read_b128 v[204:207], v139 offset:3072
	ds_read_b128 v[208:211], v139 offset:4096
	ds_read_b128 v[212:215], v139 offset:5120
	ds_read_b128 v[216:219], v139 offset:6144
	ds_read_b128 v[220:223], v139 offset:7168
	global_load_lds_dwordx4 v[224:225], off
	v_lshl_add_u64 v[224:225], s[46:47], 0, v[154:155]
	s_add_i32 m0, s16, 0xe000
	s_nop 0
	global_load_lds_dwordx4 v[224:225], off
	s_waitcnt vmcnt(8)
	s_waitcnt lgkmcnt(0)
	s_barrier
	s_waitcnt lgkmcnt(0)
	v_mfma_f32_16x16x32_bf16 v[124:127], v[156:159], v[192:195], v[124:127]
	v_mfma_f32_16x16x32_bf16 v[120:123], v[164:167], v[192:195], v[120:123]
	v_mfma_f32_16x16x32_bf16 v[116:119], v[156:159], v[200:203], v[116:119]
	v_mfma_f32_16x16x32_bf16 v[112:115], v[164:167], v[200:203], v[112:115]
	v_mfma_f32_16x16x32_bf16 v[100:103], v[156:159], v[208:211], v[100:103]
	v_mfma_f32_16x16x32_bf16 v[96:99], v[164:167], v[208:211], v[96:99]
	v_mfma_f32_16x16x32_bf16 v[84:87], v[156:159], v[216:219], v[84:87]
	v_mfma_f32_16x16x32_bf16 v[80:83], v[164:167], v[216:219], v[80:83]
	v_mfma_f32_16x16x32_bf16 v[124:127], v[160:163], v[196:199], v[124:127]
	v_mfma_f32_16x16x32_bf16 v[120:123], v[168:171], v[196:199], v[120:123]
	v_mfma_f32_16x16x32_bf16 v[116:119], v[160:163], v[204:207], v[116:119]
	v_mfma_f32_16x16x32_bf16 v[112:115], v[168:171], v[204:207], v[112:115]
	v_mfma_f32_16x16x32_bf16 v[100:103], v[160:163], v[212:215], v[100:103]
	v_mfma_f32_16x16x32_bf16 v[96:99], v[168:171], v[212:215], v[96:99]
	v_mfma_f32_16x16x32_bf16 v[84:87], v[160:163], v[220:223], v[84:87]
	v_mfma_f32_16x16x32_bf16 v[80:83], v[168:171], v[220:223], v[80:83]
	v_mfma_f32_16x16x32_bf16 v[108:111], v[172:175], v[192:195], v[108:111]
	v_mfma_f32_16x16x32_bf16 v[104:107], v[184:187], v[192:195], v[104:107]
	v_mfma_f32_16x16x32_bf16 v[92:95], v[172:175], v[200:203], v[92:95]
	v_mfma_f32_16x16x32_bf16 v[88:91], v[184:187], v[200:203], v[88:91]
	v_mfma_f32_16x16x32_bf16 v[76:79], v[172:175], v[208:211], v[76:79]
	v_mfma_f32_16x16x32_bf16 v[72:75], v[184:187], v[208:211], v[72:75]
	v_mfma_f32_16x16x32_bf16 v[68:71], v[172:175], v[216:219], v[68:71]
	v_mfma_f32_16x16x32_bf16 v[64:67], v[184:187], v[216:219], v[64:67]
	v_mfma_f32_16x16x32_bf16 v[108:111], v[180:183], v[196:199], v[108:111]
	v_mfma_f32_16x16x32_bf16 v[104:107], v[188:191], v[196:199], v[104:107]
	v_mfma_f32_16x16x32_bf16 v[92:95], v[180:183], v[204:207], v[92:95]
	v_mfma_f32_16x16x32_bf16 v[88:91], v[188:191], v[204:207], v[88:91]
	v_mfma_f32_16x16x32_bf16 v[76:79], v[180:183], v[212:215], v[76:79]
	v_mfma_f32_16x16x32_bf16 v[72:75], v[188:191], v[212:215], v[72:75]
	v_mfma_f32_16x16x32_bf16 v[68:71], v[180:183], v[220:223], v[68:71]
	v_mfma_f32_16x16x32_bf16 v[64:67], v[188:191], v[220:223], v[64:67]
	s_barrier
; #define PG8_STAGE(bufoff, gbase, voff) do { _Pragma("unroll") for (int _i = 0; _i < 2; ++_i) \
;         __builtin_amdgcn_global_load_lds((const unsigned*)((const char*)(gbase) + (voff)[_i]), (LAS unsigned*)(lds + (bufoff) + ldsw + _i * 8192), 16, 0, 0); } while (0)
; #define PG8_LDA(dst, b, h) do { _Pragma("unroll") for (int m = 0; m < 4; ++m) _Pragma("unroll") for (int k = 0; k < 2; ++k) dst[m][k] = *(const LAS bf16x8*)(lds + PG8_SA(b, h) + aoff + m * 2048 + k * 1024); } while (0)
; #define PG8_LDB(dst, b, h) do { _Pragma("unroll") for (int n = 0; n < 2; ++n) _Pragma("unroll") for (int k = 0; k < 2; ++k) dst[n][k] = *(const LAS bf16x8*)(lds + PG8_SB(b, h) + boff + n * 2048 + k * 1024); } while (0)
; #define PG8_MMA(ai, bj, At, Bt) do { __builtin_amdgcn_s_setprio(1); _Pragma("unroll") for (int m = 0; m < 4; ++m) _Pragma("unroll") for (int n = 0; n < 2; ++n) _Pragma("unroll") for (int k = 0; k < 2; ++k) \
;         acc[ai][bj][m][n] = __builtin_amdgcn_mfma_f32_16x16x32_bf16(Bt[n][k], At[m][k], acc[ai][bj][m][n], 0, 0, 0); __builtin_amdgcn_s_setprio(0); } while (0)
; #define PG8_WAIT_V(n) asm volatile("s_waitcnt vmcnt(" #n ")" ::: "memory")
; #define PG8_WAIT_L(n) asm volatile("s_waitcnt lgkmcnt(" #n ")" ::: "memory")
; #define PG8_BAR __builtin_amdgcn_s_barrier()
; #define PG8_SCHED __builtin_amdgcn_sched_barrier(0)
; template <class Epi, class Sched, bool ALIGN_EPI>
; __device__ __forceinline__ void gemm_phase(LAS unsigned char* lds, const int wid, const int lda_, const int ldb_, const int K_, const Sched& S, const Epi& E) {
;     ...
;             PG8_LDA(At, 0, 1); PG8_STAGE(PG8_SB(0, 0), b2, voffB); PG8_STAGE(PG8_SB(0, 1), b2 + hstepB, voffB); PG8_STAGE(PG8_SA(0, 0), a2, voffA);
;             PG8_WAIT_V(8); PG8_WAIT_L(0); PG8_BAR; PG8_MMA(1, 0, At, B0); PG8_MMA(1, 1, At, B1); PG8_BAR; PG8_SCHED;
;             PG8_LDB(B0, 1, 0); PG8_LDB(B1, 1, 1); PG8_SCHED; PG8_LDA(At, 1, 0); PG8_STAGE(PG8_SA(0, 1), a2 + hstepA, voffA);
	s_add_i32 s27, s77, s3
	v_lshl_add_u64 v[224:225], s[78:79], 0, v[176:177]
	s_mov_b32 m0, s27
	ds_read_b128 v[192:195], v139 offset:16384
	ds_read_b128 v[196:199], v139 offset:17408
	ds_read_b128 v[200:203], v139 offset:18432
	ds_read_b128 v[204:207], v139 offset:19456
	ds_read_b128 v[208:211], v139 offset:20480
	ds_read_b128 v[212:215], v139 offset:21504
	ds_read_b128 v[216:219], v139 offset:22528
	ds_read_b128 v[220:223], v139 offset:23552
	global_load_lds_dwordx4 v[224:225], off
	s_add_i32 m0, s27, 0x2000
	v_lshl_add_u64 v[226:227], s[78:79], 0, v[132:133]
	s_add_u32 s78, s78, s10
	s_addc_u32 s79, s79, s11
	s_add_i32 s17, s17, s3
	global_load_lds_dwordx4 v[226:227], off
	v_lshl_add_u64 v[228:229], s[78:79], 0, v[176:177]
	s_mov_b32 m0, s17
	v_lshl_add_u64 v[230:231], s[78:79], 0, v[132:133]
	global_load_lds_dwordx4 v[228:229], off
	s_add_i32 m0, s17, 0x2000
	v_lshl_add_u64 v[232:233], s[48:49], 0, v[128:129]
	global_load_lds_dwordx4 v[230:231], off
	s_mov_b32 m0, s16
	v_lshl_add_u64 v[234:235], s[48:49], 0, v[130:131]
	global_load_lds_dwordx4 v[232:233], off
	s_mov_b32 m0, s14
	s_nop 0
	global_load_lds_dwordx4 v[234:235], off
	s_waitcnt vmcnt(8)
	s_waitcnt lgkmcnt(0)
	s_barrier
	s_waitcnt lgkmcnt(0)
	v_mfma_f32_16x16x32_bf16 v[60:63], v[156:159], v[192:195], v[60:63]
	v_mfma_f32_16x16x32_bf16 v[56:59], v[164:167], v[192:195], v[56:59]
	v_mfma_f32_16x16x32_bf16 v[52:55], v[156:159], v[200:203], v[52:55]
	v_mfma_f32_16x16x32_bf16 v[48:51], v[164:167], v[200:203], v[48:51]
	v_mfma_f32_16x16x32_bf16 v[36:39], v[156:159], v[208:211], v[36:39]
	v_mfma_f32_16x16x32_bf16 v[32:35], v[164:167], v[208:211], v[32:35]
	v_mfma_f32_16x16x32_bf16 v[20:23], v[156:159], v[216:219], v[20:23]
	v_mfma_f32_16x16x32_bf16 v[16:19], v[164:167], v[216:219], v[16:19]
	v_mfma_f32_16x16x32_bf16 v[60:63], v[160:163], v[196:199], v[60:63]
	v_mfma_f32_16x16x32_bf16 v[56:59], v[168:171], v[196:199], v[56:59]
	v_mfma_f32_16x16x32_bf16 v[52:55], v[160:163], v[204:207], v[52:55]
	v_mfma_f32_16x16x32_bf16 v[48:51], v[168:171], v[204:207], v[48:51]
	v_mfma_f32_16x16x32_bf16 v[36:39], v[160:163], v[212:215], v[36:39]
	v_mfma_f32_16x16x32_bf16 v[32:35], v[168:171], v[212:215], v[32:35]
	v_mfma_f32_16x16x32_bf16 v[20:23], v[160:163], v[220:223], v[20:23]
	v_mfma_f32_16x16x32_bf16 v[16:19], v[168:171], v[220:223], v[16:19]
	v_mfma_f32_16x16x32_bf16 v[44:47], v[172:175], v[192:195], v[44:47]
	v_mfma_f32_16x16x32_bf16 v[40:43], v[184:187], v[192:195], v[40:43]
	v_mfma_f32_16x16x32_bf16 v[28:31], v[172:175], v[200:203], v[28:31]
	v_mfma_f32_16x16x32_bf16 v[24:27], v[184:187], v[200:203], v[24:27]
	v_mfma_f32_16x16x32_bf16 v[12:15], v[172:175], v[208:211], v[12:15]
	v_mfma_f32_16x16x32_bf16 v[8:11], v[184:187], v[208:211], v[8:11]
	v_mfma_f32_16x16x32_bf16 v[4:7], v[172:175], v[216:219], v[4:7]
	v_mfma_f32_16x16x32_bf16 v[0:3], v[184:187], v[216:219], v[0:3]
	v_mfma_f32_16x16x32_bf16 v[44:47], v[180:183], v[196:199], v[44:47]
	v_mfma_f32_16x16x32_bf16 v[40:43], v[188:191], v[196:199], v[40:43]
	v_mfma_f32_16x16x32_bf16 v[28:31], v[180:183], v[204:207], v[28:31]
	v_mfma_f32_16x16x32_bf16 v[24:27], v[188:191], v[204:207], v[24:27]
	v_mfma_f32_16x16x32_bf16 v[12:15], v[180:183], v[212:215], v[12:15]
	v_mfma_f32_16x16x32_bf16 v[8:11], v[188:191], v[212:215], v[8:11]
	v_mfma_f32_16x16x32_bf16 v[4:7], v[180:183], v[220:223], v[4:7]
	v_mfma_f32_16x16x32_bf16 v[0:3], v[188:191], v[220:223], v[0:3]
	s_barrier
.Lgemm_join_1341:
	s_add_i32 s17, 0, 0x18000
	v_add_u32_e32 v141, s17, v135
	s_add_i32 s27, 0, 0x1c000
	ds_read_b128 v[156:159], v141
	ds_read_b128 v[160:163], v141 offset:1024
	ds_read_b128 v[164:167], v141 offset:2048
	ds_read_b128 v[168:171], v141 offset:3072
	v_add_u32_e32 v141, s27, v135
	ds_read_b128 v[172:175], v141
	ds_read_b128 v[180:183], v141 offset:1024
	ds_read_b128 v[184:187], v141 offset:2048
	ds_read_b128 v[188:191], v141 offset:3072
	s_add_u32 s48, s48, s0
	s_addc_u32 s49, s49, s1
	s_mov_b32 m0, s15
	v_lshl_add_u64 v[236:237], s[48:49], 0, v[128:129]
	ds_read_b128 v[192:195], v139 offset:32768
	ds_read_b128 v[196:199], v139 offset:33792
	ds_read_b128 v[200:203], v139 offset:34816
	ds_read_b128 v[204:207], v139 offset:35840
	ds_read_b128 v[208:211], v139 offset:36864
	ds_read_b128 v[212:215], v139 offset:37888
	ds_read_b128 v[216:219], v139 offset:38912
	ds_read_b128 v[220:223], v139 offset:39936
	global_load_lds_dwordx4 v[236:237], off
	v_lshl_add_u64 v[236:237], s[48:49], 0, v[130:131]
	s_mov_b32 m0, s26
	s_nop 0
	global_load_lds_dwordx4 v[236:237], off
	s_waitcnt vmcnt(8)
	s_waitcnt lgkmcnt(0)
	s_barrier
; #define PG8_STAGE(bufoff, gbase, voff) do { _Pragma("unroll") for (int _i = 0; _i < 2; ++_i) \
;         __builtin_amdgcn_global_load_lds((const unsigned*)((const char*)(gbase) + (voff)[_i]), (LAS unsigned*)(lds + (bufoff) + ldsw + _i * 8192), 16, 0, 0); } while (0)
; #define PG8_LDA(dst, b, h) do { _Pragma("unroll") for (int m = 0; m < 4; ++m) _Pragma("unroll") for (int k = 0; k < 2; ++k) dst[m][k] = *(const LAS bf16x8*)(lds + PG8_SA(b, h) + aoff + m * 2048 + k * 1024); } while (0)
; #define PG8_MMA(ai, bj, At, Bt) do { __builtin_amdgcn_s_setprio(1); _Pragma("unroll") for (int m = 0; m < 4; ++m) _Pragma("unroll") for (int n = 0; n < 2; ++n) _Pragma("unroll") for (int k = 0; k < 2; ++k) \
;         acc[ai][bj][m][n] = __builtin_amdgcn_mfma_f32_16x16x32_bf16(Bt[n][k], At[m][k], acc[ai][bj][m][n], 0, 0, 0); __builtin_amdgcn_s_setprio(0); } while (0)
; #define PG8_WAIT_V(n) asm volatile("s_waitcnt vmcnt(" #n ")" ::: "memory")
; #define PG8_WAIT_L(n) asm volatile("s_waitcnt lgkmcnt(" #n ")" ::: "memory")
; #define PG8_BAR __builtin_amdgcn_s_barrier()
; #define PG8_SCHED __builtin_amdgcn_sched_barrier(0)
; template <class Epi, class Sched, bool ALIGN_EPI>
; __device__ __forceinline__ void gemm_phase(LAS unsigned char* lds, const int wid, const int lda_, const int ldb_, const int K_, const Sched& S, const Epi& E) {
;     ...
;             PG8_WAIT_V(8); PG8_WAIT_L(0); PG8_BAR; PG8_MMA(0, 0, At, B0); PG8_MMA(0, 1, At, B1); PG8_BAR; PG8_SCHED;
;             PG8_LDA(At, 1, 1); PG8_STAGE(PG8_SB(1, 0), b3, voffB); PG8_STAGE(PG8_SB(1, 1), b3 + hstepB, voffB); PG8_STAGE(PG8_SA(1, 0), a3, voffA);
;             PG8_WAIT_V(8); PG8_WAIT_L(0); PG8_BAR; PG8_MMA(1, 0, At, B0); PG8_MMA(1, 1, At, B1); PG8_BAR; PG8_SCHED;
;     __device__ __forceinline__ void out(const pg8::Unit& u, char*& o, int& ldo, int& kind) const { ldo = D;
;     ...
;         else { o = (char*)ws + WS_PART + (((size_t)u.kq * MCTX + (size_t)(u.pm - 64) * 256) * D + (size_t)u.pn * 256) * 2; kind = 0; } }
	s_waitcnt lgkmcnt(0)
	v_mfma_f32_16x16x32_bf16 v[124:127], v[156:159], v[192:195], v[124:127]
	v_mfma_f32_16x16x32_bf16 v[120:123], v[164:167], v[192:195], v[120:123]
	v_mfma_f32_16x16x32_bf16 v[116:119], v[156:159], v[200:203], v[116:119]
	v_mfma_f32_16x16x32_bf16 v[112:115], v[164:167], v[200:203], v[112:115]
	v_mfma_f32_16x16x32_bf16 v[100:103], v[156:159], v[208:211], v[100:103]
	v_mfma_f32_16x16x32_bf16 v[96:99], v[164:167], v[208:211], v[96:99]
	v_mfma_f32_16x16x32_bf16 v[84:87], v[156:159], v[216:219], v[84:87]
	v_mfma_f32_16x16x32_bf16 v[80:83], v[164:167], v[216:219], v[80:83]
	v_mfma_f32_16x16x32_bf16 v[124:127], v[160:163], v[196:199], v[124:127]
	v_mfma_f32_16x16x32_bf16 v[120:123], v[168:171], v[196:199], v[120:123]
	v_mfma_f32_16x16x32_bf16 v[116:119], v[160:163], v[204:207], v[116:119]
	v_mfma_f32_16x16x32_bf16 v[112:115], v[168:171], v[204:207], v[112:115]
	v_mfma_f32_16x16x32_bf16 v[100:103], v[160:163], v[212:215], v[100:103]
	v_mfma_f32_16x16x32_bf16 v[96:99], v[168:171], v[212:215], v[96:99]
	v_mfma_f32_16x16x32_bf16 v[84:87], v[160:163], v[220:223], v[84:87]
	v_mfma_f32_16x16x32_bf16 v[80:83], v[168:171], v[220:223], v[80:83]
	v_mfma_f32_16x16x32_bf16 v[108:111], v[172:175], v[192:195], v[108:111]
	v_mfma_f32_16x16x32_bf16 v[104:107], v[184:187], v[192:195], v[104:107]
	v_mfma_f32_16x16x32_bf16 v[92:95], v[172:175], v[200:203], v[92:95]
	v_mfma_f32_16x16x32_bf16 v[88:91], v[184:187], v[200:203], v[88:91]
	v_mfma_f32_16x16x32_bf16 v[76:79], v[172:175], v[208:211], v[76:79]
	v_mfma_f32_16x16x32_bf16 v[72:75], v[184:187], v[208:211], v[72:75]
	v_mfma_f32_16x16x32_bf16 v[68:71], v[172:175], v[216:219], v[68:71]
	v_mfma_f32_16x16x32_bf16 v[64:67], v[184:187], v[216:219], v[64:67]
	v_mfma_f32_16x16x32_bf16 v[108:111], v[180:183], v[196:199], v[108:111]
	v_mfma_f32_16x16x32_bf16 v[104:107], v[188:191], v[196:199], v[104:107]
	v_mfma_f32_16x16x32_bf16 v[92:95], v[180:183], v[204:207], v[92:95]
	v_mfma_f32_16x16x32_bf16 v[88:91], v[188:191], v[204:207], v[88:91]
	v_mfma_f32_16x16x32_bf16 v[76:79], v[180:183], v[212:215], v[76:79]
	v_mfma_f32_16x16x32_bf16 v[72:75], v[188:191], v[212:215], v[72:75]
	v_mfma_f32_16x16x32_bf16 v[68:71], v[180:183], v[220:223], v[68:71]
	v_mfma_f32_16x16x32_bf16 v[64:67], v[188:191], v[220:223], v[64:67]
	s_barrier
	s_add_i32 s17, s17, s3
	v_lshl_add_u64 v[224:225], v[224:225], 0, s[24:25]
	s_mov_b32 m0, s17
	ds_read_b128 v[192:195], v139 offset:49152
	ds_read_b128 v[196:199], v139 offset:50176
	ds_read_b128 v[200:203], v139 offset:51200
	ds_read_b128 v[204:207], v139 offset:52224
	ds_read_b128 v[208:211], v139 offset:53248
	ds_read_b128 v[212:215], v139 offset:54272
	ds_read_b128 v[216:219], v139 offset:55296
	ds_read_b128 v[220:223], v139 offset:56320
	global_load_lds_dwordx4 v[224:225], off
	v_lshl_add_u64 v[224:225], v[226:227], 0, s[24:25]
	s_add_i32 m0, s17, 0x2000
	s_add_i32 s17, s27, s3
	global_load_lds_dwordx4 v[224:225], off
	v_lshl_add_u64 v[224:225], v[228:229], 0, s[24:25]
	s_mov_b32 m0, s17
	s_nop 0
	global_load_lds_dwordx4 v[224:225], off
	v_lshl_add_u64 v[224:225], v[230:231], 0, s[24:25]
	s_add_i32 m0, s17, 0x2000
	s_nop 0
	global_load_lds_dwordx4 v[224:225], off
	v_lshl_add_u64 v[224:225], v[232:233], 0, s[24:25]
	s_mov_b32 m0, s50
	s_nop 0
	global_load_lds_dwordx4 v[224:225], off
	v_lshl_add_u64 v[224:225], v[234:235], 0, s[24:25]
	s_mov_b32 m0, s51
	s_nop 0
	global_load_lds_dwordx4 v[224:225], off
	s_waitcnt vmcnt(8)
	s_waitcnt lgkmcnt(0)
	s_barrier
	s_waitcnt lgkmcnt(0)
	v_mfma_f32_16x16x32_bf16 v[60:63], v[156:159], v[192:195], v[60:63]
	v_mfma_f32_16x16x32_bf16 v[56:59], v[164:167], v[192:195], v[56:59]
	v_mfma_f32_16x16x32_bf16 v[52:55], v[156:159], v[200:203], v[52:55]
	v_mfma_f32_16x16x32_bf16 v[48:51], v[164:167], v[200:203], v[48:51]
	v_mfma_f32_16x16x32_bf16 v[36:39], v[156:159], v[208:211], v[36:39]
	v_mfma_f32_16x16x32_bf16 v[32:35], v[164:167], v[208:211], v[32:35]
	v_mfma_f32_16x16x32_bf16 v[20:23], v[156:159], v[216:219], v[20:23]
	v_mfma_f32_16x16x32_bf16 v[16:19], v[164:167], v[216:219], v[16:19]
	v_mfma_f32_16x16x32_bf16 v[60:63], v[160:163], v[196:199], v[60:63]
	v_mfma_f32_16x16x32_bf16 v[56:59], v[168:171], v[196:199], v[56:59]
	v_mfma_f32_16x16x32_bf16 v[52:55], v[160:163], v[204:207], v[52:55]
	v_mfma_f32_16x16x32_bf16 v[48:51], v[168:171], v[204:207], v[48:51]
	v_mfma_f32_16x16x32_bf16 v[36:39], v[160:163], v[212:215], v[36:39]
	v_mfma_f32_16x16x32_bf16 v[32:35], v[168:171], v[212:215], v[32:35]
	v_mfma_f32_16x16x32_bf16 v[20:23], v[160:163], v[220:223], v[20:23]
	v_mfma_f32_16x16x32_bf16 v[16:19], v[168:171], v[220:223], v[16:19]
	v_mfma_f32_16x16x32_bf16 v[44:47], v[172:175], v[192:195], v[44:47]
	v_mfma_f32_16x16x32_bf16 v[40:43], v[184:187], v[192:195], v[40:43]
	v_mfma_f32_16x16x32_bf16 v[28:31], v[172:175], v[200:203], v[28:31]
	v_mfma_f32_16x16x32_bf16 v[24:27], v[184:187], v[200:203], v[24:27]
	v_mfma_f32_16x16x32_bf16 v[12:15], v[172:175], v[208:211], v[12:15]
	v_mfma_f32_16x16x32_bf16 v[8:11], v[184:187], v[208:211], v[8:11]
	v_mfma_f32_16x16x32_bf16 v[4:7], v[172:175], v[216:219], v[4:7]
	v_mfma_f32_16x16x32_bf16 v[0:3], v[184:187], v[216:219], v[0:3]
	v_mfma_f32_16x16x32_bf16 v[44:47], v[180:183], v[196:199], v[44:47]
	v_mfma_f32_16x16x32_bf16 v[40:43], v[188:191], v[196:199], v[40:43]
	v_mfma_f32_16x16x32_bf16 v[28:31], v[180:183], v[204:207], v[28:31]
	v_mfma_f32_16x16x32_bf16 v[24:27], v[188:191], v[204:207], v[24:27]
	v_mfma_f32_16x16x32_bf16 v[12:15], v[180:183], v[212:215], v[12:15]
	v_mfma_f32_16x16x32_bf16 v[8:11], v[188:191], v[212:215], v[8:11]
	v_mfma_f32_16x16x32_bf16 v[4:7], v[180:183], v[220:223], v[4:7]
	v_mfma_f32_16x16x32_bf16 v[0:3], v[188:191], v[220:223], v[0:3]
	s_barrier
	s_add_u32 s46, s46, 0x100
	s_addc_u32 s47, s47, 0
	s_add_u32 s31, s31, 0x100
	s_addc_u32 s35, s35, 0
	s_cmp_ge_u32 s76, s4
	s_mov_b32 s39, s76
	s_cbranch_scc0 .LBB0_1341
	s_setprio 2
	s_mov_b64 s[46:47], -1
	s_and_b64 vcc, exec, s[44:45]
	s_cbranch_vccz .LBB0_1344
	s_mov_b32 s39, s92
	s_ashr_i32 s31, s30, 31
	s_ashr_i32 s35, s34, 31
	s_lshl_b64 s[4:5], s[30:31], 20
	s_lshl_b64 s[44:45], s[34:35], 9
	s_lshl_b64 s[38:39], s[38:39], 23
	v_readlane_b32 s46, v251, 28
	v_readlane_b32 s47, v251, 29
	s_add_u32 s17, s46, s44
	s_addc_u32 s27, s47, s45
	s_add_u32 s17, s17, s38
	s_addc_u32 s27, s27, s39
	s_add_u32 s4, s17, s4
	s_addc_u32 s5, s27, s5
	s_add_u32 s4, s4, 0xfc000000
	s_addc_u32 s5, s5, -1
	s_mov_b64 s[46:47], 0
